# stack2 + small-GEMM epilogue load batching + w_sp load batching + sample-attention cache-row load remap (whole 128B lines per wave load)
# speedup vs baseline: 1.0186x; 1.0186x over previous
.Lfsr_first_f1:
	s_waitcnt vmcnt(6)
	v_cvt_pk_bf16_f32 v66, v102, v103
	v_cvt_pk_bf16_f32 v67, v104, v105
	v_cvt_pk_bf16_f32 v68, v98, v99
	v_cvt_pk_bf16_f32 v69, v100, v101
	ds_write_b128 v133, v[66:69]
	s_waitcnt vmcnt(4)
	v_cvt_pk_bf16_f32 v66, v110, v111
	v_cvt_pk_bf16_f32 v67, v112, v113
	v_cvt_pk_bf16_f32 v68, v106, v107
	v_cvt_pk_bf16_f32 v69, v108, v109
	ds_write_b128 v198, v[66:69]
	s_waitcnt vmcnt(2)
	v_cvt_pk_bf16_f32 v66, v122, v123
	v_cvt_pk_bf16_f32 v67, v124, v125
	v_cvt_pk_bf16_f32 v68, v114, v115
	v_cvt_pk_bf16_f32 v69, v116, v117
	s_cmpk_eq_i32 s97, 0xf000
	ds_write_b128 v199, v[66:69] offset:32768
	s_waitcnt vmcnt(0)
	v_cvt_pk_bf16_f32 v66, v126, v127
	v_cvt_pk_bf16_f32 v67, v128, v129
	v_cvt_pk_bf16_f32 v68, v118, v119
	v_cvt_pk_bf16_f32 v69, v120, v121
	ds_write_b128 v200, v[66:69] offset:32768
	s_branch .Lfsr_join_f1

; template <int MODE, bool SAMPLE>
; __device__ __forceinline__ void attn_unit(const Params& p, char* lds, int b, int h, int qb) {
;     ...
;         WRITET(buf, stg2[NS == 2 ? par : 0]);
;         if (j >= NS) LOADT(j - NS, stg2[NS == 2 ? par : 0]);
;         __syncthreads();
;         if (wact && j <= jd && var < 2) {
;             const char* Kt = K_lds + buf * 16384; const int vb = vb0 + buf * 16384;
;             f32x16 p0, p1; bf16x8 pa0, pa1, pa2, pa3;
;             if (MODE == 0) {
;                 const float* bt = biasL + j * 64 + 4 * hi;
; #pragma unroll
;                 for (int g = 0; g < 4; ++g) { const f32x4 a = *(const f32x4*)(bt + 8 * g), c = *(const f32x4*)(bt + 32 + 8 * g);
; #pragma unroll
;                     for (int i = 0; i < 4; ++i) { p0[4 * g + i] = a[i]; p1[4 * g + i] = c[i]; } }
;                 qkt(p0, p1, Kt, Qs, r32, hi);
.LBB0_615:
	v_cndmask_b32_e64 v66, 0, 1, s[74:75]
	s_cmp_lt_u32 s76, 8
	v_lshlrev_b32_e32 v0, 2, v152
	v_lshlrev_b32_e32 v164, 2, v154
	v_cmp_ne_u32_e64 s[0:1], 1, v66
	s_cbranch_scc0 .Lfsr_first_f1
	v_and_b32_e32 v76, 15, v183
	v_bfe_u32 v77, v183, 4, 3
	v_xor_b32_e32 v78, v76, v77
	v_lshrrev_b32_e32 v74, 1, v76
	v_xor_b32_e32 v74, v74, v77
	v_sub_u32_e32 v74, v74, v78
	v_and_b32_e32 v78, 1, v76
	v_lshlrev_b32_e32 v74, 4, v74
	v_lshl_add_u32 v74, v78, 3, v74
	v_lshrrev_b32_e32 v75, 3, v76
	v_lshrrev_b32_e32 v78, 2, v76
	v_sub_u32_e32 v75, v75, v78
	v_lshlrev_b32_e32 v75, 9, v75
	v_and_b32_e32 v78, 7, v76
	v_lshl_add_u32 v75, v78, 3, v75
	v_and_b32_e32 v78, 3, v76
	v_lshlrev_b32_e32 v78, 4, v78
	v_sub_u32_e32 v75, v75, v78
	v_add_u32_e32 v70, v133, v74
	v_add_u32_e32 v71, v198, v74
	v_add_u32_e32 v72, v199, v75
	v_add_u32_e32 v73, v200, v75
	s_waitcnt vmcnt(6)
	v_cvt_pk_bf16_f32 v66, v102, v103
	v_cvt_pk_bf16_f32 v67, v104, v105
	v_cvt_pk_bf16_f32 v68, v98, v99
	v_cvt_pk_bf16_f32 v69, v100, v101
	ds_write_b64 v70, v[66:67] offset:16384
	ds_write_b64 v70, v[68:69] offset:16512
	s_waitcnt vmcnt(4)
	v_cvt_pk_bf16_f32 v66, v110, v111
	v_cvt_pk_bf16_f32 v67, v112, v113
	v_cvt_pk_bf16_f32 v68, v106, v107
	v_cvt_pk_bf16_f32 v69, v108, v109
	ds_write_b64 v71, v[66:67] offset:16384
	ds_write_b64 v71, v[68:69] offset:16512
	s_waitcnt vmcnt(2)
	v_cvt_pk_bf16_f32 v66, v122, v123
	v_cvt_pk_bf16_f32 v67, v124, v125
	v_cvt_pk_bf16_f32 v68, v114, v115
	v_cvt_pk_bf16_f32 v69, v116, v117
	ds_write_b64 v72, v[66:67] offset:49152
	ds_write_b64 v72, v[68:69] offset:50176
	s_waitcnt vmcnt(0)
	v_cvt_pk_bf16_f32 v66, v126, v127
	v_cvt_pk_bf16_f32 v67, v128, v129
	v_cvt_pk_bf16_f32 v68, v118, v119
	v_cvt_pk_bf16_f32 v69, v120, v121
	ds_write_b64 v73, v[66:67] offset:49152
	ds_write_b64 v73, v[68:69] offset:50176
	v_or_b32_e32 v67, s11, v171
	v_or_b32_e32 v66, s3, v170
	v_readlane_b32 s36, v253, 16
	v_lshlrev_b64 v[66:67], 2, v[66:67]
	v_and_b32_e32 v72, 15, v183
	v_lshlrev_b32_e32 v72, 4, v72
	v_sub_u32_e32 v66, v66, v72
	v_readlane_b32 s40, v253, 20
	v_readlane_b32 s41, v253, 21
	v_readlane_b32 s42, v253, 22
	v_readlane_b32 s43, v253, 23
	v_lshl_add_u64 v[68:69], s[40:41], 0, v[66:67]
	v_mov_b32_e32 v165, v1
	v_lshl_add_u64 v[70:71], v[68:69], 0, v[0:1]
	v_lshl_add_u64 v[68:69], v[68:69], 0, v[164:165]
	v_lshl_add_u64 v[66:67], s[42:43], 0, v[66:67]
	global_load_dwordx4 v[98:101], v[70:71], off offset:256 nt
	global_load_dwordx4 v[102:105], v[70:71], off nt
	global_load_dwordx4 v[106:109], v[68:69], off offset:256 nt
	global_load_dwordx4 v[110:113], v[68:69], off nt
	v_lshl_add_u64 v[68:69], v[66:67], 0, v[0:1]
	v_lshl_add_u64 v[66:67], v[66:67], 0, v[164:165]
	global_load_dwordx4 v[114:117], v[68:69], off offset:256 nt
	global_load_dwordx4 v[122:125], v[68:69], off nt
	global_load_dwordx4 v[118:121], v[66:67], off offset:256 nt
	global_load_dwordx4 v[126:129], v[66:67], off nt
	s_and_b64 vcc, exec, s[0:1]
	v_readlane_b32 s37, v253, 17
	v_readlane_b32 s38, v253, 18
	v_readlane_b32 s39, v253, 19
	v_readlane_b32 s44, v253, 24
	v_readlane_b32 s45, v253, 25
	v_readlane_b32 s46, v253, 26
	v_readlane_b32 s47, v253, 27
	v_readlane_b32 s48, v253, 28
	v_readlane_b32 s49, v253, 29
	v_readlane_b32 s50, v253, 30
	v_readlane_b32 s51, v253, 31
	s_waitcnt lgkmcnt(0)
	s_barrier
	s_cbranch_vccnz .LBB0_622
	v_add_u32_e32 v78, s97, v214
	v_add_u32_e32 v66, 0x11100, v78
	v_add_u32_e32 v67, 0x11180, v78
	v_add_u32_e32 v70, 0x11120, v78
	v_add_u32_e32 v74, 0x11140, v78
	ds_read_b128 v[82:85], v66
	ds_read_b128 v[66:69], v67
	ds_read_b128 v[86:89], v70
	ds_read_b128 v[90:93], v74
	v_add_u32_e32 v70, 0x111a0, v78
	v_add_u32_e32 v74, 0x111c0, v78
	v_add_u32_e32 v79, 0x11160, v78
	v_add_u32_e32 v78, 0x111e0, v78
	v_add_u32_e32 v165, s33, v182
	ds_read_b128 v[94:97], v79
	ds_read_b128 v[78:81], v78
	ds_read_b128 v[202:205], v165
	v_add_u32_e32 v165, 0, v182
	ds_read_b128 v[70:73], v70
	ds_read_b128 v[74:77], v74
	ds_read_b128 v[206:209], v165 offset:16384
	ds_read_b128 v[216:219], v165 offset:24576
	s_waitcnt lgkmcnt(1)
	v_mfma_f32_32x32x16_bf16 v[82:97], v[206:209], v[202:205], v[82:97]
	v_add_u32_e32 v165, s33, v184
	s_waitcnt lgkmcnt(0)
	v_mfma_f32_32x32x16_bf16 v[66:81], v[216:219], v[202:205], v[66:81]
	ds_read_b128 v[202:205], v165
	v_add_u32_e32 v165, 0, v184
	ds_read_b128 v[206:209], v165 offset:16384
	ds_read_b128 v[216:219], v165 offset:24576
	v_add_u32_e32 v165, s33, v185
	s_waitcnt lgkmcnt(1)
	v_mfma_f32_32x32x16_bf16 v[82:97], v[206:209], v[202:205], v[82:97]
	s_waitcnt lgkmcnt(0)
	v_mfma_f32_32x32x16_bf16 v[66:81], v[216:219], v[202:205], v[66:81]
	ds_read_b128 v[202:205], v165
	v_add_u32_e32 v165, 0, v185
	ds_read_b128 v[206:209], v165 offset:16384
	ds_read_b128 v[216:219], v165 offset:24576
	v_add_u32_e32 v165, s33, v186
	s_waitcnt lgkmcnt(1)
	v_mfma_f32_32x32x16_bf16 v[82:97], v[206:209], v[202:205], v[82:97]
	s_waitcnt lgkmcnt(0)
	v_mfma_f32_32x32x16_bf16 v[66:81], v[216:219], v[202:205], v[66:81]
	ds_read_b128 v[202:205], v165
	v_add_u32_e32 v165, 0, v186
	ds_read_b128 v[206:209], v165 offset:16384
	ds_read_b128 v[216:219], v165 offset:24576
	v_add_u32_e32 v165, s33, v187
	s_waitcnt lgkmcnt(1)
	v_mfma_f32_32x32x16_bf16 v[82:97], v[206:209], v[202:205], v[82:97]
	s_waitcnt lgkmcnt(0)
	v_mfma_f32_32x32x16_bf16 v[66:81], v[216:219], v[202:205], v[66:81]
	ds_read_b128 v[202:205], v165
	v_add_u32_e32 v165, 0, v187
	ds_read_b128 v[206:209], v165 offset:16384
	ds_read_b128 v[216:219], v165 offset:24576
	v_add_u32_e32 v165, s33, v188
	s_waitcnt lgkmcnt(1)
	v_mfma_f32_32x32x16_bf16 v[82:97], v[206:209], v[202:205], v[82:97]
	s_waitcnt lgkmcnt(0)
; __device__ __forceinline__ int crow(int r, int hi) { return (r & 3) + 8 * (r >> 2) + 4 * hi; }
; template <int MODE, bool SAMPLE>
; __device__ __forceinline__ void attn_unit(const Params& p, char* lds, int b, int h, int qb) {
;     ...
;                 qkt(p0, p1, Kt, Qs, r32, hi);
;                 if (j == jd) {
; #pragma unroll
;                     for (int r = 0; r < 16; ++r) { const int kp = j * 64 + crow(r, hi); if (kp > qpos) p0[r] = -1e30f; if (kp + 32 > qpos) p1[r] = -1e30f; } }
;                 float pmax = p0[0];
; #pragma unroll
;                 for (int r = 1; r < 16; ++r) pmax = fmaxf(pmax, p0[r]);
; #pragma unroll
;                 for (int r = 0; r < 16; ++r) pmax = fmaxf(pmax, p1[r]);
;                 { auto rr = __builtin_amdgcn_permlane32_swap(__float_as_uint(pmax), __float_as_uint(pmax), false, false); pmax = fmaxf(__uint_as_float(rr[0]), __uint_as_float(rr[1])); }
;                 float alpha = 1.f;
;                 if (!__all(pmax - m_reg <= 8.f)) { const float mn = fmaxf(m_reg, pmax); alpha = __builtin_amdgcn_exp2f(m_reg - mn); m_reg = mn; }
;                 float ps = 0.f;
; #pragma unroll
;                 for (int r = 0; r < 16; ++r) { p0[r] = __builtin_amdgcn_exp2f(p0[r] - m_reg); p1[r] = __builtin_amdgcn_exp2f(p1[r] - m_reg); ps += p0[r] + p1[r]; }
;                 { auto rr = __builtin_amdgcn_permlane32_swap(__float_as_uint(ps), __float_as_uint(ps), false, false); ps = __uint_as_float(rr[0]) + __uint_as_float(rr[1]); }
;                 l_reg = l_reg * alpha + ps;
;                 if (__any(alpha < 1.f)) { if (hi == 0) wsc[r32] = alpha; asm volatile("s_waitcnt lgkmcnt(0)" ::: "memory");
; #pragma unroll
;                     for (int d = 0; d < 4; ++d)
; #pragma unroll
;                         for (int r = 0; r < 16; ++r) o[d][r] *= wsc[crow(r, hi)]; }
	v_mfma_f32_32x32x16_bf16 v[66:81], v[216:219], v[202:205], v[66:81]
	ds_read_b128 v[202:205], v165
	v_add_u32_e32 v165, 0, v188
	ds_read_b128 v[206:209], v165 offset:16384
	ds_read_b128 v[216:219], v165 offset:24576
	v_add_u32_e32 v165, s33, v189
	s_waitcnt lgkmcnt(1)
	v_mfma_f32_32x32x16_bf16 v[82:97], v[206:209], v[202:205], v[82:97]
	s_waitcnt lgkmcnt(0)
	v_mfma_f32_32x32x16_bf16 v[66:81], v[216:219], v[202:205], v[66:81]
	ds_read_b128 v[202:205], v165
	v_add_u32_e32 v165, 0, v189
	ds_read_b128 v[206:209], v165 offset:16384
	ds_read_b128 v[216:219], v165 offset:24576
	v_add_u32_e32 v165, s33, v190
	s_waitcnt lgkmcnt(1)
	v_mfma_f32_32x32x16_bf16 v[82:97], v[206:209], v[202:205], v[82:97]
	s_waitcnt lgkmcnt(0)
	v_mfma_f32_32x32x16_bf16 v[66:81], v[216:219], v[202:205], v[66:81]
	ds_read_b128 v[202:205], v165
	v_add_u32_e32 v165, 0, v190
	ds_read_b128 v[206:209], v165 offset:16384
	ds_read_b128 v[216:219], v165 offset:24576
	s_waitcnt lgkmcnt(1)
	v_mfma_f32_32x32x16_bf16 v[82:97], v[206:209], v[202:205], v[82:97]
	s_waitcnt lgkmcnt(0)
	v_mfma_f32_32x32x16_bf16 v[66:81], v[216:219], v[202:205], v[66:81]
	s_nop 9
	v_max_f32_e32 v165, v83, v83
	v_max_f32_e32 v202, v82, v82
	v_max_f32_e32 v165, v202, v165
	v_max3_f32 v165, v165, v84, v85
	v_max3_f32 v165, v165, v86, v87
	v_max3_f32 v165, v165, v88, v89
	v_max3_f32 v165, v165, v90, v91
	v_max3_f32 v165, v165, v92, v93
	v_max3_f32 v165, v165, v94, v95
	v_max3_f32 v165, v165, v96, v97
	v_max3_f32 v165, v165, v66, v67
	v_max3_f32 v165, v165, v68, v69
	v_max3_f32 v165, v165, v70, v71
	v_max3_f32 v165, v165, v72, v73
	v_max3_f32 v165, v165, v74, v75
	v_max3_f32 v165, v165, v76, v77
	v_max3_f32 v165, v165, v78, v79
	v_max3_f32 v165, v165, v80, v81
	v_mov_b32_e32 v202, v165
	s_nop 1
	v_permlane32_swap_b32_e32 v165, v202
	v_max_f32_e32 v202, v202, v202
	v_max_f32_e32 v165, v165, v165
	v_max_f32_e32 v165, v165, v202
	v_sub_f32_e32 v202, v165, v163
	v_cmp_ge_f32_e32 vcc, s83, v202
	s_cmp_eq_u64 vcc, exec
	v_max_f32_e32 v202, v163, v163
	s_cselect_b64 vcc, -1, 0
	v_max_f32_e32 v165, v202, v165
	v_sub_f32_e32 v202, v163, v165
	v_cndmask_b32_e32 v163, v165, v163, vcc
	v_sub_f32_e32 v82, v82, v163
	v_sub_f32_e32 v66, v66, v163
	v_exp_f32_e32 v165, v82
	v_exp_f32_e32 v82, v66
	v_exp_f32_e32 v203, v202
	v_sub_f32_e32 v67, v67, v163
	v_sub_f32_e32 v68, v68, v163
	v_add_f32_e32 v66, v165, v82
	v_add_f32_e32 v202, 0, v66
	v_sub_f32_e32 v66, v83, v163
	v_exp_f32_e32 v66, v66
	v_exp_f32_e32 v83, v67
	v_sub_f32_e32 v69, v69, v163
	v_sub_f32_e32 v70, v70, v163
	v_exp_f32_e32 v70, v70
	v_add_f32_e32 v67, v66, v83
	v_add_f32_e32 v202, v67, v202
	v_sub_f32_e32 v67, v84, v163
	v_exp_f32_e32 v67, v67
	v_exp_f32_e32 v84, v68
	v_sub_f32_e32 v71, v71, v163
	v_exp_f32_e32 v71, v71
	v_sub_f32_e32 v72, v72, v163
	v_add_f32_e32 v68, v67, v84
	v_add_f32_e32 v202, v68, v202
	v_sub_f32_e32 v68, v85, v163
	v_exp_f32_e32 v68, v68
	v_exp_f32_e32 v85, v69
	v_exp_f32_e32 v72, v72
	v_sub_f32_e32 v73, v73, v163
	v_exp_f32_e32 v73, v73
	v_add_f32_e32 v69, v68, v85
	v_add_f32_e32 v202, v69, v202
	v_sub_f32_e32 v69, v86, v163
	v_exp_f32_e32 v69, v69
	v_sub_f32_e32 v74, v74, v163
	v_exp_f32_e32 v74, v74
	v_sub_f32_e32 v75, v75, v163
	v_add_f32_e32 v86, v69, v70
	v_add_f32_e32 v202, v86, v202
	v_sub_f32_e32 v86, v87, v163
	v_exp_f32_e32 v86, v86
	v_exp_f32_e32 v75, v75
	v_sub_f32_e32 v76, v76, v163
	v_exp_f32_e32 v76, v76
	v_add_f32_e32 v87, v86, v71
	v_add_f32_e32 v202, v87, v202
	v_sub_f32_e32 v87, v88, v163
	v_exp_f32_e32 v87, v87
	v_sub_f32_e32 v77, v77, v163
	v_exp_f32_e32 v77, v77
	v_sub_f32_e32 v78, v78, v163
	v_add_f32_e32 v88, v87, v72
	v_add_f32_e32 v202, v88, v202
	v_sub_f32_e32 v88, v89, v163
	v_exp_f32_e32 v88, v88
	v_exp_f32_e32 v78, v78
	v_sub_f32_e32 v79, v79, v163
	v_exp_f32_e32 v79, v79
	v_add_f32_e32 v89, v88, v73
	v_add_f32_e32 v202, v89, v202
	v_sub_f32_e32 v89, v90, v163
	v_exp_f32_e32 v89, v89
	v_sub_f32_e32 v80, v80, v163
	v_exp_f32_e32 v80, v80
	v_sub_f32_e32 v81, v81, v163
	v_add_f32_e32 v90, v89, v74
	v_add_f32_e32 v202, v90, v202
	v_sub_f32_e32 v90, v91, v163
	v_exp_f32_e32 v90, v90
	v_exp_f32_e32 v81, v81
	v_add_f32_e32 v91, v90, v75
	v_add_f32_e32 v202, v91, v202
	v_sub_f32_e32 v91, v92, v163
	v_exp_f32_e32 v91, v91
	s_nop 0
	v_add_f32_e32 v92, v91, v76
	v_add_f32_e32 v202, v92, v202
	v_sub_f32_e32 v92, v93, v163
	v_exp_f32_e32 v92, v92
	s_nop 0
	v_add_f32_e32 v93, v92, v77
	v_add_f32_e32 v202, v93, v202
	v_sub_f32_e32 v93, v94, v163
	v_exp_f32_e32 v93, v93
	s_nop 0
	v_add_f32_e32 v94, v93, v78
	v_add_f32_e32 v202, v94, v202
	v_sub_f32_e32 v94, v95, v163
	v_exp_f32_e32 v94, v94
	s_nop 0
	v_add_f32_e32 v95, v94, v79
	v_add_f32_e32 v202, v95, v202
	v_sub_f32_e32 v95, v96, v163
	v_exp_f32_e32 v95, v95
	s_nop 0
	v_add_f32_e32 v96, v95, v80
	v_add_f32_e32 v202, v96, v202
	v_sub_f32_e32 v96, v97, v163
	v_exp_f32_e32 v96, v96
	s_nop 0
	v_add_f32_e32 v97, v96, v81
	v_add_f32_e32 v202, v97, v202
	v_cndmask_b32_e64 v97, v203, 1.0, vcc
	v_mov_b32_e32 v203, v202
	s_nop 1
	v_permlane32_swap_b32_e32 v202, v203
	v_cmp_gt_f32_e32 vcc, 1.0, v97
	s_cbranch_vccz .LBB0_621
	s_and_saveexec_b64 s[4:5], s[14:15]
	ds_write_b32 v145, v97
	s_or_b64 exec, exec, s[4:5]
	s_waitcnt lgkmcnt(0)
	ds_read_b128 v[204:207], v147 offset:96
	ds_read_b128 v[216:219], v147 offset:64
	ds_read_b128 v[220:223], v147 offset:32
	ds_read_b128 v[224:227], v147
	s_waitcnt lgkmcnt(3)
	v_pk_mul_f32 v[64:65], v[64:65], v[206:207]
	s_waitcnt lgkmcnt(2)
	v_pk_mul_f32 v[60:61], v[60:61], v[218:219]
	s_waitcnt lgkmcnt(1)
	v_pk_mul_f32 v[56:57], v[56:57], v[222:223]
	s_waitcnt lgkmcnt(0)
	v_pk_mul_f32 v[52:53], v[52:53], v[226:227]
	v_pk_mul_f32 v[62:63], v[62:63], v[204:205]
	v_pk_mul_f32 v[58:59], v[58:59], v[216:217]
	v_pk_mul_f32 v[54:55], v[54:55], v[220:221]
	v_pk_mul_f32 v[50:51], v[50:51], v[224:225]
	v_pk_mul_f32 v[48:49], v[48:49], v[206:207]
	v_pk_mul_f32 v[44:45], v[44:45], v[218:219]
	v_pk_mul_f32 v[40:41], v[40:41], v[222:223]
	v_pk_mul_f32 v[36:37], v[36:37], v[226:227]
	v_pk_mul_f32 v[46:47], v[46:47], v[204:205]
	v_pk_mul_f32 v[42:43], v[42:43], v[216:217]
	v_pk_mul_f32 v[38:39], v[38:39], v[220:221]
	v_pk_mul_f32 v[34:35], v[34:35], v[224:225]
	v_pk_mul_f32 v[32:33], v[32:33], v[206:207]
	v_pk_mul_f32 v[28:29], v[28:29], v[218:219]
	v_pk_mul_f32 v[24:25], v[24:25], v[222:223]
	v_pk_mul_f32 v[20:21], v[20:21], v[226:227]
	v_pk_mul_f32 v[30:31], v[30:31], v[204:205]
	v_pk_mul_f32 v[26:27], v[26:27], v[216:217]
	v_pk_mul_f32 v[22:23], v[22:23], v[220:221]
	v_pk_mul_f32 v[18:19], v[18:19], v[224:225]
	v_pk_mul_f32 v[16:17], v[16:17], v[206:207]
	v_pk_mul_f32 v[12:13], v[12:13], v[218:219]
	v_pk_mul_f32 v[8:9], v[8:9], v[222:223]
	v_pk_mul_f32 v[4:5], v[4:5], v[226:227]
	v_pk_mul_f32 v[14:15], v[14:15], v[204:205]
	v_pk_mul_f32 v[10:11], v[10:11], v[216:217]
	v_pk_mul_f32 v[6:7], v[6:7], v[220:221]
	v_pk_mul_f32 v[2:3], v[2:3], v[224:225]

; template <int MODE, bool SAMPLE>
; __device__ __forceinline__ void attn_unit(const Params& p, char* lds, int b, int h, int qb) {
;     ...
;         WRITET(buf, stg2[NS == 2 ? par : 0]);
;         if (j >= NS) LOADT(j - NS, stg2[NS == 2 ? par : 0]);
;         __syncthreads();
.LBB0_622:
	v_and_b32_e32 v76, 15, v183
	v_bfe_u32 v77, v183, 4, 3
	v_xor_b32_e32 v78, v76, v77
	v_lshrrev_b32_e32 v74, 1, v76
	v_xor_b32_e32 v74, v74, v77
	v_sub_u32_e32 v74, v74, v78
	v_and_b32_e32 v78, 1, v76
	v_lshlrev_b32_e32 v74, 4, v74
	v_lshl_add_u32 v74, v78, 3, v74
	v_lshrrev_b32_e32 v75, 3, v76
	v_lshrrev_b32_e32 v78, 2, v76
	v_sub_u32_e32 v75, v75, v78
	v_lshlrev_b32_e32 v75, 9, v75
	v_and_b32_e32 v78, 7, v76
	v_lshl_add_u32 v75, v78, 3, v75
	v_and_b32_e32 v78, 3, v76
	v_lshlrev_b32_e32 v78, 4, v78
	v_sub_u32_e32 v75, v75, v78
	v_add_u32_e32 v70, v133, v74
	v_add_u32_e32 v71, v198, v74
	v_add_u32_e32 v72, v199, v75
	v_add_u32_e32 v73, v200, v75
	s_waitcnt vmcnt(6)
	v_cvt_pk_bf16_f32 v66, v102, v103
	v_cvt_pk_bf16_f32 v67, v104, v105
	v_cvt_pk_bf16_f32 v68, v98, v99
	v_cvt_pk_bf16_f32 v69, v100, v101
	ds_write_b64 v70, v[66:67]
	ds_write_b64 v70, v[68:69] offset:128
	s_waitcnt vmcnt(4)
	v_cvt_pk_bf16_f32 v66, v110, v111
	v_cvt_pk_bf16_f32 v67, v112, v113
	v_cvt_pk_bf16_f32 v68, v106, v107
	v_cvt_pk_bf16_f32 v69, v108, v109
	ds_write_b64 v71, v[66:67]
	ds_write_b64 v71, v[68:69] offset:128
	s_waitcnt vmcnt(2)
	v_cvt_pk_bf16_f32 v66, v122, v123
	v_cvt_pk_bf16_f32 v67, v124, v125
	v_cvt_pk_bf16_f32 v68, v114, v115
	v_cvt_pk_bf16_f32 v69, v116, v117
	s_cmpk_eq_i32 s97, 0xf000
	ds_write_b64 v72, v[66:67] offset:32768
	ds_write_b64 v72, v[68:69] offset:33792
	s_waitcnt vmcnt(0)
	v_cvt_pk_bf16_f32 v66, v126, v127
	v_cvt_pk_bf16_f32 v67, v128, v129
	v_cvt_pk_bf16_f32 v68, v118, v119
	v_cvt_pk_bf16_f32 v69, v120, v121
	ds_write_b64 v73, v[66:67] offset:32768
	ds_write_b64 v73, v[68:69] offset:33792
.Lfsr_join_f1:
	s_cbranch_scc1 .LBB0_624
	s_lshl_b64 s[4:5], s[54:55], 10
	v_lshl_add_u64 v[66:67], s[4:5], 0, v[168:169]
	v_readlane_b32 s36, v253, 16
	v_lshlrev_b64 v[66:67], 2, v[66:67]
	v_and_b32_e32 v72, 15, v183
	v_lshlrev_b32_e32 v72, 4, v72
	v_sub_u32_e32 v66, v66, v72
	v_readlane_b32 s40, v253, 20
	v_readlane_b32 s41, v253, 21
	v_readlane_b32 s42, v253, 22
	v_readlane_b32 s43, v253, 23
	v_lshl_add_u64 v[68:69], s[40:41], 0, v[66:67]
	v_mov_b32_e32 v165, v1
	v_lshl_add_u64 v[70:71], v[68:69], 0, v[0:1]
	v_lshl_add_u64 v[68:69], v[68:69], 0, v[164:165]
	v_lshl_add_u64 v[66:67], s[42:43], 0, v[66:67]
	global_load_dwordx4 v[98:101], v[70:71], off offset:256 nt
	global_load_dwordx4 v[102:105], v[70:71], off nt
	global_load_dwordx4 v[106:109], v[68:69], off offset:256 nt
	global_load_dwordx4 v[110:113], v[68:69], off nt
	v_lshl_add_u64 v[68:69], v[66:67], 0, v[0:1]
	v_lshl_add_u64 v[66:67], v[66:67], 0, v[164:165]
	global_load_dwordx4 v[114:117], v[68:69], off offset:256 nt
	global_load_dwordx4 v[122:125], v[68:69], off nt
	global_load_dwordx4 v[118:121], v[66:67], off offset:256 nt
	global_load_dwordx4 v[126:129], v[66:67], off nt
	v_readlane_b32 s37, v253, 17
	v_readlane_b32 s38, v253, 18
	v_readlane_b32 s39, v253, 19
	v_readlane_b32 s44, v253, 24
	v_readlane_b32 s45, v253, 25
	v_readlane_b32 s46, v253, 26
	v_readlane_b32 s47, v253, 27
	v_readlane_b32 s48, v253, 28
	v_readlane_b32 s49, v253, 29
	v_readlane_b32 s50, v253, 30
	v_readlane_b32 s51, v253, 31

.Lfsr_first_s1:
	s_waitcnt vmcnt(6)
	v_cvt_pk_bf16_f32 v66, v102, v103
	v_cvt_pk_bf16_f32 v67, v104, v105
	s_waitcnt vmcnt(6)
	v_cvt_pk_bf16_f32 v68, v98, v99
	v_cvt_pk_bf16_f32 v69, v100, v101
	ds_write_b128 v133, v[66:69]
	s_waitcnt vmcnt(4)
	v_cvt_pk_bf16_f32 v66, v110, v111
	v_cvt_pk_bf16_f32 v67, v112, v113
	s_waitcnt vmcnt(4)
	v_cvt_pk_bf16_f32 v68, v106, v107
	v_cvt_pk_bf16_f32 v69, v108, v109
	ds_write_b128 v198, v[66:69]
	s_waitcnt vmcnt(2)
	v_cvt_pk_bf16_f32 v66, v118, v119
	v_cvt_pk_bf16_f32 v67, v120, v121
	s_waitcnt vmcnt(2)
	v_cvt_pk_bf16_f32 v68, v114, v115
	v_cvt_pk_bf16_f32 v69, v116, v117
	s_cmp_eq_u32 s4, 0xffc00000
	ds_write_b128 v199, v[66:69] offset:32768
	s_waitcnt vmcnt(0)
	v_cvt_pk_bf16_f32 v66, v126, v127
	v_cvt_pk_bf16_f32 v67, v128, v129
	s_waitcnt vmcnt(0)
	v_cvt_pk_bf16_f32 v68, v122, v123
	v_cvt_pk_bf16_f32 v69, v124, v125
	ds_write_b128 v200, v[66:69] offset:32768
	s_branch .Lfsr_join_s1

; template <int MODE, bool SAMPLE>
; __device__ __forceinline__ void attn_unit(const Params& p, char* lds, int b, int h, int qb) {
;     ...
;             } else {
;                 p0 = f32x16{}; p1 = f32x16{};
;                 qkt(p0, p1, Kt, Qs, r32, hi);
.LBB0_639:
	v_cndmask_b32_e64 v66, 0, 1, s[72:73]
	s_cmp_lt_u32 s9, 8
	v_cmp_ne_u32_e64 s[0:1], 1, v66
	s_cbranch_scc0 .Lfsr_first_s1
	v_and_b32_e32 v76, 15, v183
	v_bfe_u32 v77, v183, 4, 3
	v_xor_b32_e32 v78, v76, v77
	v_lshrrev_b32_e32 v74, 1, v76
	v_xor_b32_e32 v74, v74, v77
	v_sub_u32_e32 v74, v74, v78
	v_and_b32_e32 v78, 1, v76
	v_lshlrev_b32_e32 v74, 4, v74
	v_lshl_add_u32 v74, v78, 3, v74
	v_lshrrev_b32_e32 v75, 3, v76
	v_lshrrev_b32_e32 v78, 2, v76
	v_sub_u32_e32 v75, v75, v78
	v_lshlrev_b32_e32 v75, 9, v75
	v_and_b32_e32 v78, 7, v76
	v_lshl_add_u32 v75, v78, 3, v75
	v_and_b32_e32 v78, 3, v76
	v_lshlrev_b32_e32 v78, 4, v78
	v_sub_u32_e32 v75, v75, v78
	v_add_u32_e32 v70, v133, v74
	v_add_u32_e32 v71, v198, v74
	v_add_u32_e32 v72, v199, v75
	v_add_u32_e32 v73, v200, v75
	s_waitcnt vmcnt(6)
	v_cvt_pk_bf16_f32 v66, v102, v103
	v_cvt_pk_bf16_f32 v67, v104, v105
	v_cvt_pk_bf16_f32 v68, v98, v99
	v_cvt_pk_bf16_f32 v69, v100, v101
	ds_write_b64 v70, v[66:67] offset:16384
	ds_write_b64 v70, v[68:69] offset:16512
	s_waitcnt vmcnt(4)
	v_cvt_pk_bf16_f32 v66, v110, v111
	v_cvt_pk_bf16_f32 v67, v112, v113
	v_cvt_pk_bf16_f32 v68, v106, v107
	v_cvt_pk_bf16_f32 v69, v108, v109
	ds_write_b64 v71, v[66:67] offset:16384
	ds_write_b64 v71, v[68:69] offset:16512
	s_waitcnt vmcnt(2)
	v_cvt_pk_bf16_f32 v66, v118, v119
	v_cvt_pk_bf16_f32 v67, v120, v121
	v_cvt_pk_bf16_f32 v68, v114, v115
	v_cvt_pk_bf16_f32 v69, v116, v117
	ds_write_b64 v72, v[66:67] offset:49152
	ds_write_b64 v72, v[68:69] offset:50176
	s_waitcnt vmcnt(0)
	v_cvt_pk_bf16_f32 v66, v126, v127
	v_cvt_pk_bf16_f32 v67, v128, v129
	v_cvt_pk_bf16_f32 v68, v122, v123
	v_cvt_pk_bf16_f32 v69, v124, v125
	ds_write_b64 v73, v[66:67] offset:49152
	ds_write_b64 v73, v[68:69] offset:50176
	v_lshl_add_u64 v[66:67], v[168:169], 0, s[4:5]
	v_and_b32_e32 v72, 15, v183
	v_lshlrev_b32_e32 v72, 4, v72
	v_sub_co_u32_e32 v66, vcc, v66, v72
	s_nop 1
	v_subbrev_co_u32_e32 v67, vcc, 0, v67, vcc
	v_add_co_u32_e32 v70, vcc, s86, v66
	v_lshl_add_u64 v[68:69], v[66:67], 0, s[58:59]
	s_nop 0
	v_addc_co_u32_e32 v71, vcc, 0, v67, vcc
	s_mov_b32 s6, 0x420000
	global_load_dwordx4 v[102:105], v[70:71], off nt
	global_load_dwordx4 v[98:101], v[68:69], off offset:256 nt
	v_lshl_add_u64 v[68:69], v[66:67], 0, s[60:61]
	v_add_co_u32_e32 v66, vcc, s6, v66
	s_nop 1
	v_addc_co_u32_e32 v67, vcc, 0, v67, vcc
	global_load_dwordx4 v[110:113], v[66:67], off nt
	global_load_dwordx4 v[106:109], v[68:69], off offset:256 nt
	v_lshl_add_u64 v[66:67], v[170:171], 0, s[4:5]
	v_and_b32_e32 v72, 15, v183
	v_lshlrev_b32_e32 v72, 4, v72
	v_sub_co_u32_e32 v66, vcc, v66, v72
	s_nop 1
	v_subbrev_co_u32_e32 v67, vcc, 0, v67, vcc
	v_add_co_u32_e32 v70, vcc, s86, v66
	v_lshl_add_u64 v[68:69], v[66:67], 0, s[58:59]
	s_nop 0
	v_addc_co_u32_e32 v71, vcc, 0, v67, vcc
	global_load_dwordx4 v[118:121], v[70:71], off nt
	global_load_dwordx4 v[114:117], v[68:69], off offset:256 nt
	v_lshl_add_u64 v[68:69], v[66:67], 0, s[60:61]
	v_add_co_u32_e32 v66, vcc, 0x420000, v66
	s_nop 1
	v_addc_co_u32_e32 v67, vcc, 0, v67, vcc
	global_load_dwordx4 v[126:129], v[66:67], off nt
	global_load_dwordx4 v[122:125], v[68:69], off offset:256 nt
	s_and_b64 vcc, exec, s[0:1]
	s_waitcnt lgkmcnt(0)
	s_barrier
	s_cbranch_vccnz .LBB0_642
	ds_read_b128 v[66:69], v202 offset:16384
	v_add_u32_e32 v70, s8, v182
	ds_read_b128 v[70:73], v70
	ds_read_b128 v[74:77], v202 offset:24576
	v_add_u32_e32 v78, s8, v184
	ds_read_b128 v[216:219], v78
	ds_read_b128 v[220:223], v203 offset:16384
	ds_read_b128 v[224:227], v203 offset:24576
	v_add_u32_e32 v147, s8, v185
	s_waitcnt lgkmcnt(4)
	v_mfma_f32_32x32x16_bf16 v[82:97], v[66:69], v[70:73], 0
	s_waitcnt lgkmcnt(3)
	v_mfma_f32_32x32x16_bf16 v[66:81], v[74:77], v[70:73], 0
	s_waitcnt lgkmcnt(1)
	v_mfma_f32_32x32x16_bf16 v[82:97], v[220:223], v[216:219], v[82:97]
	s_waitcnt lgkmcnt(0)
	v_mfma_f32_32x32x16_bf16 v[66:81], v[224:227], v[216:219], v[66:81]
	ds_read_b128 v[216:219], v204 offset:16384
	ds_read_b128 v[220:223], v147
	ds_read_b128 v[224:227], v204 offset:24576
	v_add_u32_e32 v147, s8, v186
	ds_read_b128 v[228:231], v147
	v_add_u32_e32 v147, s8, v187
	s_waitcnt lgkmcnt(2)
	v_mfma_f32_32x32x16_bf16 v[82:97], v[216:219], v[220:223], v[82:97]
	s_waitcnt lgkmcnt(1)
	v_mfma_f32_32x32x16_bf16 v[66:81], v[224:227], v[220:223], v[66:81]
	ds_read_b128 v[216:219], v205 offset:16384
	ds_read_b128 v[220:223], v205 offset:24576
	s_waitcnt lgkmcnt(1)
	v_mfma_f32_32x32x16_bf16 v[82:97], v[216:219], v[228:231], v[82:97]
	ds_read_b128 v[216:219], v206 offset:16384
	s_waitcnt lgkmcnt(1)
	v_mfma_f32_32x32x16_bf16 v[66:81], v[220:223], v[228:231], v[66:81]
	ds_read_b128 v[220:223], v147
	ds_read_b128 v[224:227], v206 offset:24576
	v_add_u32_e32 v147, s8, v188
	ds_read_b128 v[228:231], v147
	v_add_u32_e32 v147, s8, v189
	s_waitcnt lgkmcnt(1)
	v_mfma_f32_32x32x16_bf16 v[66:81], v[224:227], v[220:223], v[66:81]
	v_mfma_f32_32x32x16_bf16 v[82:97], v[216:219], v[220:223], v[82:97]
	ds_read_b128 v[216:219], v207 offset:16384
	ds_read_b128 v[220:223], v207 offset:24576
	s_waitcnt lgkmcnt(0)
	v_mfma_f32_32x32x16_bf16 v[66:81], v[220:223], v[228:231], v[66:81]
	v_mfma_f32_32x32x16_bf16 v[82:97], v[216:219], v[228:231], v[82:97]
	ds_read_b128 v[216:219], v208 offset:16384
	ds_read_b128 v[220:223], v147
	ds_read_b128 v[224:227], v208 offset:24576
	v_add_u32_e32 v147, s8, v190
	ds_read_b128 v[228:231], v147
	s_waitcnt lgkmcnt(1)
	v_mfma_f32_32x32x16_bf16 v[66:81], v[224:227], v[220:223], v[66:81]
	v_mfma_f32_32x32x16_bf16 v[82:97], v[216:219], v[220:223], v[82:97]
	ds_read_b128 v[216:219], v209 offset:16384
	ds_read_b128 v[220:223], v209 offset:24576
	s_waitcnt lgkmcnt(0)
; __device__ __forceinline__ int crow(int r, int hi) { return (r & 3) + 8 * (r >> 2) + 4 * hi; }
; template <int MODE, bool SAMPLE>
; __device__ __forceinline__ void attn_unit(const Params& p, char* lds, int b, int h, int qb) {
;     ...
;                 if (j == jd) {
; #pragma unroll
;                     for (int r = 0; r < 16; ++r) { const int kp = j * 64 + crow(r, hi); if (kp >= qpos) p0[r] = -1e30f; if (kp + 32 >= qpos) p1[r] = -1e30f; } }
;                 f32x16 s0, s1;
; #pragma unroll
;                 for (int r = 0; r < 16; ++r) { p0[r] = __builtin_amdgcn_exp2f(fminf(p0[r], 100.f)); p1[r] = __builtin_amdgcn_exp2f(fminf(p1[r], 100.f));
;                     s0[r] = __builtin_amdgcn_rcpf(1.f + p0[r]); s1[r] = __builtin_amdgcn_rcpf(1.f + p1[r]); }
;                 float run = carry, bs[8];
; #pragma unroll
;                 for (int i = 7; i >= 0; --i) { const f32x16& S = (i >= 4) ? s1 : s0; const int rb = 4 * (i & 3);
;                     const float gs = (S[rb] * S[rb + 1]) * (S[rb + 2] * S[rb + 3]);
;                     auto rr = __builtin_amdgcn_permlane32_swap(__float_as_uint(gs), __float_as_uint(gs), false, false);
;                     const float glo = __uint_as_float(rr[0]), ghi = __uint_as_float(rr[1]);
;                     const float exH = run; run *= ghi; const float exL = run; run *= glo;
;                     bs[i] = hi ? exH : exL; }
;                 carry = run;
	v_mfma_f32_32x32x16_bf16 v[66:81], v[220:223], v[228:231], v[66:81]
	v_mfma_f32_32x32x16_bf16 v[82:97], v[216:219], v[228:231], v[82:97]
	s_nop 10
	v_max_f32_e32 v69, v69, v69
	v_min_f32_e32 v69, 0x42c80000, v69
	v_exp_f32_e32 v219, v69
	v_max_f32_e32 v81, v81, v81
	v_min_f32_e32 v81, 0x42c80000, v81
	v_max_f32_e32 v68, v68, v68
	v_max_f32_e32 v66, v66, v66
	v_max_f32_e32 v69, v86, v86
	v_min_f32_e32 v69, 0x42c80000, v69
	v_exp_f32_e32 v86, v69
	v_max_f32_e32 v69, v70, v70
	v_max_f32_e32 v70, v87, v87
	v_min_f32_e32 v70, 0x42c80000, v70
	v_exp_f32_e32 v87, v70
	v_max_f32_e32 v70, v71, v71
	v_max_f32_e32 v71, v88, v88
	v_min_f32_e32 v71, 0x42c80000, v71
	v_exp_f32_e32 v88, v71
	v_max_f32_e32 v71, v72, v72
	v_max_f32_e32 v72, v89, v89
	v_min_f32_e32 v72, 0x42c80000, v72
	v_exp_f32_e32 v89, v72
	v_max_f32_e32 v72, v73, v73
	v_max_f32_e32 v73, v90, v90
	v_min_f32_e32 v73, 0x42c80000, v73
	v_exp_f32_e32 v90, v73
	v_max_f32_e32 v73, v74, v74
	v_max_f32_e32 v74, v91, v91
	v_min_f32_e32 v74, 0x42c80000, v74
	v_exp_f32_e32 v91, v74
	v_max_f32_e32 v74, v75, v75
	v_max_f32_e32 v75, v92, v92
	v_min_f32_e32 v75, 0x42c80000, v75
	v_exp_f32_e32 v92, v75
	v_max_f32_e32 v75, v76, v76
	v_max_f32_e32 v76, v93, v93
	v_min_f32_e32 v76, 0x42c80000, v76
	v_exp_f32_e32 v93, v76
	v_max_f32_e32 v76, v77, v77
	v_max_f32_e32 v77, v94, v94
	v_min_f32_e32 v77, 0x42c80000, v77
	v_exp_f32_e32 v94, v77
	v_max_f32_e32 v77, v78, v78
	v_max_f32_e32 v78, v95, v95
	v_min_f32_e32 v78, 0x42c80000, v78
	v_exp_f32_e32 v95, v78
	v_max_f32_e32 v78, v79, v79
	v_max_f32_e32 v79, v96, v96
	v_min_f32_e32 v79, 0x42c80000, v79
	v_min_f32_e32 v77, 0x42c80000, v77
	v_exp_f32_e32 v96, v79
	v_max_f32_e32 v79, v80, v80
	v_exp_f32_e32 v237, v77
	v_min_f32_e32 v79, 0x42c80000, v79
	v_min_f32_e32 v78, 0x42c80000, v78
	v_exp_f32_e32 v241, v79
	v_exp_f32_e32 v239, v78
	v_max_f32_e32 v80, v97, v97
	v_exp_f32_e32 v97, v81
	v_min_f32_e32 v73, 0x42c80000, v73
	v_add_f32_e32 v77, 1.0, v237
	v_exp_f32_e32 v229, v73
	v_rcp_f32_e32 v240, v77
	v_add_f32_e32 v77, 1.0, v95
	v_add_f32_e32 v79, 1.0, v241
	v_min_f32_e32 v74, 0x42c80000, v74
	v_min_f32_e32 v75, 0x42c80000, v75
	v_min_f32_e32 v76, 0x42c80000, v76
	v_rcp_f32_e32 v78, v77
	v_add_f32_e32 v77, 1.0, v239
	v_rcp_f32_e32 v244, v79
	v_add_f32_e32 v79, 1.0, v97
	v_exp_f32_e32 v231, v74
	v_exp_f32_e32 v233, v75
	v_exp_f32_e32 v235, v76
	v_rcp_f32_e32 v242, v77
	v_rcp_f32_e32 v245, v79
	v_min_f32_e32 v69, 0x42c80000, v69
	v_add_f32_e32 v73, 1.0, v229
	v_max_f32_e32 v83, v83, v83
	v_exp_f32_e32 v221, v69
	v_rcp_f32_e32 v232, v73
	v_add_f32_e32 v73, 1.0, v91
	v_min_f32_e32 v80, 0x42c80000, v80
	v_min_f32_e32 v83, 0x42c80000, v83
	v_min_f32_e32 v70, 0x42c80000, v70
	v_min_f32_e32 v71, 0x42c80000, v71
	v_min_f32_e32 v72, 0x42c80000, v72
	v_rcp_f32_e32 v74, v73
	v_add_f32_e32 v73, 1.0, v231
	v_add_f32_e32 v75, 1.0, v233
	v_add_f32_e32 v76, 1.0, v235
	v_exp_f32_e32 v243, v80
	v_mul_f32_e32 v80, v240, v242
	v_mul_f32_e32 v81, v244, v245
	v_exp_f32_e32 v165, v83
	v_max_f32_e32 v83, v84, v84
	v_exp_f32_e32 v223, v70
	v_exp_f32_e32 v225, v71
	v_exp_f32_e32 v227, v72
	v_rcp_f32_e32 v234, v73
	v_rcp_f32_e32 v236, v75
	v_rcp_f32_e32 v238, v76
	v_mul_f32_e32 v80, v80, v81
	v_min_f32_e32 v83, 0x42c80000, v83
	v_mov_b32_e32 v81, v80
	v_exp_f32_e32 v84, v83
	v_min_f32_e32 v68, 0x42c80000, v68
	v_max_f32_e32 v83, v85, v85
	v_add_f32_e32 v69, 1.0, v221
	v_permlane32_swap_b32_e32 v80, v81
	v_min_f32_e32 v66, 0x42c80000, v66
	v_max_f32_e32 v67, v67, v67
	v_exp_f32_e32 v217, v68
	v_min_f32_e32 v83, 0x42c80000, v83
	v_rcp_f32_e32 v224, v69
	v_add_f32_e32 v69, 1.0, v87
	v_mul_f32_e32 v81, v145, v81
	v_exp_f32_e32 v163, v66
	v_min_f32_e32 v67, 0x42c80000, v67
	v_exp_f32_e32 v85, v83
	v_rcp_f32_e32 v70, v69
	v_add_f32_e32 v69, 1.0, v223
	v_add_f32_e32 v71, 1.0, v225
	v_add_f32_e32 v72, 1.0, v227
	v_mul_f32_e32 v80, v81, v80
	v_cndmask_b32_e64 v145, v145, v81, s[14:15]
	v_mul_f32_e32 v81, v232, v234
	v_mul_f32_e32 v246, v236, v238
	v_exp_f32_e32 v215, v67
	v_rcp_f32_e32 v226, v69
	v_rcp_f32_e32 v228, v71
	v_rcp_f32_e32 v230, v72
	v_mul_f32_e32 v81, v81, v246
	v_max_f32_e32 v82, v82, v82
	v_mov_b32_e32 v246, v81
	v_min_f32_e32 v82, 0x42c80000, v82
	v_add_f32_e32 v68, 1.0, v217
	v_permlane32_swap_b32_e32 v81, v246
	v_exp_f32_e32 v147, v82
	v_add_f32_e32 v82, 1.0, v163
	v_add_f32_e32 v67, 1.0, v165
	v_rcp_f32_e32 v220, v68
	v_add_f32_e32 v68, 1.0, v85
	v_mul_f32_e32 v246, v80, v246
	v_rcp_f32_e32 v216, v82
	v_rcp_f32_e32 v82, v67
	v_add_f32_e32 v67, 1.0, v215
	v_rcp_f32_e32 v83, v68
	v_add_f32_e32 v68, 1.0, v219
	v_mul_f32_e32 v81, v246, v81
	v_cndmask_b32_e64 v246, v80, v246, s[14:15]
	v_mul_f32_e32 v80, v224, v226
	v_mul_f32_e32 v247, v228, v230
	v_rcp_f32_e32 v218, v67
	v_rcp_f32_e32 v222, v68
	v_mul_f32_e32 v80, v80, v247
	v_mov_b32_e32 v247, v80
	s_nop 1
	v_permlane32_swap_b32_e32 v80, v247
	v_mul_f32_e32 v247, v81, v247
	v_add_f32_e32 v76, 1.0, v94
	v_add_f32_e32 v77, 1.0, v96
	v_add_f32_e32 v79, 1.0, v243
	v_mul_f32_e32 v80, v247, v80
	v_cndmask_b32_e64 v247, v81, v247, s[14:15]
	v_mul_f32_e32 v81, v216, v218
	v_mul_f32_e32 v248, v220, v222
	v_rcp_f32_e32 v76, v76
	v_rcp_f32_e32 v77, v77
	v_rcp_f32_e32 v79, v79
	v_mul_f32_e32 v81, v81, v248
	v_mov_b32_e32 v248, v81
	s_nop 1
	v_permlane32_swap_b32_e32 v81, v248
	v_mul_f32_e32 v248, v80, v248
	v_add_f32_e32 v72, 1.0, v90
	v_add_f32_e32 v73, 1.0, v92
	v_add_f32_e32 v75, 1.0, v93
	v_mul_f32_e32 v249, v248, v81
	v_cndmask_b32_e64 v248, v80, v248, s[14:15]
	v_pk_mul_f32 v[80:81], v[76:77], v[78:79]
	v_rcp_f32_e32 v72, v72
	v_rcp_f32_e32 v73, v73
	v_rcp_f32_e32 v75, v75
	v_pk_mul_f32 v[80:81], v[80:81], v[80:81] op_sel:[0,1] op_sel_hi:[1,0]
; #define SBAR() __builtin_amdgcn_sched_barrier(0)
; template <int OFF> __device__ __forceinline__ s16x4 tr_read(int vb) { s16x4 r; asm volatile("ds_read_b64_tr_b16 %0, %1 offset:%2" : "=&v"(r) : "v"(vb), "i"(OFF) : "memory"); return r; }
; template <int D0> __device__ __forceinline__ void pv_one(f32x16& od, int vb, bf16x8 pa0, bf16x8 pa1, bf16x8 pa2, bf16x8 pa3) {
;     const s16x4 l0 = tr_read<v_rd_off(D0, 0, 0)>(vb), h0 = tr_read<v_rd_off(D0, 0, 1)>(vb), l1 = tr_read<v_rd_off(D0, 1, 0)>(vb), h1 = tr_read<v_rd_off(D0, 1, 1)>(vb);
;     const s16x4 l2 = tr_read<v_rd_off(D0, 2, 0)>(vb), h2 = tr_read<v_rd_off(D0, 2, 1)>(vb), l3 = tr_read<v_rd_off(D0, 3, 0)>(vb), h3 = tr_read<v_rd_off(D0, 3, 1)>(vb);
;     asm volatile("s_waitcnt lgkmcnt(0)" ::: "memory"); SBAR();
;     ...
;     od = __builtin_amdgcn_mfma_f32_32x32x16_bf16(pa0, PKV(l0, h0), od, 0, 0, 0);
;     od = __builtin_amdgcn_mfma_f32_32x32x16_bf16(pa1, PKV(l1, h1), od, 0, 0, 0);
;     od = __builtin_amdgcn_mfma_f32_32x32x16_bf16(pa2, PKV(l2, h2), od, 0, 0, 0);
;     od = __builtin_amdgcn_mfma_f32_32x32x16_bf16(pa3, PKV(l3, h3), od, 0, 0, 0);
;     ...
; }
; __device__ __forceinline__ void pv_d0(f32x16* o, int vb, bf16x8 pa0, bf16x8 pa1, bf16x8 pa2, bf16x8 pa3) {
;     pv_one<0>(o[0], vb, pa0, pa1, pa2, pa3); pv_one<1>(o[1], vb, pa0, pa1, pa2, pa3); pv_one<2>(o[2], vb, pa0, pa1, pa2, pa3); pv_one<3>(o[3], vb, pa0, pa1, pa2, pa3);
; template <int MODE, bool SAMPLE>
; __device__ __forceinline__ void attn_unit(const Params& p, char* lds, int b, int h, int qb) {
;     ...
; #pragma unroll
;                 for (int i = 0; i < 8; ++i) { f32x16& S = (i >= 4) ? s1 : s0; f32x16& Z = (i >= 4) ? p1 : p0; const int rb = 4 * (i & 3);
;                     const float i3 = bs[i] * S[rb + 3], i2 = i3 * S[rb + 2], i1 = i2 * S[rb + 1], i0 = i1 * S[rb];
;                     Z[rb + 3] *= i3; Z[rb + 2] *= i2; Z[rb + 1] *= i1; Z[rb] *= i0; }
;             }
;             PK4(p0, 0, pa0); PK4(p0, 8, pa1); PK4(p1, 0, pa2); PK4(p1, 8, pa3);
;             pv_d0(o, vb, pa0, pa1, pa2, pa3);
	v_add_f32_e32 v68, 1.0, v86
	v_mov_b32_e32 v81, v80
	s_nop 1
	v_permlane32_swap_b32_e32 v80, v81
	v_mul_f32_e32 v81, v249, v81
	v_add_f32_e32 v69, 1.0, v88
	v_add_f32_e32 v71, 1.0, v89
	v_mul_f32_e32 v250, v81, v80
	v_cndmask_b32_e64 v249, v249, v81, s[14:15]
	v_pk_mul_f32 v[80:81], v[72:73], v[74:75]
	v_rcp_f32_e32 v68, v68
	v_rcp_f32_e32 v69, v69
	v_rcp_f32_e32 v71, v71
	v_pk_mul_f32 v[80:81], v[80:81], v[80:81] op_sel:[0,1] op_sel_hi:[1,0]
	v_add_f32_e32 v66, 1.0, v147
	v_mov_b32_e32 v81, v80
	s_nop 1
	v_permlane32_swap_b32_e32 v80, v81
	v_mul_f32_e32 v81, v250, v81
	v_add_f32_e32 v67, 1.0, v84
	v_mul_f32_e32 v251, v81, v80
	v_cndmask_b32_e64 v250, v250, v81, s[14:15]
	v_pk_mul_f32 v[80:81], v[68:69], v[70:71]
	v_rcp_f32_e32 v66, v66
	v_rcp_f32_e32 v67, v67
	v_pk_mul_f32 v[80:81], v[80:81], v[80:81] op_sel:[0,1] op_sel_hi:[1,0]
	v_mul_f32_e32 v75, v75, v250
	v_mov_b32_e32 v81, v80
	s_nop 1
	v_permlane32_swap_b32_e32 v80, v81
	v_mul_f32_e32 v81, v251, v81
	v_mul_f32_e32 v252, v81, v80
	v_cndmask_b32_e64 v251, v251, v81, s[14:15]
	v_pk_mul_f32 v[80:81], v[66:67], v[82:83]
	v_mul_f32_e32 v71, v71, v251
	v_pk_mul_f32 v[80:81], v[80:81], v[80:81] op_sel:[0,1] op_sel_hi:[1,0]
	v_mul_f32_e32 v69, v69, v71
	v_mov_b32_e32 v81, v80
	s_nop 1
	v_permlane32_swap_b32_e32 v80, v81
	v_mul_f32_e32 v81, v252, v81
	v_cndmask_b32_e64 v252, v252, v81, s[14:15]
	v_mul_f32_e32 v83, v83, v252
	v_mul_f32_e32 v67, v67, v83
	v_mul_f32_e32 v79, v79, v249
	v_mul_f32_e32 v82, v82, v67
	v_mul_f32_e32 v67, v84, v67
	v_mul_f32_e32 v70, v70, v69
	v_mul_f32_e32 v73, v73, v75
	v_mul_f32_e32 v77, v77, v79
	v_mul_f32_e32 v84, v222, v248
	v_mul_f32_e32 v83, v85, v83
	v_mul_f32_e32 v68, v68, v70
	v_mul_f32_e32 v69, v88, v69
	v_mul_f32_e32 v74, v74, v73
	v_mul_f32_e32 v73, v92, v73
	v_mul_f32_e32 v78, v78, v77
	v_mul_f32_e32 v77, v96, v77
	v_mul_f32_e32 v85, v220, v84
	v_mul_f32_e32 v88, v230, v247
	v_mul_f32_e32 v92, v238, v246
	v_mul_f32_e32 v96, v245, v145
	v_mul_f32_e32 v66, v66, v82
	v_mul_f32_e32 v71, v89, v71
	v_mul_f32_e32 v68, v86, v68
	v_mul_f32_e32 v72, v72, v74
	v_mul_f32_e32 v75, v93, v75
	v_mul_f32_e32 v76, v76, v78
	v_mul_f32_e32 v86, v218, v85
	v_mul_f32_e32 v89, v228, v88
	v_mul_f32_e32 v93, v236, v92
	v_mul_f32_e32 v145, v244, v96
	v_mul_f32_e32 v66, v147, v66
	v_mul_f32_e32 v70, v87, v70
	v_mul_f32_e32 v72, v90, v72
	v_mul_f32_e32 v76, v94, v76
	v_mul_f32_e32 v87, v216, v86
	v_mul_f32_e32 v90, v226, v89
	v_mul_f32_e32 v94, v234, v93
	v_mul_f32_e32 v147, v242, v145
	v_mul_f32_e32 v82, v165, v82
	v_mul_f32_e32 v74, v91, v74
	v_mul_f32_e32 v79, v243, v79
	v_mul_f32_e32 v78, v95, v78
	v_mul_f32_e32 v87, v163, v87
	v_mul_f32_e32 v91, v224, v90
	v_mul_f32_e32 v95, v232, v94
	v_mul_f32_e32 v163, v240, v147
	v_mul_f32_e32 v84, v219, v84
	v_mul_f32_e32 v85, v217, v85
	v_mul_f32_e32 v86, v215, v86
	v_mul_f32_e32 v88, v227, v88
	v_mul_f32_e32 v89, v225, v89
	v_mul_f32_e32 v90, v223, v90
	v_mul_f32_e32 v91, v221, v91
	v_mul_f32_e32 v92, v235, v92
	v_mul_f32_e32 v93, v233, v93
	v_mul_f32_e32 v94, v231, v94
	v_mul_f32_e32 v95, v229, v95
	v_mul_f32_e32 v96, v97, v96
	v_mul_f32_e32 v97, v241, v145
	v_mul_f32_e32 v147, v239, v147
	v_mul_f32_e32 v163, v237, v163
	v_mul_f32_e32 v145, v81, v80
	v_cvt_pk_bf16_f32 v66, v66, v82
	v_cvt_pk_bf16_f32 v67, v67, v83
	v_cvt_pk_bf16_f32 v68, v68, v70
	v_cvt_pk_bf16_f32 v69, v69, v71
	v_cvt_pk_bf16_f32 v70, v72, v74
	v_cvt_pk_bf16_f32 v71, v73, v75
	v_cvt_pk_bf16_f32 v72, v76, v78
	v_cvt_pk_bf16_f32 v73, v77, v79
	v_cvt_pk_bf16_f32 v74, v87, v86
	v_cvt_pk_bf16_f32 v75, v85, v84
	v_cvt_pk_bf16_f32 v76, v91, v90
	v_cvt_pk_bf16_f32 v77, v89, v88
	v_cvt_pk_bf16_f32 v78, v95, v94
	v_cvt_pk_bf16_f32 v79, v93, v92
	v_cvt_pk_bf16_f32 v80, v163, v147
	v_cvt_pk_bf16_f32 v81, v97, v96
	ds_read_b64_tr_b16 v[82:83], v191 offset:0
	ds_read_b64_tr_b16 v[84:85], v191 offset:0x800
	ds_read_b64_tr_b16 v[86:87], v191 offset:0x1000
	ds_read_b64_tr_b16 v[88:89], v191 offset:0x1800
	ds_read_b64_tr_b16 v[90:91], v191 offset:0x2000
	ds_read_b64_tr_b16 v[92:93], v191 offset:0x2800
	ds_read_b64_tr_b16 v[94:95], v191 offset:0x3000
	ds_read_b64_tr_b16 v[96:97], v191 offset:0x3800
	s_waitcnt lgkmcnt(0)
	s_nop 0
	v_permlane32_swap_b32_e32 v66, v68
	v_permlane32_swap_b32_e32 v67, v69
	v_permlane32_swap_b32_e32 v70, v72
	v_permlane32_swap_b32_e32 v71, v73
	v_permlane32_swap_b32_e32 v74, v76
	v_permlane32_swap_b32_e32 v75, v77
	v_permlane32_swap_b32_e32 v78, v80
	v_permlane32_swap_b32_e32 v79, v81
	v_mfma_f32_32x32x16_bf16 v[2:17], v[66:69], v[82:85], v[2:17]
	ds_read_b64_tr_b16 v[82:83], v191 offset:0x200
	ds_read_b64_tr_b16 v[84:85], v191 offset:0xa00
	v_mfma_f32_32x32x16_bf16 v[2:17], v[70:73], v[86:89], v[2:17]
	ds_read_b64_tr_b16 v[86:87], v191 offset:0x1200
	ds_read_b64_tr_b16 v[88:89], v191 offset:0x1a00
	v_mfma_f32_32x32x16_bf16 v[2:17], v[74:77], v[90:93], v[2:17]
	ds_read_b64_tr_b16 v[90:91], v191 offset:0x2200
	ds_read_b64_tr_b16 v[92:93], v191 offset:0x2a00
	v_mfma_f32_32x32x16_bf16 v[2:17], v[78:81], v[94:97], v[2:17]
	ds_read_b64_tr_b16 v[94:95], v191 offset:0x3200
	ds_read_b64_tr_b16 v[96:97], v191 offset:0x3a00
	s_waitcnt lgkmcnt(0)
	v_mfma_f32_32x32x16_bf16 v[50:65], v[66:69], v[82:85], v[50:65]
	ds_read_b64_tr_b16 v[82:83], v191 offset:0x400
	ds_read_b64_tr_b16 v[84:85], v191 offset:0xc00
	v_mfma_f32_32x32x16_bf16 v[50:65], v[70:73], v[86:89], v[50:65]
	ds_read_b64_tr_b16 v[86:87], v191 offset:0x1400
	ds_read_b64_tr_b16 v[88:89], v191 offset:0x1c00
	v_mfma_f32_32x32x16_bf16 v[50:65], v[74:77], v[90:93], v[50:65]
	ds_read_b64_tr_b16 v[90:91], v191 offset:0x2400
	ds_read_b64_tr_b16 v[92:93], v191 offset:0x2c00
	v_mfma_f32_32x32x16_bf16 v[50:65], v[78:81], v[94:97], v[50:65]
	ds_read_b64_tr_b16 v[94:95], v191 offset:0x3400
	ds_read_b64_tr_b16 v[96:97], v191 offset:0x3c00
	s_waitcnt lgkmcnt(0)
	v_mfma_f32_32x32x16_bf16 v[34:49], v[66:69], v[82:85], v[34:49]
	ds_read_b64_tr_b16 v[82:83], v191 offset:0x600
	ds_read_b64_tr_b16 v[84:85], v191 offset:0xe00
	v_mfma_f32_32x32x16_bf16 v[34:49], v[70:73], v[86:89], v[34:49]
	ds_read_b64_tr_b16 v[86:87], v191 offset:0x1600
	ds_read_b64_tr_b16 v[88:89], v191 offset:0x1e00
	v_mfma_f32_32x32x16_bf16 v[34:49], v[74:77], v[90:93], v[34:49]
	ds_read_b64_tr_b16 v[90:91], v191 offset:0x2600
	ds_read_b64_tr_b16 v[92:93], v191 offset:0x2e00
	v_mfma_f32_32x32x16_bf16 v[34:49], v[78:81], v[94:97], v[34:49]
	ds_read_b64_tr_b16 v[94:95], v191 offset:0x3600
	ds_read_b64_tr_b16 v[96:97], v191 offset:0x3e00
	s_waitcnt lgkmcnt(0)
	v_mfma_f32_32x32x16_bf16 v[18:33], v[66:69], v[82:85], v[18:33]
	v_mfma_f32_32x32x16_bf16 v[18:33], v[70:73], v[86:89], v[18:33]
	v_mfma_f32_32x32x16_bf16 v[18:33], v[74:77], v[90:93], v[18:33]
	v_mfma_f32_32x32x16_bf16 v[18:33], v[78:81], v[94:97], v[18:33]
; template <int MODE, bool SAMPLE>
; __device__ __forceinline__ void attn_unit(const Params& p, char* lds, int b, int h, int qb) {
;     ...
;         WRITET(buf, stg2[NS == 2 ? par : 0]);
;         if (j >= NS) LOADT(j - NS, stg2[NS == 2 ? par : 0]);
;         __syncthreads();
.LBB0_642:
	v_and_b32_e32 v76, 15, v183
	v_bfe_u32 v77, v183, 4, 3
	v_xor_b32_e32 v78, v76, v77
	v_lshrrev_b32_e32 v74, 1, v76
	v_xor_b32_e32 v74, v74, v77
	v_sub_u32_e32 v74, v74, v78
	v_and_b32_e32 v78, 1, v76
	v_lshlrev_b32_e32 v74, 4, v74
	v_lshl_add_u32 v74, v78, 3, v74
	v_lshrrev_b32_e32 v75, 3, v76
	v_lshrrev_b32_e32 v78, 2, v76
	v_sub_u32_e32 v75, v75, v78
	v_lshlrev_b32_e32 v75, 9, v75
	v_and_b32_e32 v78, 7, v76
	v_lshl_add_u32 v75, v78, 3, v75
	v_and_b32_e32 v78, 3, v76
	v_lshlrev_b32_e32 v78, 4, v78
	v_sub_u32_e32 v75, v75, v78
	v_add_u32_e32 v70, v133, v74
	v_add_u32_e32 v71, v198, v74
	v_add_u32_e32 v72, v199, v75
	v_add_u32_e32 v73, v200, v75
	s_waitcnt vmcnt(6)
	v_cvt_pk_bf16_f32 v66, v102, v103
	v_cvt_pk_bf16_f32 v67, v104, v105
	s_waitcnt vmcnt(6)
	v_cvt_pk_bf16_f32 v68, v98, v99
	v_cvt_pk_bf16_f32 v69, v100, v101
	ds_write_b64 v70, v[66:67]
	ds_write_b64 v70, v[68:69] offset:128
	s_waitcnt vmcnt(4)
	v_cvt_pk_bf16_f32 v66, v110, v111
	v_cvt_pk_bf16_f32 v67, v112, v113
	s_waitcnt vmcnt(4)
	v_cvt_pk_bf16_f32 v68, v106, v107
	v_cvt_pk_bf16_f32 v69, v108, v109
	ds_write_b64 v71, v[66:67]
	ds_write_b64 v71, v[68:69] offset:128
	s_waitcnt vmcnt(2)
	v_cvt_pk_bf16_f32 v66, v118, v119
	v_cvt_pk_bf16_f32 v67, v120, v121
	s_waitcnt vmcnt(2)
	v_cvt_pk_bf16_f32 v68, v114, v115
	v_cvt_pk_bf16_f32 v69, v116, v117
	s_cmp_eq_u32 s4, 0xffc00000
	ds_write_b64 v72, v[66:67] offset:32768
	ds_write_b64 v72, v[68:69] offset:33792
	s_waitcnt vmcnt(0)
	v_cvt_pk_bf16_f32 v66, v126, v127
	v_cvt_pk_bf16_f32 v67, v128, v129
	s_waitcnt vmcnt(0)
	v_cvt_pk_bf16_f32 v68, v122, v123
	v_cvt_pk_bf16_f32 v69, v124, v125
	ds_write_b64 v73, v[66:67] offset:32768
	ds_write_b64 v73, v[68:69] offset:33792
.Lfsr_join_s1:
	s_cbranch_scc1 .LBB0_644
	s_lshl_b64 s[10:11], s[54:55], 10
	v_lshl_add_u64 v[66:67], s[10:11], 0, v[166:167]
	v_readlane_b32 s36, v253, 16
	v_lshlrev_b64 v[66:67], 2, v[66:67]
	v_and_b32_e32 v72, 15, v183
	v_lshlrev_b32_e32 v72, 4, v72
	v_sub_u32_e32 v66, v66, v72
	v_readlane_b32 s46, v253, 26
	v_readlane_b32 s47, v253, 27
	v_readlane_b32 s48, v253, 28
	v_readlane_b32 s49, v253, 29
	v_lshl_add_u64 v[68:69], s[46:47], 0, v[66:67]
	v_mov_b32_e32 v165, v1
	v_lshl_add_u64 v[70:71], v[68:69], 0, v[0:1]
	v_lshl_add_u64 v[68:69], v[68:69], 0, v[164:165]
	v_lshl_add_u64 v[66:67], s[48:49], 0, v[66:67]
	global_load_dwordx4 v[98:101], v[70:71], off offset:256 nt
	global_load_dwordx4 v[102:105], v[70:71], off nt
	global_load_dwordx4 v[106:109], v[68:69], off offset:256 nt
	global_load_dwordx4 v[110:113], v[68:69], off nt
	v_lshl_add_u64 v[68:69], v[66:67], 0, v[0:1]
	v_lshl_add_u64 v[66:67], v[66:67], 0, v[164:165]
	global_load_dwordx4 v[114:117], v[68:69], off offset:256 nt
	global_load_dwordx4 v[118:121], v[68:69], off nt
	global_load_dwordx4 v[122:125], v[66:67], off offset:256 nt
	global_load_dwordx4 v[126:129], v[66:67], off nt
	v_readlane_b32 s37, v253, 17
	v_readlane_b32 s38, v253, 18
	v_readlane_b32 s39, v253, 19
	v_readlane_b32 s40, v253, 20
	v_readlane_b32 s41, v253, 21
	v_readlane_b32 s42, v253, 22
	v_readlane_b32 s43, v253, 23
	v_readlane_b32 s44, v253, 24
	v_readlane_b32 s45, v253, 25
	v_readlane_b32 s50, v253, 30
	v_readlane_b32 s51, v253, 31

.Lfsr_first_f2:
	s_waitcnt vmcnt(6)
	v_cvt_pk_bf16_f32 v66, v102, v103
	v_cvt_pk_bf16_f32 v67, v104, v105
	v_cvt_pk_bf16_f32 v68, v98, v99
	v_cvt_pk_bf16_f32 v69, v100, v101
	ds_write_b128 v198, v[66:69]
	s_waitcnt vmcnt(4)
	v_cvt_pk_bf16_f32 v66, v110, v111
	v_cvt_pk_bf16_f32 v67, v112, v113
	v_cvt_pk_bf16_f32 v68, v106, v107
	v_cvt_pk_bf16_f32 v69, v108, v109
	ds_write_b128 v199, v[66:69]
	s_waitcnt vmcnt(2)
	v_cvt_pk_bf16_f32 v66, v122, v123
	v_cvt_pk_bf16_f32 v67, v124, v125
	v_cvt_pk_bf16_f32 v68, v114, v115
	v_cvt_pk_bf16_f32 v69, v116, v117
	s_cmpk_eq_i32 s96, 0xf000
	ds_write_b128 v200, v[66:69] offset:32768
	s_waitcnt vmcnt(0)
	v_cvt_pk_bf16_f32 v66, v126, v127
	v_cvt_pk_bf16_f32 v67, v128, v129
	v_cvt_pk_bf16_f32 v68, v118, v119
	v_cvt_pk_bf16_f32 v69, v120, v121
	ds_write_b128 v201, v[66:69] offset:32768
	s_branch .Lfsr_join_f2

; template <int MODE, bool SAMPLE>
; __device__ __forceinline__ void attn_unit(const Params& p, char* lds, int b, int h, int qb) {
;     ...
;         WRITET(buf, stg2[NS == 2 ? par : 0]);
;         if (j >= NS) LOADT(j - NS, stg2[NS == 2 ? par : 0]);
;         __syncthreads();
;         if (wact && j <= jd && var < 2) {
;             const char* Kt = K_lds + buf * 16384; const int vb = vb0 + buf * 16384;
;             f32x16 p0, p1; bf16x8 pa0, pa1, pa2, pa3;
;             if (MODE == 0) {
;                 const float* bt = biasL + j * 64 + 4 * hi;
; #pragma unroll
;                 for (int g = 0; g < 4; ++g) { const f32x4 a = *(const f32x4*)(bt + 8 * g), c = *(const f32x4*)(bt + 32 + 8 * g);
; #pragma unroll
;                     for (int i = 0; i < 4; ++i) { p0[4 * g + i] = a[i]; p1[4 * g + i] = c[i]; } }
;                 qkt(p0, p1, Kt, Qs, r32, hi);
.LBB0_844:
	v_cndmask_b32_e64 v66, 0, 1, s[74:75]
	s_cmp_lt_u32 s55, 8
	v_lshlrev_b32_e32 v0, 2, v150
	v_lshlrev_b32_e32 v162, 2, v152
	v_cmp_ne_u32_e64 s[0:1], 1, v66
	s_cbranch_scc0 .Lfsr_first_f2
	v_and_b32_e32 v76, 15, v183
	v_bfe_u32 v77, v183, 4, 3
	v_xor_b32_e32 v78, v76, v77
	v_lshrrev_b32_e32 v74, 1, v76
	v_xor_b32_e32 v74, v74, v77
	v_sub_u32_e32 v74, v74, v78
	v_and_b32_e32 v78, 1, v76
	v_lshlrev_b32_e32 v74, 4, v74
	v_lshl_add_u32 v74, v78, 3, v74
	v_lshrrev_b32_e32 v75, 3, v76
	v_lshrrev_b32_e32 v78, 2, v76
	v_sub_u32_e32 v75, v75, v78
	v_lshlrev_b32_e32 v75, 9, v75
	v_and_b32_e32 v78, 7, v76
	v_lshl_add_u32 v75, v78, 3, v75
	v_and_b32_e32 v78, 3, v76
	v_lshlrev_b32_e32 v78, 4, v78
	v_sub_u32_e32 v75, v75, v78
	v_add_u32_e32 v70, v198, v74
	v_add_u32_e32 v71, v199, v74
	v_add_u32_e32 v72, v200, v75
	v_add_u32_e32 v73, v201, v75
	s_waitcnt vmcnt(6)
	v_cvt_pk_bf16_f32 v66, v102, v103
	v_cvt_pk_bf16_f32 v67, v104, v105
	v_cvt_pk_bf16_f32 v68, v98, v99
	v_cvt_pk_bf16_f32 v69, v100, v101
	ds_write_b64 v70, v[66:67] offset:16384
	ds_write_b64 v70, v[68:69] offset:16512
	s_waitcnt vmcnt(4)
	v_cvt_pk_bf16_f32 v66, v110, v111
	v_cvt_pk_bf16_f32 v67, v112, v113
	v_cvt_pk_bf16_f32 v68, v106, v107
	v_cvt_pk_bf16_f32 v69, v108, v109
	ds_write_b64 v71, v[66:67] offset:16384
	ds_write_b64 v71, v[68:69] offset:16512
	s_waitcnt vmcnt(2)
	v_cvt_pk_bf16_f32 v66, v122, v123
	v_cvt_pk_bf16_f32 v67, v124, v125
	v_cvt_pk_bf16_f32 v68, v114, v115
	v_cvt_pk_bf16_f32 v69, v116, v117
	ds_write_b64 v72, v[66:67] offset:49152
	ds_write_b64 v72, v[68:69] offset:50176
	s_waitcnt vmcnt(0)
	v_cvt_pk_bf16_f32 v66, v126, v127
	v_cvt_pk_bf16_f32 v67, v128, v129
	v_cvt_pk_bf16_f32 v68, v118, v119
	v_cvt_pk_bf16_f32 v69, v120, v121
	ds_write_b64 v73, v[66:67] offset:49152
	ds_write_b64 v73, v[68:69] offset:50176
	v_or_b32_e32 v67, s61, v169
	v_or_b32_e32 v66, s9, v168
	v_readlane_b32 s36, v253, 16
	v_lshlrev_b64 v[66:67], 2, v[66:67]
	v_and_b32_e32 v72, 15, v183
	v_lshlrev_b32_e32 v72, 4, v72
	v_sub_u32_e32 v66, v66, v72
	v_readlane_b32 s40, v253, 20
	v_readlane_b32 s41, v253, 21
	v_readlane_b32 s42, v253, 22
	v_readlane_b32 s43, v253, 23
	v_lshl_add_u64 v[68:69], s[40:41], 0, v[66:67]
	v_mov_b32_e32 v163, v1
	v_lshl_add_u64 v[70:71], v[68:69], 0, v[0:1]
	v_lshl_add_u64 v[68:69], v[68:69], 0, v[162:163]
	v_lshl_add_u64 v[66:67], s[42:43], 0, v[66:67]
	global_load_dwordx4 v[98:101], v[70:71], off offset:256 nt
	global_load_dwordx4 v[102:105], v[70:71], off nt
	global_load_dwordx4 v[106:109], v[68:69], off offset:256 nt
	global_load_dwordx4 v[110:113], v[68:69], off nt
	v_lshl_add_u64 v[68:69], v[66:67], 0, v[0:1]
	v_lshl_add_u64 v[66:67], v[66:67], 0, v[162:163]
	global_load_dwordx4 v[114:117], v[68:69], off offset:256 nt
	global_load_dwordx4 v[122:125], v[68:69], off nt
	global_load_dwordx4 v[118:121], v[66:67], off offset:256 nt
	global_load_dwordx4 v[126:129], v[66:67], off nt
	s_and_b64 vcc, exec, s[0:1]
	v_readlane_b32 s37, v253, 17
	v_readlane_b32 s38, v253, 18
	v_readlane_b32 s39, v253, 19
	v_readlane_b32 s44, v253, 24
	v_readlane_b32 s45, v253, 25
	v_readlane_b32 s46, v253, 26
	v_readlane_b32 s47, v253, 27
	v_readlane_b32 s48, v253, 28
	v_readlane_b32 s49, v253, 29
	v_readlane_b32 s50, v253, 30
	v_readlane_b32 s51, v253, 31
	s_waitcnt lgkmcnt(0)
	s_barrier
	s_cbranch_vccnz .LBB0_851
	v_add_u32_e32 v78, s96, v135
	v_add_u32_e32 v66, 0x11100, v78
	v_add_u32_e32 v67, 0x11180, v78
	v_add_u32_e32 v70, 0x11120, v78
	v_add_u32_e32 v74, 0x11140, v78
	ds_read_b128 v[82:85], v66
	ds_read_b128 v[66:69], v67
	ds_read_b128 v[86:89], v70
	ds_read_b128 v[90:93], v74
	v_add_u32_e32 v70, 0x111a0, v78
	v_add_u32_e32 v74, 0x111c0, v78
	v_add_u32_e32 v79, 0x11160, v78
	v_add_u32_e32 v78, 0x111e0, v78
	v_add_u32_e32 v163, s33, v181
	ds_read_b128 v[94:97], v79
	ds_read_b128 v[78:81], v78
	ds_read_b128 v[204:207], v163
	v_add_u32_e32 v163, 0, v181
	ds_read_b128 v[70:73], v70
	ds_read_b128 v[74:77], v74
	ds_read_b128 v[212:215], v163 offset:16384
	ds_read_b128 v[216:219], v163 offset:24576
	s_waitcnt lgkmcnt(1)
	v_mfma_f32_32x32x16_bf16 v[82:97], v[212:215], v[204:207], v[82:97]
	v_add_u32_e32 v163, s33, v182
	s_waitcnt lgkmcnt(0)
	v_mfma_f32_32x32x16_bf16 v[66:81], v[216:219], v[204:207], v[66:81]
	ds_read_b128 v[204:207], v163
	v_add_u32_e32 v163, 0, v182
	ds_read_b128 v[212:215], v163 offset:16384
	ds_read_b128 v[216:219], v163 offset:24576
	v_add_u32_e32 v163, s33, v184
	s_waitcnt lgkmcnt(1)
	v_mfma_f32_32x32x16_bf16 v[82:97], v[212:215], v[204:207], v[82:97]
	s_waitcnt lgkmcnt(0)
	v_mfma_f32_32x32x16_bf16 v[66:81], v[216:219], v[204:207], v[66:81]
	ds_read_b128 v[204:207], v163
	v_add_u32_e32 v163, 0, v184
	ds_read_b128 v[212:215], v163 offset:16384
	ds_read_b128 v[216:219], v163 offset:24576
	v_add_u32_e32 v163, s33, v185
	s_waitcnt lgkmcnt(1)
	v_mfma_f32_32x32x16_bf16 v[82:97], v[212:215], v[204:207], v[82:97]
	s_waitcnt lgkmcnt(0)
	v_mfma_f32_32x32x16_bf16 v[66:81], v[216:219], v[204:207], v[66:81]
	ds_read_b128 v[204:207], v163
	v_add_u32_e32 v163, 0, v185
	ds_read_b128 v[212:215], v163 offset:16384
	ds_read_b128 v[216:219], v163 offset:24576
	v_add_u32_e32 v163, s33, v186
	s_waitcnt lgkmcnt(1)
	v_mfma_f32_32x32x16_bf16 v[82:97], v[212:215], v[204:207], v[82:97]
	s_waitcnt lgkmcnt(0)
	v_mfma_f32_32x32x16_bf16 v[66:81], v[216:219], v[204:207], v[66:81]
	ds_read_b128 v[204:207], v163
	v_add_u32_e32 v163, 0, v186
	ds_read_b128 v[212:215], v163 offset:16384
	ds_read_b128 v[216:219], v163 offset:24576
	v_add_u32_e32 v163, s33, v187
	s_waitcnt lgkmcnt(1)
	v_mfma_f32_32x32x16_bf16 v[82:97], v[212:215], v[204:207], v[82:97]
	s_waitcnt lgkmcnt(0)
; __device__ __forceinline__ int crow(int r, int hi) { return (r & 3) + 8 * (r >> 2) + 4 * hi; }
; template <int MODE, bool SAMPLE>
; __device__ __forceinline__ void attn_unit(const Params& p, char* lds, int b, int h, int qb) {
;     ...
;                 qkt(p0, p1, Kt, Qs, r32, hi);
;                 if (j == jd) {
; #pragma unroll
;                     for (int r = 0; r < 16; ++r) { const int kp = j * 64 + crow(r, hi); if (kp > qpos) p0[r] = -1e30f; if (kp + 32 > qpos) p1[r] = -1e30f; } }
;                 float pmax = p0[0];
; #pragma unroll
;                 for (int r = 1; r < 16; ++r) pmax = fmaxf(pmax, p0[r]);
; #pragma unroll
;                 for (int r = 0; r < 16; ++r) pmax = fmaxf(pmax, p1[r]);
;                 { auto rr = __builtin_amdgcn_permlane32_swap(__float_as_uint(pmax), __float_as_uint(pmax), false, false); pmax = fmaxf(__uint_as_float(rr[0]), __uint_as_float(rr[1])); }
;                 float alpha = 1.f;
;                 if (!__all(pmax - m_reg <= 8.f)) { const float mn = fmaxf(m_reg, pmax); alpha = __builtin_amdgcn_exp2f(m_reg - mn); m_reg = mn; }
;                 float ps = 0.f;
; #pragma unroll
;                 for (int r = 0; r < 16; ++r) { p0[r] = __builtin_amdgcn_exp2f(p0[r] - m_reg); p1[r] = __builtin_amdgcn_exp2f(p1[r] - m_reg); ps += p0[r] + p1[r]; }
;                 { auto rr = __builtin_amdgcn_permlane32_swap(__float_as_uint(ps), __float_as_uint(ps), false, false); ps = __uint_as_float(rr[0]) + __uint_as_float(rr[1]); }
;                 l_reg = l_reg * alpha + ps;
;                 if (__any(alpha < 1.f)) { if (hi == 0) wsc[r32] = alpha; asm volatile("s_waitcnt lgkmcnt(0)" ::: "memory");
; #pragma unroll
;                     for (int d = 0; d < 4; ++d)
; #pragma unroll
;                         for (int r = 0; r < 16; ++r) o[d][r] *= wsc[crow(r, hi)]; }
	v_mfma_f32_32x32x16_bf16 v[66:81], v[216:219], v[204:207], v[66:81]
	ds_read_b128 v[204:207], v163
	v_add_u32_e32 v163, 0, v187
	ds_read_b128 v[212:215], v163 offset:16384
	ds_read_b128 v[216:219], v163 offset:24576
	v_add_u32_e32 v163, s33, v188
	s_waitcnt lgkmcnt(1)
	v_mfma_f32_32x32x16_bf16 v[82:97], v[212:215], v[204:207], v[82:97]
	s_waitcnt lgkmcnt(0)
	v_mfma_f32_32x32x16_bf16 v[66:81], v[216:219], v[204:207], v[66:81]
	ds_read_b128 v[204:207], v163
	v_add_u32_e32 v163, 0, v188
	ds_read_b128 v[212:215], v163 offset:16384
	ds_read_b128 v[216:219], v163 offset:24576
	v_add_u32_e32 v163, s33, v189
	s_waitcnt lgkmcnt(1)
	v_mfma_f32_32x32x16_bf16 v[82:97], v[212:215], v[204:207], v[82:97]
	s_waitcnt lgkmcnt(0)
	v_mfma_f32_32x32x16_bf16 v[66:81], v[216:219], v[204:207], v[66:81]
	ds_read_b128 v[204:207], v163
	v_add_u32_e32 v163, 0, v189
	ds_read_b128 v[212:215], v163 offset:16384
	ds_read_b128 v[216:219], v163 offset:24576
	s_waitcnt lgkmcnt(1)
	v_mfma_f32_32x32x16_bf16 v[82:97], v[212:215], v[204:207], v[82:97]
	s_waitcnt lgkmcnt(0)
	v_mfma_f32_32x32x16_bf16 v[66:81], v[216:219], v[204:207], v[66:81]
	s_nop 9
	v_max_f32_e32 v163, v83, v83
	v_max_f32_e32 v203, v82, v82
	v_max_f32_e32 v163, v203, v163
	v_max3_f32 v163, v163, v84, v85
	v_max3_f32 v163, v163, v86, v87
	v_max3_f32 v163, v163, v88, v89
	v_max3_f32 v163, v163, v90, v91
	v_max3_f32 v163, v163, v92, v93
	v_max3_f32 v163, v163, v94, v95
	v_max3_f32 v163, v163, v96, v97
	v_max3_f32 v163, v163, v66, v67
	v_max3_f32 v163, v163, v68, v69
	v_max3_f32 v163, v163, v70, v71
	v_max3_f32 v163, v163, v72, v73
	v_max3_f32 v163, v163, v74, v75
	v_max3_f32 v163, v163, v76, v77
	v_max3_f32 v163, v163, v78, v79
	v_max3_f32 v163, v163, v80, v81
	v_mov_b32_e32 v203, v163
	s_nop 1
	v_permlane32_swap_b32_e32 v163, v203
	v_max_f32_e32 v203, v203, v203
	v_max_f32_e32 v163, v163, v163
	v_max_f32_e32 v163, v163, v203
	v_sub_f32_e32 v203, v163, v161
	v_cmp_ge_f32_e32 vcc, s82, v203
	s_cmp_eq_u64 vcc, exec
	v_max_f32_e32 v203, v161, v161
	s_cselect_b64 vcc, -1, 0
	v_max_f32_e32 v163, v203, v163
	v_sub_f32_e32 v203, v161, v163
	v_cndmask_b32_e32 v161, v163, v161, vcc
	v_sub_f32_e32 v82, v82, v161
	v_sub_f32_e32 v66, v66, v161
	v_exp_f32_e32 v163, v82
	v_exp_f32_e32 v82, v66
	v_exp_f32_e32 v204, v203
	v_sub_f32_e32 v67, v67, v161
	v_sub_f32_e32 v68, v68, v161
	v_add_f32_e32 v66, v163, v82
	v_add_f32_e32 v203, 0, v66
	v_sub_f32_e32 v66, v83, v161
	v_exp_f32_e32 v66, v66
	v_exp_f32_e32 v83, v67
	v_sub_f32_e32 v69, v69, v161
	v_sub_f32_e32 v70, v70, v161
	v_exp_f32_e32 v70, v70
	v_add_f32_e32 v67, v66, v83
	v_add_f32_e32 v203, v67, v203
	v_sub_f32_e32 v67, v84, v161
	v_exp_f32_e32 v67, v67
	v_exp_f32_e32 v84, v68
	v_sub_f32_e32 v71, v71, v161
	v_exp_f32_e32 v71, v71
	v_sub_f32_e32 v72, v72, v161
	v_add_f32_e32 v68, v67, v84
	v_add_f32_e32 v203, v68, v203
	v_sub_f32_e32 v68, v85, v161
	v_exp_f32_e32 v68, v68
	v_exp_f32_e32 v85, v69
	v_exp_f32_e32 v72, v72
	v_sub_f32_e32 v73, v73, v161
	v_exp_f32_e32 v73, v73
	v_add_f32_e32 v69, v68, v85
	v_add_f32_e32 v203, v69, v203
	v_sub_f32_e32 v69, v86, v161
	v_exp_f32_e32 v69, v69
	v_sub_f32_e32 v74, v74, v161
	v_exp_f32_e32 v74, v74
	v_sub_f32_e32 v75, v75, v161
	v_add_f32_e32 v86, v69, v70
	v_add_f32_e32 v203, v86, v203
	v_sub_f32_e32 v86, v87, v161
	v_exp_f32_e32 v86, v86
	v_exp_f32_e32 v75, v75
	v_sub_f32_e32 v76, v76, v161
	v_exp_f32_e32 v76, v76
	v_add_f32_e32 v87, v86, v71
	v_add_f32_e32 v203, v87, v203
	v_sub_f32_e32 v87, v88, v161
	v_exp_f32_e32 v87, v87
	v_sub_f32_e32 v77, v77, v161
	v_exp_f32_e32 v77, v77
	v_sub_f32_e32 v78, v78, v161
	v_add_f32_e32 v88, v87, v72
	v_add_f32_e32 v203, v88, v203
	v_sub_f32_e32 v88, v89, v161
	v_exp_f32_e32 v88, v88
	v_exp_f32_e32 v78, v78
	v_sub_f32_e32 v79, v79, v161
	v_exp_f32_e32 v79, v79
	v_add_f32_e32 v89, v88, v73
	v_add_f32_e32 v203, v89, v203
	v_sub_f32_e32 v89, v90, v161
	v_exp_f32_e32 v89, v89
	v_sub_f32_e32 v80, v80, v161
	v_exp_f32_e32 v80, v80
	v_sub_f32_e32 v81, v81, v161
	v_add_f32_e32 v90, v89, v74
	v_add_f32_e32 v203, v90, v203
	v_sub_f32_e32 v90, v91, v161
	v_exp_f32_e32 v90, v90
	v_exp_f32_e32 v81, v81
	v_add_f32_e32 v91, v90, v75
	v_add_f32_e32 v203, v91, v203
	v_sub_f32_e32 v91, v92, v161
	v_exp_f32_e32 v91, v91
	s_nop 0
	v_add_f32_e32 v92, v91, v76
	v_add_f32_e32 v203, v92, v203
	v_sub_f32_e32 v92, v93, v161
	v_exp_f32_e32 v92, v92
	s_nop 0
	v_add_f32_e32 v93, v92, v77
	v_add_f32_e32 v203, v93, v203
	v_sub_f32_e32 v93, v94, v161
	v_exp_f32_e32 v93, v93
	s_nop 0
	v_add_f32_e32 v94, v93, v78
	v_add_f32_e32 v203, v94, v203
	v_sub_f32_e32 v94, v95, v161
	v_exp_f32_e32 v94, v94
	s_nop 0
	v_add_f32_e32 v95, v94, v79
	v_add_f32_e32 v203, v95, v203
	v_sub_f32_e32 v95, v96, v161
	v_exp_f32_e32 v95, v95
	s_nop 0
	v_add_f32_e32 v96, v95, v80
	v_add_f32_e32 v203, v96, v203
	v_sub_f32_e32 v96, v97, v161
	v_exp_f32_e32 v96, v96
	s_nop 0
	v_add_f32_e32 v97, v96, v81
	v_add_f32_e32 v203, v97, v203
	v_cndmask_b32_e64 v97, v204, 1.0, vcc
	v_mov_b32_e32 v204, v203
	s_nop 1
	v_permlane32_swap_b32_e32 v203, v204
	v_cmp_gt_f32_e32 vcc, 1.0, v97
	s_cbranch_vccz .LBB0_850
	s_and_saveexec_b64 s[2:3], s[12:13]
	ds_write_b32 v147, v97
	s_or_b64 exec, exec, s[2:3]
	s_waitcnt lgkmcnt(0)
	ds_read_b128 v[206:209], v149 offset:96
	ds_read_b128 v[212:215], v149 offset:64
	ds_read_b128 v[216:219], v149 offset:32
	ds_read_b128 v[220:223], v149
	s_waitcnt lgkmcnt(3)
	v_pk_mul_f32 v[64:65], v[64:65], v[208:209]
	s_waitcnt lgkmcnt(2)
	v_pk_mul_f32 v[60:61], v[60:61], v[214:215]
	s_waitcnt lgkmcnt(1)
	v_pk_mul_f32 v[56:57], v[56:57], v[218:219]
	s_waitcnt lgkmcnt(0)
	v_pk_mul_f32 v[52:53], v[52:53], v[222:223]
	v_pk_mul_f32 v[62:63], v[62:63], v[206:207]
	v_pk_mul_f32 v[58:59], v[58:59], v[212:213]
	v_pk_mul_f32 v[54:55], v[54:55], v[216:217]
	v_pk_mul_f32 v[50:51], v[50:51], v[220:221]
	v_pk_mul_f32 v[48:49], v[48:49], v[208:209]
	v_pk_mul_f32 v[44:45], v[44:45], v[214:215]
	v_pk_mul_f32 v[40:41], v[40:41], v[218:219]
	v_pk_mul_f32 v[36:37], v[36:37], v[222:223]
	v_pk_mul_f32 v[46:47], v[46:47], v[206:207]
	v_pk_mul_f32 v[42:43], v[42:43], v[212:213]
	v_pk_mul_f32 v[38:39], v[38:39], v[216:217]
	v_pk_mul_f32 v[34:35], v[34:35], v[220:221]
	v_pk_mul_f32 v[32:33], v[32:33], v[208:209]
	v_pk_mul_f32 v[28:29], v[28:29], v[214:215]
	v_pk_mul_f32 v[24:25], v[24:25], v[218:219]
	v_pk_mul_f32 v[20:21], v[20:21], v[222:223]
	v_pk_mul_f32 v[30:31], v[30:31], v[206:207]
	v_pk_mul_f32 v[26:27], v[26:27], v[212:213]
	v_pk_mul_f32 v[22:23], v[22:23], v[216:217]
	v_pk_mul_f32 v[18:19], v[18:19], v[220:221]
	v_pk_mul_f32 v[16:17], v[16:17], v[208:209]
	v_pk_mul_f32 v[12:13], v[12:13], v[214:215]
	v_pk_mul_f32 v[8:9], v[8:9], v[218:219]
	v_pk_mul_f32 v[4:5], v[4:5], v[222:223]
	v_pk_mul_f32 v[14:15], v[14:15], v[206:207]
	v_pk_mul_f32 v[10:11], v[10:11], v[212:213]
	v_pk_mul_f32 v[6:7], v[6:7], v[216:217]
	v_pk_mul_f32 v[2:3], v[2:3], v[220:221]

; template <int MODE, bool SAMPLE>
; __device__ __forceinline__ void attn_unit(const Params& p, char* lds, int b, int h, int qb) {
;     ...
;         WRITET(buf, stg2[NS == 2 ? par : 0]);
;         if (j >= NS) LOADT(j - NS, stg2[NS == 2 ? par : 0]);
;         __syncthreads();
.LBB0_851:
	v_and_b32_e32 v76, 15, v183
	v_bfe_u32 v77, v183, 4, 3
	v_xor_b32_e32 v78, v76, v77
	v_lshrrev_b32_e32 v74, 1, v76
	v_xor_b32_e32 v74, v74, v77
	v_sub_u32_e32 v74, v74, v78
	v_and_b32_e32 v78, 1, v76
	v_lshlrev_b32_e32 v74, 4, v74
	v_lshl_add_u32 v74, v78, 3, v74
	v_lshrrev_b32_e32 v75, 3, v76
	v_lshrrev_b32_e32 v78, 2, v76
	v_sub_u32_e32 v75, v75, v78
	v_lshlrev_b32_e32 v75, 9, v75
	v_and_b32_e32 v78, 7, v76
	v_lshl_add_u32 v75, v78, 3, v75
	v_and_b32_e32 v78, 3, v76
	v_lshlrev_b32_e32 v78, 4, v78
	v_sub_u32_e32 v75, v75, v78
	v_add_u32_e32 v70, v198, v74
	v_add_u32_e32 v71, v199, v74
	v_add_u32_e32 v72, v200, v75
	v_add_u32_e32 v73, v201, v75
	s_waitcnt vmcnt(6)
	v_cvt_pk_bf16_f32 v66, v102, v103
	v_cvt_pk_bf16_f32 v67, v104, v105
	v_cvt_pk_bf16_f32 v68, v98, v99
	v_cvt_pk_bf16_f32 v69, v100, v101
	ds_write_b64 v70, v[66:67]
	ds_write_b64 v70, v[68:69] offset:128
	s_waitcnt vmcnt(4)
	v_cvt_pk_bf16_f32 v66, v110, v111
	v_cvt_pk_bf16_f32 v67, v112, v113
	v_cvt_pk_bf16_f32 v68, v106, v107
	v_cvt_pk_bf16_f32 v69, v108, v109
	ds_write_b64 v71, v[66:67]
	ds_write_b64 v71, v[68:69] offset:128
	s_waitcnt vmcnt(2)
	v_cvt_pk_bf16_f32 v66, v122, v123
	v_cvt_pk_bf16_f32 v67, v124, v125
	v_cvt_pk_bf16_f32 v68, v114, v115
	v_cvt_pk_bf16_f32 v69, v116, v117
	s_cmpk_eq_i32 s96, 0xf000
	ds_write_b64 v72, v[66:67] offset:32768
	ds_write_b64 v72, v[68:69] offset:33792
	s_waitcnt vmcnt(0)
	v_cvt_pk_bf16_f32 v66, v126, v127
	v_cvt_pk_bf16_f32 v67, v128, v129
	v_cvt_pk_bf16_f32 v68, v118, v119
	v_cvt_pk_bf16_f32 v69, v120, v121
	ds_write_b64 v73, v[66:67] offset:32768
	ds_write_b64 v73, v[68:69] offset:33792
.Lfsr_join_f2:
	s_cbranch_scc1 .LBB0_853
	s_lshl_b64 s[2:3], s[52:53], 10
	v_lshl_add_u64 v[66:67], s[2:3], 0, v[166:167]
	v_readlane_b32 s36, v253, 16
	v_lshlrev_b64 v[66:67], 2, v[66:67]
	v_and_b32_e32 v72, 15, v183
	v_lshlrev_b32_e32 v72, 4, v72
	v_sub_u32_e32 v66, v66, v72
	v_readlane_b32 s40, v253, 20
	v_readlane_b32 s41, v253, 21
	v_readlane_b32 s42, v253, 22
	v_readlane_b32 s43, v253, 23
	v_lshl_add_u64 v[68:69], s[40:41], 0, v[66:67]
	v_mov_b32_e32 v163, v1
	v_lshl_add_u64 v[70:71], v[68:69], 0, v[0:1]
	v_lshl_add_u64 v[68:69], v[68:69], 0, v[162:163]
	v_lshl_add_u64 v[66:67], s[42:43], 0, v[66:67]
	global_load_dwordx4 v[98:101], v[70:71], off offset:256 nt
	global_load_dwordx4 v[102:105], v[70:71], off nt
	global_load_dwordx4 v[106:109], v[68:69], off offset:256 nt
	global_load_dwordx4 v[110:113], v[68:69], off nt
	v_lshl_add_u64 v[68:69], v[66:67], 0, v[0:1]
	v_lshl_add_u64 v[66:67], v[66:67], 0, v[162:163]
	global_load_dwordx4 v[114:117], v[68:69], off offset:256 nt
	global_load_dwordx4 v[122:125], v[68:69], off nt
	global_load_dwordx4 v[118:121], v[66:67], off offset:256 nt
	global_load_dwordx4 v[126:129], v[66:67], off nt
	v_readlane_b32 s37, v253, 17
	v_readlane_b32 s38, v253, 18
	v_readlane_b32 s39, v253, 19
	v_readlane_b32 s44, v253, 24
	v_readlane_b32 s45, v253, 25
	v_readlane_b32 s46, v253, 26
	v_readlane_b32 s47, v253, 27
	v_readlane_b32 s48, v253, 28
	v_readlane_b32 s49, v253, 29
	v_readlane_b32 s50, v253, 30
	v_readlane_b32 s51, v253, 31

.Lfsr_first_s2:
	s_waitcnt vmcnt(6)
	v_cvt_pk_bf16_f32 v66, v102, v103
	v_cvt_pk_bf16_f32 v67, v104, v105
	s_waitcnt vmcnt(6)
	v_cvt_pk_bf16_f32 v68, v98, v99
	v_cvt_pk_bf16_f32 v69, v100, v101
	ds_write_b128 v198, v[66:69]
	s_waitcnt vmcnt(4)
	v_cvt_pk_bf16_f32 v66, v110, v111
	v_cvt_pk_bf16_f32 v67, v112, v113
	s_waitcnt vmcnt(4)
	v_cvt_pk_bf16_f32 v68, v106, v107
	v_cvt_pk_bf16_f32 v69, v108, v109
	ds_write_b128 v199, v[66:69]
	s_waitcnt vmcnt(2)
	v_cvt_pk_bf16_f32 v66, v118, v119
	v_cvt_pk_bf16_f32 v67, v120, v121
	s_waitcnt vmcnt(2)
	v_cvt_pk_bf16_f32 v68, v114, v115
	v_cvt_pk_bf16_f32 v69, v116, v117
	s_cmp_eq_u32 s64, 0xffc00000
	ds_write_b128 v200, v[66:69] offset:32768
	s_waitcnt vmcnt(0)
	v_cvt_pk_bf16_f32 v66, v126, v127
	v_cvt_pk_bf16_f32 v67, v128, v129
	s_waitcnt vmcnt(0)
	v_cvt_pk_bf16_f32 v68, v122, v123
	v_cvt_pk_bf16_f32 v69, v124, v125
	ds_write_b128 v201, v[66:69] offset:32768
	s_branch .Lfsr_join_s2

; template <int MODE, bool SAMPLE>
; __device__ __forceinline__ void attn_unit(const Params& p, char* lds, int b, int h, int qb) {
;     ...
;             } else {
;                 p0 = f32x16{}; p1 = f32x16{};
;                 qkt(p0, p1, Kt, Qs, r32, hi);
.LBB0_868:
	v_cndmask_b32_e64 v66, 0, 1, s[72:73]
	s_cmp_lt_u32 s3, 8
	v_cmp_ne_u32_e64 s[0:1], 1, v66
	s_cbranch_scc0 .Lfsr_first_s2
	v_and_b32_e32 v76, 15, v183
	v_bfe_u32 v77, v183, 4, 3
	v_xor_b32_e32 v78, v76, v77
	v_lshrrev_b32_e32 v74, 1, v76
	v_xor_b32_e32 v74, v74, v77
	v_sub_u32_e32 v74, v74, v78
	v_and_b32_e32 v78, 1, v76
	v_lshlrev_b32_e32 v74, 4, v74
	v_lshl_add_u32 v74, v78, 3, v74
	v_lshrrev_b32_e32 v75, 3, v76
	v_lshrrev_b32_e32 v78, 2, v76
	v_sub_u32_e32 v75, v75, v78
	v_lshlrev_b32_e32 v75, 9, v75
	v_and_b32_e32 v78, 7, v76
	v_lshl_add_u32 v75, v78, 3, v75
	v_and_b32_e32 v78, 3, v76
	v_lshlrev_b32_e32 v78, 4, v78
	v_sub_u32_e32 v75, v75, v78
	v_add_u32_e32 v70, v198, v74
	v_add_u32_e32 v71, v199, v74
	v_add_u32_e32 v72, v200, v75
	v_add_u32_e32 v73, v201, v75
	s_waitcnt vmcnt(6)
	v_cvt_pk_bf16_f32 v66, v102, v103
	v_cvt_pk_bf16_f32 v67, v104, v105
	v_cvt_pk_bf16_f32 v68, v98, v99
	v_cvt_pk_bf16_f32 v69, v100, v101
	ds_write_b64 v70, v[66:67] offset:16384
	ds_write_b64 v70, v[68:69] offset:16512
	s_waitcnt vmcnt(4)
	v_cvt_pk_bf16_f32 v66, v110, v111
	v_cvt_pk_bf16_f32 v67, v112, v113
	v_cvt_pk_bf16_f32 v68, v106, v107
	v_cvt_pk_bf16_f32 v69, v108, v109
	ds_write_b64 v71, v[66:67] offset:16384
	ds_write_b64 v71, v[68:69] offset:16512
	s_waitcnt vmcnt(2)
	v_cvt_pk_bf16_f32 v66, v118, v119
	v_cvt_pk_bf16_f32 v67, v120, v121
	v_cvt_pk_bf16_f32 v68, v114, v115
	v_cvt_pk_bf16_f32 v69, v116, v117
	ds_write_b64 v72, v[66:67] offset:49152
	ds_write_b64 v72, v[68:69] offset:50176
	s_waitcnt vmcnt(0)
	v_cvt_pk_bf16_f32 v66, v126, v127
	v_cvt_pk_bf16_f32 v67, v128, v129
	v_cvt_pk_bf16_f32 v68, v122, v123
	v_cvt_pk_bf16_f32 v69, v124, v125
	ds_write_b64 v73, v[66:67] offset:49152
	ds_write_b64 v73, v[68:69] offset:50176
	v_lshl_add_u64 v[66:67], v[166:167], 0, s[64:65]
	v_and_b32_e32 v72, 15, v183
	v_lshlrev_b32_e32 v72, 4, v72
	v_sub_co_u32_e32 v66, vcc, v66, v72
	s_nop 1
	v_subbrev_co_u32_e32 v67, vcc, 0, v67, vcc
	v_add_co_u32_e32 v70, vcc, s83, v66
	v_lshl_add_u64 v[68:69], v[66:67], 0, s[56:57]
	s_nop 0
	v_addc_co_u32_e32 v71, vcc, 0, v67, vcc
	s_mov_b32 s6, 0x420000
	global_load_dwordx4 v[102:105], v[70:71], off nt
	global_load_dwordx4 v[98:101], v[68:69], off offset:256 nt
	v_lshl_add_u64 v[68:69], v[66:67], 0, s[58:59]
	v_add_co_u32_e32 v66, vcc, s6, v66
	s_nop 1
	v_addc_co_u32_e32 v67, vcc, 0, v67, vcc
	global_load_dwordx4 v[110:113], v[66:67], off nt
	global_load_dwordx4 v[106:109], v[68:69], off offset:256 nt
	v_lshl_add_u64 v[66:67], v[168:169], 0, s[64:65]
	v_and_b32_e32 v72, 15, v183
	v_lshlrev_b32_e32 v72, 4, v72
	v_sub_co_u32_e32 v66, vcc, v66, v72
	s_nop 1
	v_subbrev_co_u32_e32 v67, vcc, 0, v67, vcc
	v_add_co_u32_e32 v70, vcc, s83, v66
	v_lshl_add_u64 v[68:69], v[66:67], 0, s[56:57]
	s_nop 0
	v_addc_co_u32_e32 v71, vcc, 0, v67, vcc
	global_load_dwordx4 v[118:121], v[70:71], off nt
	global_load_dwordx4 v[114:117], v[68:69], off offset:256 nt
	v_lshl_add_u64 v[68:69], v[66:67], 0, s[58:59]
	v_add_co_u32_e32 v66, vcc, 0x420000, v66
	s_nop 1
	v_addc_co_u32_e32 v67, vcc, 0, v67, vcc
	global_load_dwordx4 v[126:129], v[66:67], off nt
	global_load_dwordx4 v[122:125], v[68:69], off offset:256 nt
	s_and_b64 vcc, exec, s[0:1]
	s_waitcnt lgkmcnt(0)
	s_barrier
	s_cbranch_vccnz .LBB0_871
	ds_read_b128 v[66:69], v203 offset:16384
	v_add_u32_e32 v70, s2, v181
	ds_read_b128 v[70:73], v70
	ds_read_b128 v[74:77], v203 offset:24576
	v_add_u32_e32 v78, s2, v182
	ds_read_b128 v[212:215], v78
	ds_read_b128 v[216:219], v204 offset:16384
	ds_read_b128 v[220:223], v204 offset:24576
	v_add_u32_e32 v149, s2, v184
	s_waitcnt lgkmcnt(4)
	v_mfma_f32_32x32x16_bf16 v[82:97], v[66:69], v[70:73], 0
	s_waitcnt lgkmcnt(3)
	v_mfma_f32_32x32x16_bf16 v[66:81], v[74:77], v[70:73], 0
	s_waitcnt lgkmcnt(1)
	v_mfma_f32_32x32x16_bf16 v[82:97], v[216:219], v[212:215], v[82:97]
	s_waitcnt lgkmcnt(0)
	v_mfma_f32_32x32x16_bf16 v[66:81], v[220:223], v[212:215], v[66:81]
	ds_read_b128 v[212:215], v205 offset:16384
	ds_read_b128 v[216:219], v149
	ds_read_b128 v[220:223], v205 offset:24576
	v_add_u32_e32 v149, s2, v185
	ds_read_b128 v[224:227], v149
	v_add_u32_e32 v149, s2, v186
	s_waitcnt lgkmcnt(2)
	v_mfma_f32_32x32x16_bf16 v[82:97], v[212:215], v[216:219], v[82:97]
	s_waitcnt lgkmcnt(1)
	v_mfma_f32_32x32x16_bf16 v[66:81], v[220:223], v[216:219], v[66:81]
	ds_read_b128 v[212:215], v206 offset:16384
	ds_read_b128 v[216:219], v206 offset:24576
	s_waitcnt lgkmcnt(1)
	v_mfma_f32_32x32x16_bf16 v[82:97], v[212:215], v[224:227], v[82:97]
	ds_read_b128 v[212:215], v207 offset:16384
	s_waitcnt lgkmcnt(1)
	v_mfma_f32_32x32x16_bf16 v[66:81], v[216:219], v[224:227], v[66:81]
	ds_read_b128 v[216:219], v149
	ds_read_b128 v[220:223], v207 offset:24576
	v_add_u32_e32 v149, s2, v187
	ds_read_b128 v[224:227], v149
	v_add_u32_e32 v149, s2, v188
	s_waitcnt lgkmcnt(1)
	v_mfma_f32_32x32x16_bf16 v[66:81], v[220:223], v[216:219], v[66:81]
	v_mfma_f32_32x32x16_bf16 v[82:97], v[212:215], v[216:219], v[82:97]
	ds_read_b128 v[212:215], v208 offset:16384
	ds_read_b128 v[216:219], v208 offset:24576
	s_waitcnt lgkmcnt(0)
	v_mfma_f32_32x32x16_bf16 v[66:81], v[216:219], v[224:227], v[66:81]
	v_mfma_f32_32x32x16_bf16 v[82:97], v[212:215], v[224:227], v[82:97]
	ds_read_b128 v[212:215], v209 offset:16384
	ds_read_b128 v[216:219], v149
	ds_read_b128 v[220:223], v209 offset:24576
	v_add_u32_e32 v149, s2, v189
	ds_read_b128 v[224:227], v149
	s_waitcnt lgkmcnt(1)
	v_mfma_f32_32x32x16_bf16 v[66:81], v[220:223], v[216:219], v[66:81]
	v_mfma_f32_32x32x16_bf16 v[82:97], v[212:215], v[216:219], v[82:97]
	ds_read_b128 v[212:215], v210 offset:16384
	ds_read_b128 v[216:219], v210 offset:24576
	s_waitcnt lgkmcnt(0)
; __device__ __forceinline__ int crow(int r, int hi) { return (r & 3) + 8 * (r >> 2) + 4 * hi; }
; template <int MODE, bool SAMPLE>
; __device__ __forceinline__ void attn_unit(const Params& p, char* lds, int b, int h, int qb) {
;     ...
;                 if (j == jd) {
; #pragma unroll
;                     for (int r = 0; r < 16; ++r) { const int kp = j * 64 + crow(r, hi); if (kp >= qpos) p0[r] = -1e30f; if (kp + 32 >= qpos) p1[r] = -1e30f; } }
;                 f32x16 s0, s1;
; #pragma unroll
;                 for (int r = 0; r < 16; ++r) { p0[r] = __builtin_amdgcn_exp2f(fminf(p0[r], 100.f)); p1[r] = __builtin_amdgcn_exp2f(fminf(p1[r], 100.f));
;                     s0[r] = __builtin_amdgcn_rcpf(1.f + p0[r]); s1[r] = __builtin_amdgcn_rcpf(1.f + p1[r]); }
;                 float run = carry, bs[8];
; #pragma unroll
;                 for (int i = 7; i >= 0; --i) { const f32x16& S = (i >= 4) ? s1 : s0; const int rb = 4 * (i & 3);
;                     const float gs = (S[rb] * S[rb + 1]) * (S[rb + 2] * S[rb + 3]);
;                     auto rr = __builtin_amdgcn_permlane32_swap(__float_as_uint(gs), __float_as_uint(gs), false, false);
;                     const float glo = __uint_as_float(rr[0]), ghi = __uint_as_float(rr[1]);
;                     const float exH = run; run *= ghi; const float exL = run; run *= glo;
;                     bs[i] = hi ? exH : exL; }
;                 carry = run;
	v_mfma_f32_32x32x16_bf16 v[66:81], v[216:219], v[224:227], v[66:81]
	v_mfma_f32_32x32x16_bf16 v[82:97], v[212:215], v[224:227], v[82:97]
	s_nop 10
	v_max_f32_e32 v69, v69, v69
	v_min_f32_e32 v69, 0x42c80000, v69
	v_exp_f32_e32 v215, v69
	v_max_f32_e32 v81, v81, v81
	v_min_f32_e32 v81, 0x42c80000, v81
	v_max_f32_e32 v68, v68, v68
	v_max_f32_e32 v66, v66, v66
	v_max_f32_e32 v69, v86, v86
	v_min_f32_e32 v69, 0x42c80000, v69
	v_exp_f32_e32 v86, v69
	v_max_f32_e32 v69, v70, v70
	v_max_f32_e32 v70, v87, v87
	v_min_f32_e32 v70, 0x42c80000, v70
	v_exp_f32_e32 v87, v70
	v_max_f32_e32 v70, v71, v71
	v_max_f32_e32 v71, v88, v88
	v_min_f32_e32 v71, 0x42c80000, v71
	v_exp_f32_e32 v88, v71
	v_max_f32_e32 v71, v72, v72
	v_max_f32_e32 v72, v89, v89
	v_min_f32_e32 v72, 0x42c80000, v72
	v_exp_f32_e32 v89, v72
	v_max_f32_e32 v72, v73, v73
	v_max_f32_e32 v73, v90, v90
	v_min_f32_e32 v73, 0x42c80000, v73
	v_exp_f32_e32 v90, v73
	v_max_f32_e32 v73, v74, v74
	v_max_f32_e32 v74, v91, v91
	v_min_f32_e32 v74, 0x42c80000, v74
	v_exp_f32_e32 v91, v74
	v_max_f32_e32 v74, v75, v75
	v_max_f32_e32 v75, v92, v92
	v_min_f32_e32 v75, 0x42c80000, v75
	v_exp_f32_e32 v92, v75
	v_max_f32_e32 v75, v76, v76
	v_max_f32_e32 v76, v93, v93
	v_min_f32_e32 v76, 0x42c80000, v76
	v_exp_f32_e32 v93, v76
	v_max_f32_e32 v76, v77, v77
	v_max_f32_e32 v77, v94, v94
	v_min_f32_e32 v77, 0x42c80000, v77
	v_exp_f32_e32 v94, v77
	v_max_f32_e32 v77, v78, v78
	v_max_f32_e32 v78, v95, v95
	v_min_f32_e32 v78, 0x42c80000, v78
	v_exp_f32_e32 v95, v78
	v_max_f32_e32 v78, v79, v79
	v_max_f32_e32 v79, v96, v96
	v_min_f32_e32 v79, 0x42c80000, v79
	v_min_f32_e32 v77, 0x42c80000, v77
	v_exp_f32_e32 v96, v79
	v_max_f32_e32 v79, v80, v80
	v_exp_f32_e32 v233, v77
	v_min_f32_e32 v79, 0x42c80000, v79
	v_min_f32_e32 v78, 0x42c80000, v78
	v_exp_f32_e32 v237, v79
	v_exp_f32_e32 v235, v78
	v_max_f32_e32 v80, v97, v97
	v_exp_f32_e32 v97, v81
	v_min_f32_e32 v73, 0x42c80000, v73
	v_add_f32_e32 v77, 1.0, v233
	v_exp_f32_e32 v225, v73
	v_rcp_f32_e32 v236, v77
	v_add_f32_e32 v77, 1.0, v95
	v_add_f32_e32 v79, 1.0, v237
	v_min_f32_e32 v74, 0x42c80000, v74
	v_min_f32_e32 v75, 0x42c80000, v75
	v_min_f32_e32 v76, 0x42c80000, v76
	v_rcp_f32_e32 v78, v77
	v_add_f32_e32 v77, 1.0, v235
	v_rcp_f32_e32 v240, v79
	v_add_f32_e32 v79, 1.0, v97
	v_exp_f32_e32 v227, v74
	v_exp_f32_e32 v229, v75
	v_exp_f32_e32 v231, v76
	v_rcp_f32_e32 v238, v77
	v_rcp_f32_e32 v241, v79
	v_min_f32_e32 v69, 0x42c80000, v69
	v_add_f32_e32 v73, 1.0, v225
	v_max_f32_e32 v83, v83, v83
	v_exp_f32_e32 v217, v69
	v_rcp_f32_e32 v228, v73
	v_add_f32_e32 v73, 1.0, v91
	v_min_f32_e32 v80, 0x42c80000, v80
	v_min_f32_e32 v83, 0x42c80000, v83
	v_min_f32_e32 v70, 0x42c80000, v70
	v_min_f32_e32 v71, 0x42c80000, v71
	v_min_f32_e32 v72, 0x42c80000, v72
	v_rcp_f32_e32 v74, v73
	v_add_f32_e32 v73, 1.0, v227
	v_add_f32_e32 v75, 1.0, v229
	v_add_f32_e32 v76, 1.0, v231
	v_exp_f32_e32 v239, v80
	v_mul_f32_e32 v80, v236, v238
	v_mul_f32_e32 v81, v240, v241
	v_exp_f32_e32 v163, v83
	v_max_f32_e32 v83, v84, v84
	v_exp_f32_e32 v219, v70
	v_exp_f32_e32 v221, v71
	v_exp_f32_e32 v223, v72
	v_rcp_f32_e32 v230, v73
	v_rcp_f32_e32 v232, v75
	v_rcp_f32_e32 v234, v76
	v_mul_f32_e32 v80, v80, v81
	v_min_f32_e32 v83, 0x42c80000, v83
	v_mov_b32_e32 v81, v80
	v_exp_f32_e32 v84, v83
	v_min_f32_e32 v68, 0x42c80000, v68
	v_max_f32_e32 v83, v85, v85
	v_add_f32_e32 v69, 1.0, v217
	v_permlane32_swap_b32_e32 v80, v81
	v_min_f32_e32 v66, 0x42c80000, v66
	v_max_f32_e32 v67, v67, v67
	v_exp_f32_e32 v213, v68
	v_min_f32_e32 v83, 0x42c80000, v83
	v_rcp_f32_e32 v220, v69
	v_add_f32_e32 v69, 1.0, v87
	v_mul_f32_e32 v81, v147, v81
	v_exp_f32_e32 v161, v66
	v_min_f32_e32 v67, 0x42c80000, v67
	v_exp_f32_e32 v85, v83
	v_rcp_f32_e32 v70, v69
	v_add_f32_e32 v69, 1.0, v219
	v_add_f32_e32 v71, 1.0, v221
	v_add_f32_e32 v72, 1.0, v223
	v_mul_f32_e32 v80, v81, v80
	v_cndmask_b32_e64 v147, v147, v81, s[12:13]
	v_mul_f32_e32 v81, v228, v230
	v_mul_f32_e32 v242, v232, v234
	v_exp_f32_e32 v211, v67
	v_rcp_f32_e32 v222, v69
	v_rcp_f32_e32 v224, v71
	v_rcp_f32_e32 v226, v72
	v_mul_f32_e32 v81, v81, v242
	v_max_f32_e32 v82, v82, v82
	v_mov_b32_e32 v242, v81
	v_min_f32_e32 v82, 0x42c80000, v82
	v_add_f32_e32 v68, 1.0, v213
	v_permlane32_swap_b32_e32 v81, v242
	v_exp_f32_e32 v149, v82
	v_add_f32_e32 v82, 1.0, v161
	v_add_f32_e32 v67, 1.0, v163
	v_rcp_f32_e32 v216, v68
	v_add_f32_e32 v68, 1.0, v85
	v_mul_f32_e32 v242, v80, v242
	v_rcp_f32_e32 v212, v82
	v_rcp_f32_e32 v82, v67
	v_add_f32_e32 v67, 1.0, v211
	v_rcp_f32_e32 v83, v68
	v_add_f32_e32 v68, 1.0, v215
	v_mul_f32_e32 v81, v242, v81
	v_cndmask_b32_e64 v242, v80, v242, s[12:13]
	v_mul_f32_e32 v80, v220, v222
	v_mul_f32_e32 v243, v224, v226
	v_rcp_f32_e32 v214, v67
	v_rcp_f32_e32 v218, v68
	v_mul_f32_e32 v80, v80, v243
	v_mov_b32_e32 v243, v80
	s_nop 1
	v_permlane32_swap_b32_e32 v80, v243
	v_mul_f32_e32 v243, v81, v243
	v_add_f32_e32 v76, 1.0, v94
	v_add_f32_e32 v77, 1.0, v96
	v_add_f32_e32 v79, 1.0, v239
	v_mul_f32_e32 v80, v243, v80
	v_cndmask_b32_e64 v243, v81, v243, s[12:13]
	v_mul_f32_e32 v81, v212, v214
	v_mul_f32_e32 v244, v216, v218
	v_rcp_f32_e32 v76, v76
	v_rcp_f32_e32 v77, v77
	v_rcp_f32_e32 v79, v79
	v_mul_f32_e32 v81, v81, v244
	v_mov_b32_e32 v244, v81
	s_nop 1
	v_permlane32_swap_b32_e32 v81, v244
	v_mul_f32_e32 v244, v80, v244
	v_add_f32_e32 v72, 1.0, v90
	v_add_f32_e32 v73, 1.0, v92
	v_add_f32_e32 v75, 1.0, v93
	v_mul_f32_e32 v245, v244, v81
	v_cndmask_b32_e64 v244, v80, v244, s[12:13]
	v_pk_mul_f32 v[80:81], v[76:77], v[78:79]
	v_rcp_f32_e32 v72, v72
	v_rcp_f32_e32 v73, v73
	v_rcp_f32_e32 v75, v75
	v_pk_mul_f32 v[80:81], v[80:81], v[80:81] op_sel:[0,1] op_sel_hi:[1,0]
; #define SBAR() __builtin_amdgcn_sched_barrier(0)
; template <int OFF> __device__ __forceinline__ s16x4 tr_read(int vb) { s16x4 r; asm volatile("ds_read_b64_tr_b16 %0, %1 offset:%2" : "=&v"(r) : "v"(vb), "i"(OFF) : "memory"); return r; }
; template <int D0> __device__ __forceinline__ void pv_one(f32x16& od, int vb, bf16x8 pa0, bf16x8 pa1, bf16x8 pa2, bf16x8 pa3) {
;     const s16x4 l0 = tr_read<v_rd_off(D0, 0, 0)>(vb), h0 = tr_read<v_rd_off(D0, 0, 1)>(vb), l1 = tr_read<v_rd_off(D0, 1, 0)>(vb), h1 = tr_read<v_rd_off(D0, 1, 1)>(vb);
;     const s16x4 l2 = tr_read<v_rd_off(D0, 2, 0)>(vb), h2 = tr_read<v_rd_off(D0, 2, 1)>(vb), l3 = tr_read<v_rd_off(D0, 3, 0)>(vb), h3 = tr_read<v_rd_off(D0, 3, 1)>(vb);
;     asm volatile("s_waitcnt lgkmcnt(0)" ::: "memory"); SBAR();
;     ...
;     od = __builtin_amdgcn_mfma_f32_32x32x16_bf16(pa0, PKV(l0, h0), od, 0, 0, 0);
;     od = __builtin_amdgcn_mfma_f32_32x32x16_bf16(pa1, PKV(l1, h1), od, 0, 0, 0);
;     od = __builtin_amdgcn_mfma_f32_32x32x16_bf16(pa2, PKV(l2, h2), od, 0, 0, 0);
;     od = __builtin_amdgcn_mfma_f32_32x32x16_bf16(pa3, PKV(l3, h3), od, 0, 0, 0);
;     ...
; }
; __device__ __forceinline__ void pv_d0(f32x16* o, int vb, bf16x8 pa0, bf16x8 pa1, bf16x8 pa2, bf16x8 pa3) {
;     pv_one<0>(o[0], vb, pa0, pa1, pa2, pa3); pv_one<1>(o[1], vb, pa0, pa1, pa2, pa3); pv_one<2>(o[2], vb, pa0, pa1, pa2, pa3); pv_one<3>(o[3], vb, pa0, pa1, pa2, pa3);
; template <int MODE, bool SAMPLE>
; __device__ __forceinline__ void attn_unit(const Params& p, char* lds, int b, int h, int qb) {
;     ...
; #pragma unroll
;                 for (int i = 0; i < 8; ++i) { f32x16& S = (i >= 4) ? s1 : s0; f32x16& Z = (i >= 4) ? p1 : p0; const int rb = 4 * (i & 3);
;                     const float i3 = bs[i] * S[rb + 3], i2 = i3 * S[rb + 2], i1 = i2 * S[rb + 1], i0 = i1 * S[rb];
;                     Z[rb + 3] *= i3; Z[rb + 2] *= i2; Z[rb + 1] *= i1; Z[rb] *= i0; }
;             }
;             PK4(p0, 0, pa0); PK4(p0, 8, pa1); PK4(p1, 0, pa2); PK4(p1, 8, pa3);
;             pv_d0(o, vb, pa0, pa1, pa2, pa3);
	v_add_f32_e32 v68, 1.0, v86
	v_mov_b32_e32 v81, v80
	s_nop 1
	v_permlane32_swap_b32_e32 v80, v81
	v_mul_f32_e32 v81, v245, v81
	v_add_f32_e32 v69, 1.0, v88
	v_add_f32_e32 v71, 1.0, v89
	v_mul_f32_e32 v246, v81, v80
	v_cndmask_b32_e64 v245, v245, v81, s[12:13]
	v_pk_mul_f32 v[80:81], v[72:73], v[74:75]
	v_rcp_f32_e32 v68, v68
	v_rcp_f32_e32 v69, v69
	v_rcp_f32_e32 v71, v71
	v_pk_mul_f32 v[80:81], v[80:81], v[80:81] op_sel:[0,1] op_sel_hi:[1,0]
	v_add_f32_e32 v66, 1.0, v149
	v_mov_b32_e32 v81, v80
	s_nop 1
	v_permlane32_swap_b32_e32 v80, v81
	v_mul_f32_e32 v81, v246, v81
	v_add_f32_e32 v67, 1.0, v84
	v_mul_f32_e32 v247, v81, v80
	v_cndmask_b32_e64 v246, v246, v81, s[12:13]
	v_pk_mul_f32 v[80:81], v[68:69], v[70:71]
	v_rcp_f32_e32 v66, v66
	v_rcp_f32_e32 v67, v67
	v_pk_mul_f32 v[80:81], v[80:81], v[80:81] op_sel:[0,1] op_sel_hi:[1,0]
	v_mul_f32_e32 v75, v75, v246
	v_mov_b32_e32 v81, v80
	s_nop 1
	v_permlane32_swap_b32_e32 v80, v81
	v_mul_f32_e32 v81, v247, v81
	v_mul_f32_e32 v248, v81, v80
	v_cndmask_b32_e64 v247, v247, v81, s[12:13]
	v_pk_mul_f32 v[80:81], v[66:67], v[82:83]
	v_mul_f32_e32 v71, v71, v247
	v_pk_mul_f32 v[80:81], v[80:81], v[80:81] op_sel:[0,1] op_sel_hi:[1,0]
	v_mul_f32_e32 v69, v69, v71
	v_mov_b32_e32 v81, v80
	s_nop 1
	v_permlane32_swap_b32_e32 v80, v81
	v_mul_f32_e32 v81, v248, v81
	v_cndmask_b32_e64 v248, v248, v81, s[12:13]
	v_mul_f32_e32 v83, v83, v248
	v_mul_f32_e32 v67, v67, v83
	v_mul_f32_e32 v79, v79, v245
	v_mul_f32_e32 v82, v82, v67
	v_mul_f32_e32 v67, v84, v67
	v_mul_f32_e32 v70, v70, v69
	v_mul_f32_e32 v73, v73, v75
	v_mul_f32_e32 v77, v77, v79
	v_mul_f32_e32 v84, v218, v244
	v_mul_f32_e32 v83, v85, v83
	v_mul_f32_e32 v68, v68, v70
	v_mul_f32_e32 v69, v88, v69
	v_mul_f32_e32 v74, v74, v73
	v_mul_f32_e32 v73, v92, v73
	v_mul_f32_e32 v78, v78, v77
	v_mul_f32_e32 v77, v96, v77
	v_mul_f32_e32 v85, v216, v84
	v_mul_f32_e32 v88, v226, v243
	v_mul_f32_e32 v92, v234, v242
	v_mul_f32_e32 v96, v241, v147
	v_mul_f32_e32 v66, v66, v82
	v_mul_f32_e32 v71, v89, v71
	v_mul_f32_e32 v68, v86, v68
	v_mul_f32_e32 v72, v72, v74
	v_mul_f32_e32 v75, v93, v75
	v_mul_f32_e32 v76, v76, v78
	v_mul_f32_e32 v86, v214, v85
	v_mul_f32_e32 v89, v224, v88
	v_mul_f32_e32 v93, v232, v92
	v_mul_f32_e32 v147, v240, v96
	v_mul_f32_e32 v66, v149, v66
	v_mul_f32_e32 v70, v87, v70
	v_mul_f32_e32 v72, v90, v72
	v_mul_f32_e32 v76, v94, v76
	v_mul_f32_e32 v87, v212, v86
	v_mul_f32_e32 v90, v222, v89
	v_mul_f32_e32 v94, v230, v93
	v_mul_f32_e32 v149, v238, v147
	v_mul_f32_e32 v82, v163, v82
	v_mul_f32_e32 v74, v91, v74
	v_mul_f32_e32 v79, v239, v79
	v_mul_f32_e32 v78, v95, v78
	v_mul_f32_e32 v87, v161, v87
	v_mul_f32_e32 v91, v220, v90
	v_mul_f32_e32 v95, v228, v94
	v_mul_f32_e32 v161, v236, v149
	v_mul_f32_e32 v84, v215, v84
	v_mul_f32_e32 v85, v213, v85
	v_mul_f32_e32 v86, v211, v86
	v_mul_f32_e32 v88, v223, v88
	v_mul_f32_e32 v89, v221, v89
	v_mul_f32_e32 v90, v219, v90
	v_mul_f32_e32 v91, v217, v91
	v_mul_f32_e32 v92, v231, v92
	v_mul_f32_e32 v93, v229, v93
	v_mul_f32_e32 v94, v227, v94
	v_mul_f32_e32 v95, v225, v95
	v_mul_f32_e32 v96, v97, v96
	v_mul_f32_e32 v97, v237, v147
	v_mul_f32_e32 v149, v235, v149
	v_mul_f32_e32 v161, v233, v161
	v_mul_f32_e32 v147, v81, v80
	v_cvt_pk_bf16_f32 v66, v66, v82
	v_cvt_pk_bf16_f32 v67, v67, v83
	v_cvt_pk_bf16_f32 v68, v68, v70
	v_cvt_pk_bf16_f32 v69, v69, v71
	v_cvt_pk_bf16_f32 v70, v72, v74
	v_cvt_pk_bf16_f32 v71, v73, v75
	v_cvt_pk_bf16_f32 v72, v76, v78
	v_cvt_pk_bf16_f32 v73, v77, v79
	v_cvt_pk_bf16_f32 v74, v87, v86
	v_cvt_pk_bf16_f32 v75, v85, v84
	v_cvt_pk_bf16_f32 v76, v91, v90
	v_cvt_pk_bf16_f32 v77, v89, v88
	v_cvt_pk_bf16_f32 v78, v95, v94
	v_cvt_pk_bf16_f32 v79, v93, v92
	v_cvt_pk_bf16_f32 v80, v161, v149
	v_cvt_pk_bf16_f32 v81, v97, v96
	ds_read_b64_tr_b16 v[82:83], v190 offset:0
	ds_read_b64_tr_b16 v[84:85], v190 offset:0x800
	ds_read_b64_tr_b16 v[86:87], v190 offset:0x1000
	ds_read_b64_tr_b16 v[88:89], v190 offset:0x1800
	ds_read_b64_tr_b16 v[90:91], v190 offset:0x2000
	ds_read_b64_tr_b16 v[92:93], v190 offset:0x2800
	ds_read_b64_tr_b16 v[94:95], v190 offset:0x3000
	ds_read_b64_tr_b16 v[96:97], v190 offset:0x3800
	s_waitcnt lgkmcnt(0)
	s_nop 0
	v_permlane32_swap_b32_e32 v66, v68
	v_permlane32_swap_b32_e32 v67, v69
	v_permlane32_swap_b32_e32 v70, v72
	v_permlane32_swap_b32_e32 v71, v73
	v_permlane32_swap_b32_e32 v74, v76
	v_permlane32_swap_b32_e32 v75, v77
	v_permlane32_swap_b32_e32 v78, v80
	v_permlane32_swap_b32_e32 v79, v81
	v_mfma_f32_32x32x16_bf16 v[2:17], v[66:69], v[82:85], v[2:17]
	ds_read_b64_tr_b16 v[82:83], v190 offset:0x200
	ds_read_b64_tr_b16 v[84:85], v190 offset:0xa00
	v_mfma_f32_32x32x16_bf16 v[2:17], v[70:73], v[86:89], v[2:17]
	ds_read_b64_tr_b16 v[86:87], v190 offset:0x1200
	ds_read_b64_tr_b16 v[88:89], v190 offset:0x1a00
	v_mfma_f32_32x32x16_bf16 v[2:17], v[74:77], v[90:93], v[2:17]
	ds_read_b64_tr_b16 v[90:91], v190 offset:0x2200
	ds_read_b64_tr_b16 v[92:93], v190 offset:0x2a00
	v_mfma_f32_32x32x16_bf16 v[2:17], v[78:81], v[94:97], v[2:17]
	ds_read_b64_tr_b16 v[94:95], v190 offset:0x3200
	ds_read_b64_tr_b16 v[96:97], v190 offset:0x3a00
	s_waitcnt lgkmcnt(0)
	v_mfma_f32_32x32x16_bf16 v[50:65], v[66:69], v[82:85], v[50:65]
	ds_read_b64_tr_b16 v[82:83], v190 offset:0x400
	ds_read_b64_tr_b16 v[84:85], v190 offset:0xc00
	v_mfma_f32_32x32x16_bf16 v[50:65], v[70:73], v[86:89], v[50:65]
	ds_read_b64_tr_b16 v[86:87], v190 offset:0x1400
	ds_read_b64_tr_b16 v[88:89], v190 offset:0x1c00
	v_mfma_f32_32x32x16_bf16 v[50:65], v[74:77], v[90:93], v[50:65]
	ds_read_b64_tr_b16 v[90:91], v190 offset:0x2400
	ds_read_b64_tr_b16 v[92:93], v190 offset:0x2c00
	v_mfma_f32_32x32x16_bf16 v[50:65], v[78:81], v[94:97], v[50:65]
	ds_read_b64_tr_b16 v[94:95], v190 offset:0x3400
	ds_read_b64_tr_b16 v[96:97], v190 offset:0x3c00
	s_waitcnt lgkmcnt(0)
	v_mfma_f32_32x32x16_bf16 v[34:49], v[66:69], v[82:85], v[34:49]
	ds_read_b64_tr_b16 v[82:83], v190 offset:0x600
	ds_read_b64_tr_b16 v[84:85], v190 offset:0xe00
	v_mfma_f32_32x32x16_bf16 v[34:49], v[70:73], v[86:89], v[34:49]
	ds_read_b64_tr_b16 v[86:87], v190 offset:0x1600
	ds_read_b64_tr_b16 v[88:89], v190 offset:0x1e00
	v_mfma_f32_32x32x16_bf16 v[34:49], v[74:77], v[90:93], v[34:49]
	ds_read_b64_tr_b16 v[90:91], v190 offset:0x2600
	ds_read_b64_tr_b16 v[92:93], v190 offset:0x2e00
	v_mfma_f32_32x32x16_bf16 v[34:49], v[78:81], v[94:97], v[34:49]
	ds_read_b64_tr_b16 v[94:95], v190 offset:0x3600
	ds_read_b64_tr_b16 v[96:97], v190 offset:0x3e00
	s_waitcnt lgkmcnt(0)
	v_mfma_f32_32x32x16_bf16 v[18:33], v[66:69], v[82:85], v[18:33]
	v_mfma_f32_32x32x16_bf16 v[18:33], v[70:73], v[86:89], v[18:33]
	v_mfma_f32_32x32x16_bf16 v[18:33], v[74:77], v[90:93], v[18:33]
	v_mfma_f32_32x32x16_bf16 v[18:33], v[78:81], v[94:97], v[18:33]
; template <int MODE, bool SAMPLE>
; __device__ __forceinline__ void attn_unit(const Params& p, char* lds, int b, int h, int qb) {
;     ...
;         WRITET(buf, stg2[NS == 2 ? par : 0]);
;         if (j >= NS) LOADT(j - NS, stg2[NS == 2 ? par : 0]);
;         __syncthreads();
.LBB0_871:
	v_and_b32_e32 v76, 15, v183
	v_bfe_u32 v77, v183, 4, 3
	v_xor_b32_e32 v78, v76, v77
	v_lshrrev_b32_e32 v74, 1, v76
	v_xor_b32_e32 v74, v74, v77
	v_sub_u32_e32 v74, v74, v78
	v_and_b32_e32 v78, 1, v76
	v_lshlrev_b32_e32 v74, 4, v74
	v_lshl_add_u32 v74, v78, 3, v74
	v_lshrrev_b32_e32 v75, 3, v76
	v_lshrrev_b32_e32 v78, 2, v76
	v_sub_u32_e32 v75, v75, v78
	v_lshlrev_b32_e32 v75, 9, v75
	v_and_b32_e32 v78, 7, v76
	v_lshl_add_u32 v75, v78, 3, v75
	v_and_b32_e32 v78, 3, v76
	v_lshlrev_b32_e32 v78, 4, v78
	v_sub_u32_e32 v75, v75, v78
	v_add_u32_e32 v70, v198, v74
	v_add_u32_e32 v71, v199, v74
	v_add_u32_e32 v72, v200, v75
	v_add_u32_e32 v73, v201, v75
	s_waitcnt vmcnt(6)
	v_cvt_pk_bf16_f32 v66, v102, v103
	v_cvt_pk_bf16_f32 v67, v104, v105
	s_waitcnt vmcnt(6)
	v_cvt_pk_bf16_f32 v68, v98, v99
	v_cvt_pk_bf16_f32 v69, v100, v101
	ds_write_b64 v70, v[66:67]
	ds_write_b64 v70, v[68:69] offset:128
	s_waitcnt vmcnt(4)
	v_cvt_pk_bf16_f32 v66, v110, v111
	v_cvt_pk_bf16_f32 v67, v112, v113
	s_waitcnt vmcnt(4)
	v_cvt_pk_bf16_f32 v68, v106, v107
	v_cvt_pk_bf16_f32 v69, v108, v109
	ds_write_b64 v71, v[66:67]
	ds_write_b64 v71, v[68:69] offset:128
	s_waitcnt vmcnt(2)
	v_cvt_pk_bf16_f32 v66, v118, v119
	v_cvt_pk_bf16_f32 v67, v120, v121
	s_waitcnt vmcnt(2)
	v_cvt_pk_bf16_f32 v68, v114, v115
	v_cvt_pk_bf16_f32 v69, v116, v117
	s_cmp_eq_u32 s64, 0xffc00000
	ds_write_b64 v72, v[66:67] offset:32768
	ds_write_b64 v72, v[68:69] offset:33792
	s_waitcnt vmcnt(0)
	v_cvt_pk_bf16_f32 v66, v126, v127
	v_cvt_pk_bf16_f32 v67, v128, v129
	s_waitcnt vmcnt(0)
	v_cvt_pk_bf16_f32 v68, v122, v123
	v_cvt_pk_bf16_f32 v69, v124, v125
	ds_write_b64 v73, v[66:67] offset:32768
	ds_write_b64 v73, v[68:69] offset:33792
.Lfsr_join_s2:
	s_cbranch_scc1 .LBB0_873
	s_lshl_b64 s[6:7], s[52:53], 10
	v_lshl_add_u64 v[66:67], s[6:7], 0, v[164:165]
	v_readlane_b32 s36, v253, 16
	v_lshlrev_b64 v[66:67], 2, v[66:67]
	v_and_b32_e32 v72, 15, v183
	v_lshlrev_b32_e32 v72, 4, v72
	v_sub_u32_e32 v66, v66, v72
	v_readlane_b32 s46, v253, 26
	v_readlane_b32 s47, v253, 27
	v_readlane_b32 s48, v253, 28
	v_readlane_b32 s49, v253, 29
	v_lshl_add_u64 v[68:69], s[46:47], 0, v[66:67]
	v_mov_b32_e32 v163, v1
	v_lshl_add_u64 v[70:71], v[68:69], 0, v[0:1]
	v_lshl_add_u64 v[68:69], v[68:69], 0, v[162:163]
	v_lshl_add_u64 v[66:67], s[48:49], 0, v[66:67]
	global_load_dwordx4 v[98:101], v[70:71], off offset:256 nt
	global_load_dwordx4 v[102:105], v[70:71], off nt
	global_load_dwordx4 v[106:109], v[68:69], off offset:256 nt
	global_load_dwordx4 v[110:113], v[68:69], off nt
	v_lshl_add_u64 v[68:69], v[66:67], 0, v[0:1]
	v_lshl_add_u64 v[66:67], v[66:67], 0, v[162:163]
	global_load_dwordx4 v[114:117], v[68:69], off offset:256 nt
	global_load_dwordx4 v[118:121], v[68:69], off nt
	global_load_dwordx4 v[122:125], v[66:67], off offset:256 nt
	global_load_dwordx4 v[126:129], v[66:67], off nt
	v_readlane_b32 s37, v253, 17
	v_readlane_b32 s38, v253, 18
	v_readlane_b32 s39, v253, 19
	v_readlane_b32 s40, v253, 20
	v_readlane_b32 s41, v253, 21
	v_readlane_b32 s42, v253, 22
	v_readlane_b32 s43, v253, 23
	v_readlane_b32 s44, v253, 24
	v_readlane_b32 s45, v253, 25
	v_readlane_b32 s50, v253, 30
	v_readlane_b32 s51, v253, 31

; #define PG8_LAS __attribute__((address_space(3)))
;     ...
;         GS_STAGE(0, cA, cB); GS_STAGE(1, cA + 128, cB + 128); GS_STAGE(2, cA + 256, cB + 256);
;         for (int t = 0; t < nt; ++t) {
;             asm volatile("s_waitcnt vmcnt(8)" ::: "memory"); __builtin_amdgcn_s_barrier();
;             { const int tn = (t + 3 < nt) ? t + 3 : t + 3 - nt; GS_STAGE((t + 3) & 3, cA + (size_t)tn * 128, cB + (size_t)tn * 128); }
;             const int so = (t & 3) * 32768;
;             bf16x8 At[4][2], Bf[2][2];
; #pragma unroll
;             for (int m = 0; m < 4; ++m)
; #pragma unroll
;                 for (int k = 0; k < 2; ++k) At[m][k] = *(const PG8_LAS bf16x8*)(lds + so + aoff + m * 2048 + k * 1024);
; #pragma unroll
;             for (int n = 0; n < 2; ++n)
; #pragma unroll
;                 for (int k = 0; k < 2; ++k) Bf[n][k] = *(const PG8_LAS bf16x8*)(lds + so + 16384 + boff + n * 2048 + k * 1024);
;             asm volatile("s_waitcnt lgkmcnt(0)" ::: "memory"); __builtin_amdgcn_sched_barrier(0);
; #pragma unroll
;             for (int m = 0; m < 4; ++m)
; #pragma unroll
;                 for (int n = 0; n < 2; ++n)
; #pragma unroll
;                     for (int k = 0; k < 2; ++k) acc[m][n] = __builtin_amdgcn_mfma_f32_16x16x32_bf16(Bf[n][k], At[m][k], acc[m][n], 0, 0, 0);
;         }
;         asm volatile("s_waitcnt vmcnt(0)" ::: "memory"); __builtin_amdgcn_s_barrier();
.LBB0_996:
	s_cmp_lt_u32 s34, 29
	s_cselect_b32 s35, 3, 0xffffffe3
	s_add_i32 s36, s34, s35
	s_ashr_i32 s37, s36, 31
	s_lshl_b64 s[36:37], s[36:37], 7
	s_add_u32 s42, s0, s36
	s_addc_u32 s43, s1, s37
	s_add_i32 s35, s31, 0x18000
	s_and_b32 s35, s35, 0x18000
	s_add_i32 s35, s17, s35
	s_add_u32 s36, s12, s36
	s_addc_u32 s37, s13, s37
	s_add_i32 s41, s35, 0x4000
	v_lshl_add_u64 v[34:35], s[42:43], 0, v[128:129]
	s_mov_b32 m0, s35
	s_waitcnt vmcnt(8)
	s_barrier
	global_load_lds_dwordx4 v[34:35], off
	v_lshl_add_u64 v[34:35], s[36:37], 0, v[128:129]
	s_mov_b32 m0, s41
	s_nop 0
	global_load_lds_dwordx4 v[34:35], off
	v_lshl_add_u64 v[34:35], s[42:43], 0, v[130:131]
	s_add_i32 m0, s35, 0x2000
	s_nop 0
	global_load_lds_dwordx4 v[34:35], off
	v_lshl_add_u64 v[34:35], s[36:37], 0, v[130:131]
	s_add_i32 m0, s35, 0x6000
	s_and_b32 s35, s31, 0x10000
	global_load_lds_dwordx4 v[34:35], off
	v_add_u32_e32 v32, s35, v39
	ds_read_b128 v[34:37], v32
	ds_read_b128 v[44:47], v32 offset:1024
	ds_read_b128 v[48:51], v32 offset:2048
	ds_read_b128 v[52:55], v32 offset:3072
	ds_read_b128 v[56:59], v32 offset:4096
	ds_read_b128 v[60:63], v32 offset:5120
	ds_read_b128 v[64:67], v32 offset:6144
	ds_read_b128 v[68:71], v32 offset:7168
	v_add_u32_e32 v32, s35, v41
	ds_read_b128 v[72:75], v32 offset:16384
	ds_read_b128 v[76:79], v32 offset:17408
	ds_read_b128 v[80:83], v32 offset:18432
	ds_read_b128 v[84:87], v32 offset:19456
	s_waitcnt lgkmcnt(0)
	s_add_i32 s35, s34, 1
	s_cmp_lt_u32 s35, 29
	s_cselect_b32 s35, 4, 0xffffffe4
	s_add_i32 s36, s34, s35
	s_ashr_i32 s37, s36, 31
	s_lshl_b64 s[36:37], s[36:37], 7
	s_add_u32 s42, s0, s36
	s_addc_u32 s43, s1, s37
	s_add_i32 s35, s31, 0x20000
	s_and_b32 s35, s35, 0x10000
	s_add_i32 s35, s17, s35
	s_add_u32 s36, s12, s36
	s_waitcnt lgkmcnt(0)
	v_mfma_f32_16x16x32_bf16 v[28:31], v[72:75], v[34:37], v[28:31]
	s_addc_u32 s37, s13, s37
	s_add_i32 s41, s35, 0x4000
	s_mov_b32 m0, s35
	v_mfma_f32_16x16x32_bf16 v[24:27], v[80:83], v[34:37], v[24:27]
	v_lshl_add_u64 v[34:35], s[42:43], 0, v[128:129]
	s_waitcnt vmcnt(8)
	s_barrier
	global_load_lds_dwordx4 v[34:35], off
	v_lshl_add_u64 v[34:35], s[36:37], 0, v[128:129]
	s_mov_b32 m0, s41
	v_mfma_f32_16x16x32_bf16 v[20:23], v[72:75], v[48:51], v[20:23]
	global_load_lds_dwordx4 v[34:35], off
	v_lshl_add_u64 v[34:35], s[42:43], 0, v[130:131]
	s_add_i32 m0, s35, 0x2000
	v_mfma_f32_16x16x32_bf16 v[16:19], v[80:83], v[48:51], v[16:19]
	global_load_lds_dwordx4 v[34:35], off
	v_lshl_add_u64 v[34:35], s[36:37], 0, v[130:131]
	s_add_i32 m0, s35, 0x6000
	v_mfma_f32_16x16x32_bf16 v[12:15], v[72:75], v[56:59], v[12:15]
	global_load_lds_dwordx4 v[34:35], off
	s_add_i32 s35, s31, 0x8000
	v_mfma_f32_16x16x32_bf16 v[8:11], v[80:83], v[56:59], v[8:11]
	s_and_b32 s35, s35, 0x18000
	v_add_u32_e32 v32, s35, v39
	v_mfma_f32_16x16x32_bf16 v[4:7], v[72:75], v[64:67], v[4:7]
	v_mfma_f32_16x16x32_bf16 v[0:3], v[80:83], v[64:67], v[0:3]
	v_mfma_f32_16x16x32_bf16 v[28:31], v[76:79], v[44:47], v[28:31]
	v_mfma_f32_16x16x32_bf16 v[24:27], v[84:87], v[44:47], v[24:27]
	v_mfma_f32_16x16x32_bf16 v[20:23], v[76:79], v[52:55], v[20:23]
	v_mfma_f32_16x16x32_bf16 v[16:19], v[84:87], v[52:55], v[16:19]
	ds_read_b128 v[34:37], v32
	ds_read_b128 v[44:47], v32 offset:1024
	ds_read_b128 v[48:51], v32 offset:2048
	ds_read_b128 v[52:55], v32 offset:3072
	v_mfma_f32_16x16x32_bf16 v[12:15], v[76:79], v[60:63], v[12:15]
	v_mfma_f32_16x16x32_bf16 v[8:11], v[84:87], v[60:63], v[8:11]
	v_mfma_f32_16x16x32_bf16 v[4:7], v[76:79], v[68:71], v[4:7]
	ds_read_b128 v[56:59], v32 offset:4096
	ds_read_b128 v[60:63], v32 offset:5120
	ds_read_b128 v[72:75], v32 offset:6144
	ds_read_b128 v[76:79], v32 offset:7168
	v_add_u32_e32 v32, s35, v41
	ds_read_b128 v[64:67], v32 offset:16384
	ds_read_b128 v[80:83], v32 offset:17408
	v_mfma_f32_16x16x32_bf16 v[0:3], v[84:87], v[68:71], v[0:3]
	ds_read_b128 v[68:71], v32 offset:18432
	ds_read_b128 v[84:87], v32 offset:19456
	s_waitcnt lgkmcnt(0)
	s_waitcnt lgkmcnt(0)
	v_mfma_f32_16x16x32_bf16 v[28:31], v[64:67], v[34:37], v[28:31]
	s_add_i32 s31, s31, 0x10000
	s_add_i32 s34, s34, 2
	s_cmp_eq_u32 s34, 32
	v_mfma_f32_16x16x32_bf16 v[24:27], v[68:71], v[34:37], v[24:27]
	v_mfma_f32_16x16x32_bf16 v[20:23], v[64:67], v[48:51], v[20:23]
	v_mfma_f32_16x16x32_bf16 v[16:19], v[68:71], v[48:51], v[16:19]
	v_mfma_f32_16x16x32_bf16 v[12:15], v[64:67], v[56:59], v[12:15]
	v_mfma_f32_16x16x32_bf16 v[8:11], v[68:71], v[56:59], v[8:11]
	v_mfma_f32_16x16x32_bf16 v[4:7], v[64:67], v[72:75], v[4:7]
	v_mfma_f32_16x16x32_bf16 v[0:3], v[68:71], v[72:75], v[0:3]
	v_mfma_f32_16x16x32_bf16 v[28:31], v[80:83], v[44:47], v[28:31]
	v_mfma_f32_16x16x32_bf16 v[24:27], v[84:87], v[44:47], v[24:27]
	v_mfma_f32_16x16x32_bf16 v[20:23], v[80:83], v[52:55], v[20:23]
	v_mfma_f32_16x16x32_bf16 v[16:19], v[84:87], v[52:55], v[16:19]
	v_mfma_f32_16x16x32_bf16 v[12:15], v[80:83], v[60:63], v[12:15]
	v_mfma_f32_16x16x32_bf16 v[8:11], v[84:87], v[60:63], v[8:11]
	v_mfma_f32_16x16x32_bf16 v[4:7], v[80:83], v[76:79], v[4:7]
	v_mfma_f32_16x16x32_bf16 v[0:3], v[84:87], v[76:79], v[0:3]
	s_cbranch_scc0 .LBB0_996
	v_add_u32_e32 v34, s30, v38
	v_add_u32_e32 v32, 0xffffe000, v34
	v_readlane_b32 s44, v253, 16
	v_lshl_or_b32 v43, s29, 7, v40
	v_lshlrev_b64 v[36:37], 13, v[32:33]
	v_readlane_b32 s46, v253, 18
	v_readlane_b32 s47, v253, 19
	s_waitcnt vmcnt(0)
	s_barrier
; __device__ __forceinline__ unsigned cvtpk(float lo, float hi) { unsigned r; asm volatile("v_cvt_pk_bf16_f32 %0, %1, %2" : "=v"(r) : "v"(lo), "v"(hi)); return r; }
;     __device__ __forceinline__ void quad(const f32x4 (&a)[4][2], int rowq, int colq, int wr, int wc, int fr, int fq) const {
;         const int col0 = colq + wc * 32 + 4 * fq;
; #pragma unroll
;         for (int m = 0; m < 4; ++m) { const int row = rowq + wr * 64 + m * 16 + fr;
;             const float* xr = row < MP ? xp + (size_t)row * DM : xs + (size_t)(row - MP) * DM; float s = 0.f;
; #pragma unroll
;             for (int n = 0; n < 2; ++n) { const int c = col0 + n * 16; f32x4 hv = a[m][n]; if (!pre) hv += *(const f32x4*)(xr + c);
;                 __builtin_nontemporal_store(hv, (f32x4*)(H1 + (size_t)row * DM + c)); s += (hv[0] * hv[0] + hv[1] * hv[1]) + (hv[2] * hv[2] + hv[3] * hv[3]);
;                 const f32x4 gv = *(const f32x4*)(g1 + c); u32x2 w; w.x = cvtpk(hv[0] * gv[0], hv[1] * gv[1]); w.y = cvtpk(hv[2] * gv[2], hv[3] * gv[3]);
;                 *(u32x2*)(A1 + (size_t)row * DM + c) = w; }
;             s += __shfl_xor(s, 16); s += __shfl_xor(s, 32);
;             if (fq == 0) unsafeAtomicAdd(ssq + row, s); }
	v_mov_b32_e32 v35, v33
	v_lshl_add_u64 v[44:45], s[46:47], 0, v[36:37]
	v_lshlrev_b32_e32 v36, 2, v43
	v_mov_b32_e32 v37, v33
	v_lshl_add_u64 v[52:53], v[44:45], 0, v[36:37]
	global_load_dwordx4 v[44:47], v[52:53], off
	v_readlane_b32 s100, v253, 38
	v_readlane_b32 s101, v253, 39
	s_mov_b32 s98, 0x20000
	s_mov_b32 s99, 0
	global_load_dwordx4 v[100:103], v[52:53], off offset:64
	v_lshl_add_u64 v[88:89], v[52:53], 0, s[98:99]
	global_load_dwordx4 v[104:107], v[88:89], off
	global_load_dwordx4 v[108:111], v[88:89], off offset:64
	v_lshl_add_u64 v[88:89], v[88:89], 0, s[98:99]
	global_load_dwordx4 v[112:115], v[88:89], off
	global_load_dwordx4 v[116:119], v[88:89], off offset:64
	v_lshl_add_u64 v[88:89], v[88:89], 0, s[98:99]
	global_load_dwordx4 v[120:123], v[88:89], off
	global_load_dwordx4 v[124:127], v[88:89], off offset:64
	global_load_dwordx4 v[132:135], v36, s[100:101]
	global_load_dwordx4 v[136:139], v36, s[100:101] offset:64
	v_lshlrev_b64 v[48:49], 13, v[34:35]
	v_readlane_b32 s45, v253, 17
	v_readlane_b32 s48, v253, 20
	v_readlane_b32 s49, v253, 21
	v_readlane_b32 s50, v253, 22
	v_readlane_b32 s51, v253, 23
	v_readlane_b32 s52, v253, 24
	v_readlane_b32 s53, v253, 25
	v_readlane_b32 s54, v253, 26
	v_readlane_b32 s55, v253, 27
	v_readlane_b32 s56, v253, 28
	v_readlane_b32 s57, v253, 29
	v_readlane_b32 s58, v253, 30
	v_readlane_b32 s59, v253, 31
	v_lshl_add_u64 v[48:49], s[6:7], 0, v[48:49]
	v_lshl_add_u64 v[54:55], v[48:49], 0, v[36:37]
	v_readlane_b32 s44, v253, 32
	v_readlane_b32 s50, v253, 38
	v_readlane_b32 s51, v253, 39
	v_readlane_b32 s45, v253, 33
	v_readlane_b32 s46, v253, 34
	v_readlane_b32 s47, v253, 35
	v_readlane_b32 s48, v253, 36
	v_readlane_b32 s49, v253, 37
	v_readlane_b32 s52, v253, 40
	v_readlane_b32 s53, v253, 41
	v_readlane_b32 s54, v253, 42
	v_readlane_b32 s55, v253, 43
	v_readlane_b32 s56, v253, 44
	v_readlane_b32 s57, v253, 45
	v_readlane_b32 s58, v253, 46
	v_readlane_b32 s59, v253, 47
	s_waitcnt vmcnt(0)
	v_pk_add_f32 v[46:47], v[30:31], v[46:47]
	v_pk_add_f32 v[44:45], v[28:29], v[44:45]
	global_store_dwordx4 v[54:55], v[44:47], off nt
	v_lshlrev_b64 v[30:31], 12, v[34:35]
	v_mov_b32_e32 v29, v33
	v_lshlrev_b32_e32 v28, 1, v43
	v_lshl_add_u64 v[30:31], s[8:9], 0, v[30:31]
	v_lshl_add_u64 v[30:31], v[30:31], 0, v[28:29]
	v_mov_b32_e32 v48, v132
	v_mov_b32_e32 v49, v133
	v_mov_b32_e32 v50, v134
	v_mov_b32_e32 v51, v135
	v_mul_f32_e32 v43, v45, v49
	v_mul_f32_e32 v49, v46, v50
	v_mul_f32_e32 v32, v44, v48
	v_mul_f32_e32 v50, v47, v51
	v_cvt_pk_bf16_f32 v48, v32, v43
	v_cvt_pk_bf16_f32 v49, v49, v50
	global_store_dwordx2 v[30:31], v[48:49], off
	v_mov_b32_e32 v48, v100
	v_mov_b32_e32 v49, v101
	v_mov_b32_e32 v50, v102
	v_mov_b32_e32 v51, v103
	v_pk_add_f32 v[50:51], v[26:27], v[50:51]
	v_pk_add_f32 v[48:49], v[24:25], v[48:49]
	global_store_dwordx4 v[54:55], v[48:51], off offset:64 nt
	v_and_b32_e32 v25, 64, v42
	v_xor_b32_e32 v24, 16, v42
	v_add_u32_e32 v25, 64, v25
	v_cmp_lt_i32_e64 s[0:1], v24, v25
	v_mul_f32_e32 v27, v47, v47
	v_fmac_f32_e32 v27, v46, v46
	v_cndmask_b32_e64 v24, v42, v24, s[0:1]
	v_lshlrev_b32_e32 v26, 2, v24
	v_mul_f32_e32 v24, v45, v45
	v_fmac_f32_e32 v24, v44, v44
	v_add_f32_e32 v24, v24, v27
	v_mul_f32_e32 v27, v49, v49
	v_mul_f32_e32 v32, v51, v51
	v_fmac_f32_e32 v27, v48, v48
	v_fmac_f32_e32 v32, v50, v50
	v_add_f32_e32 v27, v27, v32
	v_add_f32_e32 v24, v24, v27
	ds_bpermute_b32 v32, v26, v24
	v_xor_b32_e32 v27, 32, v42
	v_cmp_lt_i32_e64 s[0:1], v27, v25
	s_waitcnt lgkmcnt(0)
	v_add_f32_e32 v24, v24, v32
	v_cndmask_b32_e64 v25, v42, v27, s[0:1]
	v_lshlrev_b32_e32 v27, 2, v25
	ds_bpermute_b32 v25, v27, v24
	v_mov_b32_e32 v52, v136
	v_mov_b32_e32 v53, v137
	v_mov_b32_e32 v54, v138
	v_mov_b32_e32 v55, v139
	v_mul_f32_e32 v45, v50, v54
	v_mul_f32_e32 v32, v48, v52
	v_mul_f32_e32 v43, v49, v53
	v_mul_f32_e32 v46, v51, v55
	v_cvt_pk_bf16_f32 v44, v32, v43
	v_cvt_pk_bf16_f32 v45, v45, v46
	global_store_dwordx2 v[30:31], v[44:45], off offset:32
	s_and_saveexec_b64 s[0:1], vcc
	s_cbranch_execz .LBB0_999
	v_lshl_add_u64 v[30:31], v[34:35], 2, s[92:93]
	s_waitcnt lgkmcnt(0)
	v_add_f32_e32 v24, v24, v25
	global_atomic_add_f32 v[30:31], v24, off
.LBB0_999:
	s_or_b64 exec, exec, s[0:1]
	v_add_u32_e32 v32, 0xffffe010, v34
	v_readlane_b32 s44, v253, 16
	s_waitcnt lgkmcnt(0)
	v_lshlrev_b64 v[24:25], 13, v[32:33]
	v_readlane_b32 s46, v253, 18
	v_readlane_b32 s47, v253, 19
	v_or_b32_e32 v32, 16, v34
	v_readlane_b32 s45, v253, 17
	v_lshl_add_u64 v[24:25], s[46:47], 0, v[24:25]
	v_lshl_add_u64 v[30:31], v[24:25], 0, v[36:37]
	v_readlane_b32 s48, v253, 20
	v_readlane_b32 s49, v253, 21
	v_readlane_b32 s50, v253, 22
	v_readlane_b32 s51, v253, 23
	v_readlane_b32 s52, v253, 24
	v_readlane_b32 s53, v253, 25
	v_readlane_b32 s54, v253, 26
	v_readlane_b32 s55, v253, 27
	v_readlane_b32 s56, v253, 28
	v_readlane_b32 s57, v253, 29
	v_readlane_b32 s58, v253, 30
	v_readlane_b32 s59, v253, 31
	v_lshlrev_b64 v[48:49], 13, v[32:33]
	v_readlane_b32 s44, v253, 32
	v_lshl_add_u64 v[48:49], s[6:7], 0, v[48:49]
	v_readlane_b32 s50, v253, 38
	v_readlane_b32 s51, v253, 39
	v_lshl_add_u64 v[48:49], v[48:49], 0, v[36:37]
	v_lshlrev_b64 v[50:51], 12, v[32:33]
	v_lshl_add_u64 v[24:25], s[50:51], 0, v[36:37]
	v_lshl_add_u64 v[50:51], s[8:9], 0, v[50:51]
	v_lshl_add_u64 v[52:53], v[50:51], 0, v[28:29]
	v_readlane_b32 s45, v253, 33
	v_readlane_b32 s46, v253, 34
	v_readlane_b32 s47, v253, 35
	v_readlane_b32 s48, v253, 36
	v_readlane_b32 s49, v253, 37
	v_readlane_b32 s52, v253, 40
	v_readlane_b32 s53, v253, 41
	v_readlane_b32 s54, v253, 42
	v_readlane_b32 s55, v253, 43
	v_readlane_b32 s56, v253, 44
	v_readlane_b32 s57, v253, 45
	v_readlane_b32 s58, v253, 46
	v_readlane_b32 s59, v253, 47
	v_mov_b32_e32 v44, v104
	v_mov_b32_e32 v45, v105
	v_mov_b32_e32 v46, v106
	v_mov_b32_e32 v47, v107
	v_pk_add_f32 v[22:23], v[22:23], v[46:47]
	v_pk_add_f32 v[20:21], v[20:21], v[44:45]
	global_store_dwordx4 v[48:49], v[20:23], off nt
	v_mov_b32_e32 v44, v132
	v_mov_b32_e32 v45, v133
	v_mov_b32_e32 v46, v134
	v_mov_b32_e32 v47, v135
	v_mul_f32_e32 v29, v20, v44
	v_mul_f32_e32 v35, v21, v45
	v_mul_f32_e32 v37, v22, v46
	v_mul_f32_e32 v43, v23, v47
	v_cvt_pk_bf16_f32 v44, v29, v35
	v_cvt_pk_bf16_f32 v45, v37, v43
	global_store_dwordx2 v[52:53], v[44:45], off
	v_mov_b32_e32 v44, v108
	v_mov_b32_e32 v45, v109
	v_mov_b32_e32 v46, v110
	v_mov_b32_e32 v47, v111
	v_pk_add_f32 v[46:47], v[18:19], v[46:47]
	v_pk_add_f32 v[44:45], v[16:17], v[44:45]
	global_store_dwordx4 v[48:49], v[44:47], off offset:64 nt
	v_mul_f32_e32 v16, v21, v21
	v_mul_f32_e32 v17, v23, v23
	v_fmac_f32_e32 v16, v20, v20
	v_fmac_f32_e32 v17, v22, v22
	v_add_f32_e32 v16, v16, v17
	v_mul_f32_e32 v17, v45, v45
	v_mul_f32_e32 v18, v47, v47
	v_fmac_f32_e32 v17, v44, v44
	v_fmac_f32_e32 v18, v46, v46
	v_add_f32_e32 v17, v17, v18
	v_add_f32_e32 v16, v16, v17
	ds_bpermute_b32 v17, v26, v16
	s_waitcnt lgkmcnt(0)
; __device__ __forceinline__ unsigned cvtpk(float lo, float hi) { unsigned r; asm volatile("v_cvt_pk_bf16_f32 %0, %1, %2" : "=v"(r) : "v"(lo), "v"(hi)); return r; }
;     __device__ __forceinline__ void quad(const f32x4 (&a)[4][2], int rowq, int colq, int wr, int wc, int fr, int fq) const {
;     ...
;         for (int m = 0; m < 4; ++m) { const int row = rowq + wr * 64 + m * 16 + fr;
;             const float* xr = row < MP ? xp + (size_t)row * DM : xs + (size_t)(row - MP) * DM; float s = 0.f;
; #pragma unroll
;             for (int n = 0; n < 2; ++n) { const int c = col0 + n * 16; f32x4 hv = a[m][n]; if (!pre) hv += *(const f32x4*)(xr + c);
;                 __builtin_nontemporal_store(hv, (f32x4*)(H1 + (size_t)row * DM + c)); s += (hv[0] * hv[0] + hv[1] * hv[1]) + (hv[2] * hv[2] + hv[3] * hv[3]);
;                 const f32x4 gv = *(const f32x4*)(g1 + c); u32x2 w; w.x = cvtpk(hv[0] * gv[0], hv[1] * gv[1]); w.y = cvtpk(hv[2] * gv[2], hv[3] * gv[3]);
;                 *(u32x2*)(A1 + (size_t)row * DM + c) = w; }
;             s += __shfl_xor(s, 16); s += __shfl_xor(s, 32);
;             if (fq == 0) unsafeAtomicAdd(ssq + row, s); }
	v_add_f32_e32 v16, v16, v17
	ds_bpermute_b32 v17, v27, v16
	v_mov_b32_e32 v48, v136
	v_mov_b32_e32 v49, v137
	v_mov_b32_e32 v50, v138
	v_mov_b32_e32 v51, v139
	v_mul_f32_e32 v18, v44, v48
	v_mul_f32_e32 v19, v45, v49
	v_mul_f32_e32 v20, v46, v50
	v_mul_f32_e32 v21, v47, v51
	v_cvt_pk_bf16_f32 v18, v18, v19
	v_cvt_pk_bf16_f32 v19, v20, v21
	global_store_dwordx2 v[52:53], v[18:19], off offset:32
	s_and_saveexec_b64 s[0:1], vcc
	s_cbranch_execz .LBB0_1001
	v_lshl_add_u64 v[18:19], v[32:33], 2, s[92:93]
	s_waitcnt lgkmcnt(0)
	v_add_f32_e32 v16, v16, v17
	global_atomic_add_f32 v[18:19], v16, off
.LBB0_1001:
	s_or_b64 exec, exec, s[0:1]
	v_add_u32_e32 v32, 0xffffe020, v34
	v_readlane_b32 s44, v253, 16
	s_waitcnt lgkmcnt(0)
	v_lshlrev_b64 v[16:17], 13, v[32:33]
	v_readlane_b32 s46, v253, 18
	v_readlane_b32 s47, v253, 19
	v_mov_b32_e32 v37, v33
	v_or_b32_e32 v32, 32, v34
	v_lshl_add_u64 v[16:17], s[46:47], 0, v[16:17]
	v_lshl_add_u64 v[20:21], v[16:17], 0, v[36:37]
	v_lshlrev_b64 v[22:23], 13, v[32:33]
	v_lshl_add_u64 v[22:23], s[6:7], 0, v[22:23]
	v_lshl_add_u64 v[22:23], v[22:23], 0, v[36:37]
	v_lshlrev_b64 v[30:31], 12, v[32:33]
	v_mov_b32_e32 v29, v33
	v_lshl_add_u64 v[30:31], s[8:9], 0, v[30:31]
	v_lshl_add_u64 v[30:31], v[30:31], 0, v[28:29]
	v_readlane_b32 s45, v253, 17
	v_readlane_b32 s48, v253, 20
	v_readlane_b32 s49, v253, 21
	v_readlane_b32 s50, v253, 22
	v_readlane_b32 s51, v253, 23
	v_readlane_b32 s52, v253, 24
	v_readlane_b32 s53, v253, 25
	v_readlane_b32 s54, v253, 26
	v_readlane_b32 s55, v253, 27
	v_readlane_b32 s56, v253, 28
	v_readlane_b32 s57, v253, 29
	v_readlane_b32 s58, v253, 30
	v_readlane_b32 s59, v253, 31
	v_mov_b32_e32 v16, v112
	v_mov_b32_e32 v17, v113
	v_mov_b32_e32 v18, v114
	v_mov_b32_e32 v19, v115
	v_pk_add_f32 v[14:15], v[14:15], v[18:19]
	v_pk_add_f32 v[12:13], v[12:13], v[16:17]
	global_store_dwordx4 v[22:23], v[12:15], off nt
	v_mov_b32_e32 v16, v132
	v_mov_b32_e32 v17, v133
	v_mov_b32_e32 v18, v134
	v_mov_b32_e32 v19, v135
	v_mul_f32_e32 v16, v12, v16
	v_mul_f32_e32 v17, v13, v17
	v_mul_f32_e32 v18, v14, v18
	v_mul_f32_e32 v19, v15, v19
	v_cvt_pk_bf16_f32 v16, v16, v17
	v_cvt_pk_bf16_f32 v17, v18, v19
	global_store_dwordx2 v[30:31], v[16:17], off
	v_mov_b32_e32 v16, v116
	v_mov_b32_e32 v17, v117
	v_mov_b32_e32 v18, v118
	v_mov_b32_e32 v19, v119
	v_pk_add_f32 v[18:19], v[10:11], v[18:19]
	v_pk_add_f32 v[16:17], v[8:9], v[16:17]
	global_store_dwordx4 v[22:23], v[16:19], off offset:64 nt
	v_mul_f32_e32 v8, v13, v13
	v_mul_f32_e32 v9, v15, v15
	v_fmac_f32_e32 v8, v12, v12
	v_fmac_f32_e32 v9, v14, v14
	v_add_f32_e32 v8, v8, v9
	v_mul_f32_e32 v9, v17, v17
	v_mul_f32_e32 v10, v19, v19
	v_fmac_f32_e32 v9, v16, v16
	v_fmac_f32_e32 v10, v18, v18
	v_add_f32_e32 v9, v9, v10
	v_add_f32_e32 v8, v8, v9
	ds_bpermute_b32 v9, v26, v8
	s_waitcnt lgkmcnt(0)
	v_add_f32_e32 v8, v8, v9
	ds_bpermute_b32 v9, v27, v8
	v_mov_b32_e32 v20, v136
	v_mov_b32_e32 v21, v137
	v_mov_b32_e32 v22, v138
	v_mov_b32_e32 v23, v139
	v_mul_f32_e32 v10, v16, v20
	v_mul_f32_e32 v11, v17, v21
	v_mul_f32_e32 v12, v18, v22
	v_mul_f32_e32 v13, v19, v23
	v_cvt_pk_bf16_f32 v10, v10, v11
	v_cvt_pk_bf16_f32 v11, v12, v13
	global_store_dwordx2 v[30:31], v[10:11], off offset:32
	s_and_saveexec_b64 s[0:1], vcc
	s_cbranch_execz .LBB0_1003
	v_lshl_add_u64 v[10:11], v[32:33], 2, s[92:93]
	s_waitcnt lgkmcnt(0)
	v_add_f32_e32 v8, v8, v9
	global_atomic_add_f32 v[10:11], v8, off
.LBB0_1003:
	s_or_b64 exec, exec, s[0:1]
	v_add_u32_e32 v32, 0xffffe030, v34
	v_readlane_b32 s44, v253, 16
	s_waitcnt lgkmcnt(0)
	v_lshlrev_b64 v[8:9], 13, v[32:33]
	v_readlane_b32 s46, v253, 18
	v_readlane_b32 s47, v253, 19
	v_or_b32_e32 v32, 48, v34
	v_lshlrev_b64 v[14:15], 13, v[32:33]
	v_lshl_add_u64 v[8:9], s[46:47], 0, v[8:9]
	v_lshl_add_u64 v[12:13], v[8:9], 0, v[36:37]
	v_lshl_add_u64 v[14:15], s[6:7], 0, v[14:15]
	v_lshl_add_u64 v[14:15], v[14:15], 0, v[36:37]
	v_lshlrev_b64 v[16:17], 12, v[32:33]
	v_lshl_add_u64 v[16:17], s[8:9], 0, v[16:17]
	v_lshl_add_u64 v[16:17], v[16:17], 0, v[28:29]
	v_readlane_b32 s45, v253, 17
	v_readlane_b32 s48, v253, 20
	v_readlane_b32 s49, v253, 21
	v_readlane_b32 s50, v253, 22
	v_readlane_b32 s51, v253, 23
	v_readlane_b32 s52, v253, 24
	v_readlane_b32 s53, v253, 25
	v_readlane_b32 s54, v253, 26
	v_readlane_b32 s55, v253, 27
	v_readlane_b32 s56, v253, 28
	v_readlane_b32 s57, v253, 29
	v_readlane_b32 s58, v253, 30
	v_readlane_b32 s59, v253, 31
	v_mov_b32_e32 v8, v120
	v_mov_b32_e32 v9, v121
	v_mov_b32_e32 v10, v122
	v_mov_b32_e32 v11, v123
	v_pk_add_f32 v[6:7], v[6:7], v[10:11]
	v_pk_add_f32 v[4:5], v[4:5], v[8:9]
	global_store_dwordx4 v[14:15], v[4:7], off nt
	v_mov_b32_e32 v8, v132
	v_mov_b32_e32 v9, v133
	v_mov_b32_e32 v10, v134
	v_mov_b32_e32 v11, v135
	v_mul_f32_e32 v8, v4, v8
	v_mul_f32_e32 v9, v5, v9
	v_mul_f32_e32 v10, v6, v10
	v_mul_f32_e32 v11, v7, v11
	v_cvt_pk_bf16_f32 v8, v8, v9
	v_cvt_pk_bf16_f32 v9, v10, v11
	global_store_dwordx2 v[16:17], v[8:9], off
	v_mov_b32_e32 v8, v124
	v_mov_b32_e32 v9, v125
	v_mov_b32_e32 v10, v126
	v_mov_b32_e32 v11, v127
	v_pk_add_f32 v[10:11], v[2:3], v[10:11]
	v_pk_add_f32 v[8:9], v[0:1], v[8:9]
	global_store_dwordx4 v[14:15], v[8:11], off offset:64 nt
	v_mul_f32_e32 v0, v5, v5
	v_mul_f32_e32 v1, v7, v7
	v_fmac_f32_e32 v0, v4, v4
	v_fmac_f32_e32 v1, v6, v6
	v_add_f32_e32 v0, v0, v1
	v_mul_f32_e32 v1, v9, v9
	v_mul_f32_e32 v2, v11, v11
	v_fmac_f32_e32 v1, v8, v8
	v_fmac_f32_e32 v2, v10, v10
	v_add_f32_e32 v1, v1, v2
	v_add_f32_e32 v0, v0, v1
	ds_bpermute_b32 v1, v26, v0
	s_waitcnt lgkmcnt(0)
	v_add_f32_e32 v0, v0, v1
	ds_bpermute_b32 v1, v27, v0
	v_mov_b32_e32 v12, v136
	v_mov_b32_e32 v13, v137
	v_mov_b32_e32 v14, v138
	v_mov_b32_e32 v15, v139
	v_mul_f32_e32 v2, v8, v12
	v_mul_f32_e32 v3, v9, v13
	v_mul_f32_e32 v4, v10, v14
	v_mul_f32_e32 v5, v11, v15
	v_cvt_pk_bf16_f32 v2, v2, v3
	v_cvt_pk_bf16_f32 v3, v4, v5
	global_store_dwordx2 v[16:17], v[2:3], off offset:32
	s_and_saveexec_b64 s[0:1], vcc
	s_cbranch_execz .LBB0_994
	v_lshl_add_u64 v[2:3], v[32:33], 2, s[92:93]
	s_waitcnt lgkmcnt(0)
	v_add_f32_e32 v0, v0, v1
	global_atomic_add_f32 v[2:3], v0, off
	s_branch .LBB0_994

; #define PG8_LAS __attribute__((address_space(3)))
;     ...
;         GS_STAGE(0, cA, cB); GS_STAGE(1, cA + 128, cB + 128); GS_STAGE(2, cA + 256, cB + 256);
;         for (int t = 0; t < nt; ++t) {
;             asm volatile("s_waitcnt vmcnt(8)" ::: "memory"); __builtin_amdgcn_s_barrier();
;             { const int tn = (t + 3 < nt) ? t + 3 : t + 3 - nt; GS_STAGE((t + 3) & 3, cA + (size_t)tn * 128, cB + (size_t)tn * 128); }
;             const int so = (t & 3) * 32768;
;             bf16x8 At[4][2], Bf[2][2];
; #pragma unroll
;             for (int m = 0; m < 4; ++m)
; #pragma unroll
;                 for (int k = 0; k < 2; ++k) At[m][k] = *(const PG8_LAS bf16x8*)(lds + so + aoff + m * 2048 + k * 1024);
; #pragma unroll
;             for (int n = 0; n < 2; ++n)
; #pragma unroll
;                 for (int k = 0; k < 2; ++k) Bf[n][k] = *(const PG8_LAS bf16x8*)(lds + so + 16384 + boff + n * 2048 + k * 1024);
;             asm volatile("s_waitcnt lgkmcnt(0)" ::: "memory"); __builtin_amdgcn_sched_barrier(0);
; #pragma unroll
;             for (int m = 0; m < 4; ++m)
; #pragma unroll
;                 for (int n = 0; n < 2; ++n)
; #pragma unroll
;                     for (int k = 0; k < 2; ++k) acc[m][n] = __builtin_amdgcn_mfma_f32_16x16x32_bf16(Bf[n][k], At[m][k], acc[m][n], 0, 0, 0);
;         }
;         asm volatile("s_waitcnt vmcnt(0)" ::: "memory"); __builtin_amdgcn_s_barrier();
.LBB0_1103:
	s_cmp_lt_u32 s45, 29
	s_cselect_b32 s46, 3, 0xffffffe3
	s_add_i32 s46, s45, s46
	s_ashr_i32 s47, s46, 31
	s_lshl_b64 s[46:47], s[46:47], 7
	s_add_u32 s48, s16, s46
	s_addc_u32 s49, s17, s47
	s_add_i32 s50, s44, 0x18000
	s_and_b32 s50, s50, 0x18000
	s_add_i32 s50, s23, s50
	s_add_u32 s46, s18, s46
	s_addc_u32 s47, s19, s47
	s_add_i32 s51, s50, 0x4000
	v_lshl_add_u64 v[34:35], s[48:49], 0, v[128:129]
	s_mov_b32 m0, s50
	s_waitcnt vmcnt(8)
	s_barrier
	global_load_lds_dwordx4 v[34:35], off
	v_lshl_add_u64 v[34:35], s[46:47], 0, v[130:131]
	s_mov_b32 m0, s51
	s_nop 0
	global_load_lds_dwordx4 v[34:35], off
	v_lshl_add_u64 v[34:35], s[48:49], 0, v[132:133]
	s_add_i32 m0, s50, 0x2000
	s_nop 0
	global_load_lds_dwordx4 v[34:35], off
	v_lshl_add_u64 v[34:35], s[46:47], 0, v[134:135]
	s_add_i32 m0, s50, 0x6000
	s_and_b32 s46, s44, 0x10000
	global_load_lds_dwordx4 v[34:35], off
	v_add_u32_e32 v32, s46, v40
	ds_read_b128 v[34:37], v32
	s_waitcnt lgkmcnt(0)
	ds_read_b128 v[44:47], v32 offset:1024
	ds_read_b128 v[48:51], v32 offset:2048
	ds_read_b128 v[52:55], v32 offset:3072
	ds_read_b128 v[56:59], v32 offset:4096
	ds_read_b128 v[60:63], v32 offset:5120
	ds_read_b128 v[64:67], v32 offset:6144
	ds_read_b128 v[68:71], v32 offset:7168
	v_add_u32_e32 v32, s46, v41
	ds_read_b128 v[72:75], v32 offset:16384
	ds_read_b128 v[76:79], v32 offset:17408
	ds_read_b128 v[80:83], v32 offset:18432
	ds_read_b128 v[84:87], v32 offset:19456
	s_waitcnt lgkmcnt(0)
	s_add_i32 s46, s45, 1
	s_cmp_lt_u32 s46, 29
	s_cselect_b32 s46, 4, 0xffffffe4
	s_add_i32 s46, s45, s46
	s_ashr_i32 s47, s46, 31
	s_lshl_b64 s[46:47], s[46:47], 7
	s_add_u32 s48, s16, s46
	s_addc_u32 s49, s17, s47
	s_add_i32 s50, s44, 0x20000
	s_and_b32 s50, s50, 0x10000
	s_add_i32 s50, s23, s50
	s_add_u32 s46, s18, s46
	s_waitcnt lgkmcnt(0)
	v_mfma_f32_16x16x32_bf16 v[28:31], v[72:75], v[34:37], v[28:31]
	s_addc_u32 s47, s19, s47
	s_add_i32 s51, s50, 0x4000
	s_mov_b32 m0, s50
	v_mfma_f32_16x16x32_bf16 v[24:27], v[80:83], v[34:37], v[24:27]
	v_lshl_add_u64 v[34:35], s[48:49], 0, v[128:129]
	s_waitcnt vmcnt(8)
	s_barrier
	global_load_lds_dwordx4 v[34:35], off
	v_lshl_add_u64 v[34:35], s[46:47], 0, v[130:131]
	s_mov_b32 m0, s51
	v_mfma_f32_16x16x32_bf16 v[20:23], v[72:75], v[48:51], v[20:23]
	global_load_lds_dwordx4 v[34:35], off
	v_lshl_add_u64 v[34:35], s[48:49], 0, v[132:133]
	s_add_i32 m0, s50, 0x2000
	v_mfma_f32_16x16x32_bf16 v[16:19], v[80:83], v[48:51], v[16:19]
	global_load_lds_dwordx4 v[34:35], off
	v_lshl_add_u64 v[34:35], s[46:47], 0, v[134:135]
	s_add_i32 m0, s50, 0x6000
	v_mfma_f32_16x16x32_bf16 v[12:15], v[72:75], v[56:59], v[12:15]
	global_load_lds_dwordx4 v[34:35], off
	s_add_i32 s46, s44, 0x8000
	v_mfma_f32_16x16x32_bf16 v[8:11], v[80:83], v[56:59], v[8:11]
	s_and_b32 s46, s46, 0x18000
	v_add_u32_e32 v32, s46, v40
	v_mfma_f32_16x16x32_bf16 v[0:3], v[72:75], v[64:67], v[0:3]
	v_mfma_f32_16x16x32_bf16 v[4:7], v[80:83], v[64:67], v[4:7]
	v_mfma_f32_16x16x32_bf16 v[28:31], v[76:79], v[44:47], v[28:31]
	v_mfma_f32_16x16x32_bf16 v[24:27], v[84:87], v[44:47], v[24:27]
	v_mfma_f32_16x16x32_bf16 v[20:23], v[76:79], v[52:55], v[20:23]
	v_mfma_f32_16x16x32_bf16 v[16:19], v[84:87], v[52:55], v[16:19]
	ds_read_b128 v[34:37], v32
	ds_read_b128 v[44:47], v32 offset:1024
	ds_read_b128 v[48:51], v32 offset:2048
	ds_read_b128 v[52:55], v32 offset:3072
	v_mfma_f32_16x16x32_bf16 v[12:15], v[76:79], v[60:63], v[12:15]
	v_mfma_f32_16x16x32_bf16 v[8:11], v[84:87], v[60:63], v[8:11]
	v_mfma_f32_16x16x32_bf16 v[0:3], v[76:79], v[68:71], v[0:3]
	ds_read_b128 v[56:59], v32 offset:4096
	ds_read_b128 v[60:63], v32 offset:5120
	ds_read_b128 v[72:75], v32 offset:6144
	ds_read_b128 v[76:79], v32 offset:7168
	v_add_u32_e32 v32, s46, v41
	ds_read_b128 v[64:67], v32 offset:16384
	ds_read_b128 v[80:83], v32 offset:17408
	v_mfma_f32_16x16x32_bf16 v[4:7], v[84:87], v[68:71], v[4:7]
	ds_read_b128 v[68:71], v32 offset:18432
	ds_read_b128 v[84:87], v32 offset:19456
	s_waitcnt lgkmcnt(0)
	s_waitcnt lgkmcnt(0)
	v_mfma_f32_16x16x32_bf16 v[28:31], v[64:67], v[34:37], v[28:31]
	s_add_i32 s44, s44, 0x10000
	s_add_i32 s45, s45, 2
	s_cmp_eq_u32 s45, 32
	v_mfma_f32_16x16x32_bf16 v[24:27], v[68:71], v[34:37], v[24:27]
	v_mfma_f32_16x16x32_bf16 v[20:23], v[64:67], v[48:51], v[20:23]
	v_mfma_f32_16x16x32_bf16 v[16:19], v[68:71], v[48:51], v[16:19]
	v_mfma_f32_16x16x32_bf16 v[12:15], v[64:67], v[56:59], v[12:15]
	v_mfma_f32_16x16x32_bf16 v[8:11], v[68:71], v[56:59], v[8:11]
	v_mfma_f32_16x16x32_bf16 v[0:3], v[64:67], v[72:75], v[0:3]
	v_mfma_f32_16x16x32_bf16 v[4:7], v[68:71], v[72:75], v[4:7]
	v_mfma_f32_16x16x32_bf16 v[28:31], v[80:83], v[44:47], v[28:31]
	v_mfma_f32_16x16x32_bf16 v[24:27], v[84:87], v[44:47], v[24:27]
	v_mfma_f32_16x16x32_bf16 v[20:23], v[80:83], v[52:55], v[20:23]
	v_mfma_f32_16x16x32_bf16 v[16:19], v[84:87], v[52:55], v[16:19]
	v_mfma_f32_16x16x32_bf16 v[12:15], v[80:83], v[60:63], v[12:15]
	v_mfma_f32_16x16x32_bf16 v[8:11], v[84:87], v[60:63], v[8:11]
	v_mfma_f32_16x16x32_bf16 v[0:3], v[80:83], v[76:79], v[0:3]
	v_mfma_f32_16x16x32_bf16 v[4:7], v[84:87], v[76:79], v[4:7]
	s_cbranch_scc0 .LBB0_1103
	v_add_u32_e32 v34, s43, v39
	v_mov_b32_e32 v35, v33
	v_lshl_add_u64 v[36:37], v[34:35], 2, s[92:93]
	s_waitcnt vmcnt(0)
	s_barrier
; __device__ __forceinline__ unsigned cvtpk(float lo, float hi) { unsigned r; asm volatile("v_cvt_pk_bf16_f32 %0, %1, %2" : "=v"(r) : "v"(lo), "v"(hi)); return r; }
; __device__ __forceinline__ float silu_fast(float g) { return g * __builtin_amdgcn_rcpf(1.f + __builtin_amdgcn_exp2f(-g * LOG2E)); }
;     __device__ __forceinline__ void quad(const f32x4 (&a)[4][2], int rowq, int colq, int wr, int wc, int fr, int fq) const {
;         const int row0 = rowq + wr * 64 + fr, col0 = colq + wc * 32 + 8 * fq;
;         if (colq < 2 * CW) {
; #pragma unroll
;             for (int m = 0; m < 4; ++m) { const int row = row0 + m * 16; const float rs = rsqrtf(ssq1[row] * (1.f / DM) + RMS_EPS);
;                 const f32x4 uu = a[m][0] * rs, zz = a[m][1] * rs; u32x2 w;
;                 w.x = cvtpk(uu[0] * silu_fast(zz[0]), uu[1] * silu_fast(zz[1])); w.y = cvtpk(uu[2] * silu_fast(zz[2]), uu[3] * silu_fast(zz[3]));
;                 const int cu = col0 >> 1; *(u32x2*)(UZV + ((size_t)(cu >> 8) * MT + row) * 256 + (cu & 255)) = w; }
;         } else {
; #pragma unroll
;             for (int m = 0; m < 4; ++m) { const int row = row0 + m * 16; const float rs = rsqrtf(ssq1[row] * (1.f / DM) + RMS_EPS);
;                 const f32x4 v0 = a[m][0] * rs, v1 = a[m][1] * rs;
;                 u32x4 w; w.x = cvtpk(v0[0], v0[1]); w.y = cvtpk(v0[2], v0[3]); w.z = cvtpk(v1[0], v1[1]); w.w = cvtpk(v1[2], v1[3]);
;                 const int cv = col0 - 2 * CW; *(u32x4*)(UZV + (size_t)MT * CW + ((size_t)(cv >> 8) * MT + row) * 256 + (cv & 255)) = w;
;                 float s = ((v0[0] + v0[1]) + (v0[2] + v0[3])) + ((v1[0] + v1[1]) + (v1[2] + v1[3]));
;                 float q = ((v0[0] * v0[0] + v0[1] * v0[1]) + (v0[2] * v0[2] + v0[3] * v0[3])) + ((v1[0] * v1[0] + v1[1] * v1[1]) + (v1[2] * v1[2] + v1[3] * v1[3]));
;                 s += __shfl_xor(s, 16); s += __shfl_xor(s, 32); q += __shfl_xor(q, 16); q += __shfl_xor(q, 32);
;                 if (fq == 0) { unsafeAtomicAdd(vsum + row, s); unsafeAtomicAdd(vsq + row, q); } }
	global_load_dword v32, v[36:37], off
	global_load_dword v240, v[36:37], off offset:64
	global_load_dword v241, v[36:37], off offset:128
	global_load_dword v242, v[36:37], off offset:192
	s_lshl_b32 s18, s37, 7
	v_or_b32_e32 v44, s18, v38
	s_cmp_lt_u32 s42, 64
	s_mov_b64 s[16:17], -1
	s_waitcnt vmcnt(0)
	v_fmamk_f32 v32, v32, 0x3a000000, v42
	v_mul_f32_e32 v36, 0x4b800000, v32
	v_cmp_gt_f32_e32 vcc, s36, v32
	s_nop 1
	v_cndmask_b32_e32 v32, v32, v36, vcc
	v_rsq_f32_e32 v32, v32
	s_nop 0
	v_mul_f32_e32 v36, 0x45800000, v32
	v_cndmask_b32_e32 v32, v32, v36, vcc
	v_pk_mul_f32 v[30:31], v[30:31], v[32:33] op_sel_hi:[1,0]
	v_pk_mul_f32 v[28:29], v[28:29], v[32:33] op_sel_hi:[1,0]
	v_pk_mul_f32 v[26:27], v[26:27], v[32:33] op_sel_hi:[1,0]
	v_pk_mul_f32 v[24:25], v[24:25], v[32:33] op_sel_hi:[1,0]
	s_cbranch_scc1 .LBB0_1114
	s_addk_i32 s18, 0xe000
	s_lshr_b32 s16, s18, 8
	s_mulk_i32 s16, 0x2200
	s_ashr_i32 s17, s16, 31
	v_lshl_add_u64 v[36:37], s[16:17], 0, v[34:35]
	v_lshlrev_b64 v[36:37], 9, v[36:37]
	v_lshl_add_u64 v[54:55], s[2:3], 0, v[36:37]
	v_add_f32_e32 v32, v28, v29
	v_add_f32_e32 v36, v30, v31
	v_add_f32_e32 v32, v32, v36
	v_add_f32_e32 v36, v24, v25
	v_add_f32_e32 v37, v26, v27
	v_add_f32_e32 v36, v36, v37
	v_add_f32_e32 v32, v32, v36
	v_mul_f32_e32 v36, v29, v29
	v_mul_f32_e32 v37, v31, v31
	v_fmac_f32_e32 v36, v28, v28
	v_fmac_f32_e32 v37, v30, v30
	v_and_b32_e32 v46, 64, v43
	v_add_f32_e32 v36, v36, v37
	v_mul_f32_e32 v37, v25, v25
	v_xor_b32_e32 v45, 16, v43
	v_add_u32_e32 v46, 64, v46
	v_mul_f32_e32 v48, v27, v27
	v_fmac_f32_e32 v37, v24, v24
	v_cmp_lt_i32_e32 vcc, v45, v46
	v_fmac_f32_e32 v48, v26, v26
	v_add_f32_e32 v37, v37, v48
	v_cndmask_b32_e32 v45, v43, v45, vcc
	v_lshlrev_b32_e32 v45, 2, v45
	v_add_f32_e32 v36, v36, v37
	ds_bpermute_b32 v47, v45, v32
	ds_bpermute_b32 v48, v45, v36
	v_xor_b32_e32 v37, 32, v43
	v_cmp_lt_i32_e32 vcc, v37, v46
	v_and_b32_e32 v56, 0xf8, v44
	s_waitcnt lgkmcnt(1)
	v_add_f32_e32 v32, v32, v47
	v_cndmask_b32_e32 v37, v43, v37, vcc
	v_lshlrev_b32_e32 v46, 2, v37
	s_waitcnt lgkmcnt(0)
	v_add_f32_e32 v48, v36, v48
	ds_bpermute_b32 v47, v46, v32
	ds_bpermute_b32 v49, v46, v48
	v_lshlrev_b32_e32 v36, 1, v56
	v_mov_b32_e32 v37, v33
	v_lshl_add_u64 v[54:55], v[54:55], 0, v[36:37]
	v_cvt_pk_bf16_f32 v50, v28, v29
	v_cvt_pk_bf16_f32 v51, v30, v31
	v_cvt_pk_bf16_f32 v52, v24, v25
	v_cvt_pk_bf16_f32 v53, v26, v27
	global_store_dwordx4 v[54:55], v[50:53], off
	s_and_saveexec_b64 s[18:19], s[0:1]
	s_cbranch_execz .LBB0_1107
	v_lshlrev_b64 v[50:51], 2, v[34:35]
	v_lshl_add_u64 v[52:53], s[10:11], 0, v[50:51]
	v_lshl_add_u64 v[50:51], s[8:9], 0, v[50:51]
	s_waitcnt lgkmcnt(1)
	v_add_f32_e32 v32, v32, v47
	s_waitcnt lgkmcnt(0)
	v_add_f32_e32 v35, v48, v49
	global_atomic_add_f32 v[50:51], v32, off
	global_atomic_add_f32 v[52:53], v35, off
.LBB0_1107:
	s_or_b64 exec, exec, s[18:19]
	v_or_b32_e32 v32, 16, v34
	s_waitcnt lgkmcnt(0)
	v_lshl_add_u64 v[48:49], v[32:33], 2, s[92:93]
	v_lshl_add_u64 v[54:55], s[16:17], 0, v[32:33]
	v_lshlrev_b64 v[54:55], 9, v[54:55]
	v_lshl_add_u64 v[54:55], s[2:3], 0, v[54:55]
	v_lshl_add_u64 v[54:55], v[54:55], 0, v[36:37]
	v_mov_b32_e32 v35, v240
	v_fmamk_f32 v35, v35, 0x3a000000, v42
	v_mul_f32_e32 v47, 0x4b800000, v35
	v_cmp_gt_f32_e32 vcc, s36, v35
	s_nop 1
	v_cndmask_b32_e32 v35, v35, v47, vcc
	v_rsq_f32_e32 v35, v35
	s_nop 0
	v_mul_f32_e32 v47, 0x45800000, v35
	v_cndmask_b32_e32 v48, v35, v47, vcc
	v_pk_mul_f32 v[52:53], v[22:23], v[48:49] op_sel_hi:[1,0]
	v_pk_mul_f32 v[56:57], v[20:21], v[48:49] op_sel_hi:[1,0]
	v_pk_mul_f32 v[58:59], v[18:19], v[48:49] op_sel_hi:[1,0]
	v_pk_mul_f32 v[48:49], v[16:17], v[48:49] op_sel_hi:[1,0]
	v_cvt_pk_bf16_f32 v50, v56, v57
	v_cvt_pk_bf16_f32 v51, v52, v53
	v_add_f32_e32 v35, v56, v57
	v_add_f32_e32 v47, v52, v53
	v_add_f32_e32 v60, v48, v49
	v_add_f32_e32 v61, v58, v59
	v_mul_f32_e32 v57, v57, v57
	v_mul_f32_e32 v53, v53, v53
	v_mul_f32_e32 v62, v49, v49
	v_mul_f32_e32 v63, v59, v59
	v_add_f32_e32 v35, v35, v47
	v_add_f32_e32 v47, v60, v61
	v_fmac_f32_e32 v57, v56, v56
	v_fmac_f32_e32 v53, v52, v52
	v_fmac_f32_e32 v62, v48, v48
	v_fmac_f32_e32 v63, v58, v58
	v_add_f32_e32 v35, v35, v47
	v_add_f32_e32 v47, v57, v53
	v_add_f32_e32 v52, v62, v63
	v_add_f32_e32 v57, v47, v52
	ds_bpermute_b32 v56, v45, v35
	ds_bpermute_b32 v60, v45, v57
	v_cvt_pk_bf16_f32 v52, v48, v49
	v_cvt_pk_bf16_f32 v53, v58, v59
	global_store_dwordx4 v[54:55], v[50:53], off
	s_waitcnt lgkmcnt(1)
	v_add_f32_e32 v35, v35, v56
	s_waitcnt lgkmcnt(0)
	v_add_f32_e32 v48, v57, v60
	ds_bpermute_b32 v47, v46, v35
	ds_bpermute_b32 v49, v46, v48
	s_and_saveexec_b64 s[18:19], s[0:1]
	s_cbranch_execz .LBB0_1109
	v_lshlrev_b64 v[50:51], 2, v[32:33]
	v_lshl_add_u64 v[52:53], s[10:11], 0, v[50:51]
	v_lshl_add_u64 v[50:51], s[8:9], 0, v[50:51]
	s_waitcnt lgkmcnt(1)
	v_add_f32_e32 v32, v35, v47
	s_waitcnt lgkmcnt(0)
	v_add_f32_e32 v35, v48, v49
	global_atomic_add_f32 v[50:51], v32, off
	global_atomic_add_f32 v[52:53], v35, off
; __device__ __forceinline__ unsigned cvtpk(float lo, float hi) { unsigned r; asm volatile("v_cvt_pk_bf16_f32 %0, %1, %2" : "=v"(r) : "v"(lo), "v"(hi)); return r; }
;     __device__ __forceinline__ void quad(const f32x4 (&a)[4][2], int rowq, int colq, int wr, int wc, int fr, int fq) const {
;     ...
;             for (int m = 0; m < 4; ++m) { const int row = row0 + m * 16; const float rs = rsqrtf(ssq1[row] * (1.f / DM) + RMS_EPS);
;                 const f32x4 v0 = a[m][0] * rs, v1 = a[m][1] * rs;
;                 u32x4 w; w.x = cvtpk(v0[0], v0[1]); w.y = cvtpk(v0[2], v0[3]); w.z = cvtpk(v1[0], v1[1]); w.w = cvtpk(v1[2], v1[3]);
;                 const int cv = col0 - 2 * CW; *(u32x4*)(UZV + (size_t)MT * CW + ((size_t)(cv >> 8) * MT + row) * 256 + (cv & 255)) = w;
;                 float s = ((v0[0] + v0[1]) + (v0[2] + v0[3])) + ((v1[0] + v1[1]) + (v1[2] + v1[3]));
;                 float q = ((v0[0] * v0[0] + v0[1] * v0[1]) + (v0[2] * v0[2] + v0[3] * v0[3])) + ((v1[0] * v1[0] + v1[1] * v1[1]) + (v1[2] * v1[2] + v1[3] * v1[3]));
;                 s += __shfl_xor(s, 16); s += __shfl_xor(s, 32); q += __shfl_xor(q, 16); q += __shfl_xor(q, 32);
;                 if (fq == 0) { unsafeAtomicAdd(vsum + row, s); unsafeAtomicAdd(vsq + row, q); } }
.LBB0_1109:
	s_or_b64 exec, exec, s[18:19]
	v_or_b32_e32 v32, 32, v34
	s_waitcnt lgkmcnt(0)
	v_lshl_add_u64 v[48:49], v[32:33], 2, s[92:93]
	v_lshl_add_u64 v[48:49], s[16:17], 0, v[32:33]
	v_lshlrev_b64 v[54:55], 9, v[48:49]
	v_lshl_add_u64 v[54:55], s[2:3], 0, v[54:55]
	v_mov_b32_e32 v35, v241
	v_fmamk_f32 v35, v35, 0x3a000000, v42
	v_mul_f32_e32 v37, 0x4b800000, v35
	v_cmp_gt_f32_e32 vcc, s36, v35
	s_nop 1
	v_cndmask_b32_e32 v35, v35, v37, vcc
	v_rsq_f32_e32 v35, v35
	s_nop 0
	v_mul_f32_e32 v37, 0x45800000, v35
	v_cndmask_b32_e32 v48, v35, v37, vcc
	v_pk_mul_f32 v[52:53], v[14:15], v[48:49] op_sel_hi:[1,0]
	v_pk_mul_f32 v[56:57], v[12:13], v[48:49] op_sel_hi:[1,0]
	v_pk_mul_f32 v[58:59], v[10:11], v[48:49] op_sel_hi:[1,0]
	v_pk_mul_f32 v[48:49], v[8:9], v[48:49] op_sel_hi:[1,0]
	v_cvt_pk_bf16_f32 v50, v56, v57
	v_cvt_pk_bf16_f32 v51, v52, v53
	v_add_f32_e32 v35, v56, v57
	v_add_f32_e32 v37, v52, v53
	v_add_f32_e32 v47, v48, v49
	v_add_f32_e32 v60, v58, v59
	v_mul_f32_e32 v57, v57, v57
	v_mul_f32_e32 v53, v53, v53
	v_mul_f32_e32 v61, v49, v49
	v_mul_f32_e32 v62, v59, v59
	v_add_f32_e32 v35, v35, v37
	v_add_f32_e32 v37, v47, v60
	v_fmac_f32_e32 v57, v56, v56
	v_fmac_f32_e32 v53, v52, v52
	v_fmac_f32_e32 v61, v48, v48
	v_fmac_f32_e32 v62, v58, v58
	v_add_f32_e32 v35, v35, v37
	v_add_f32_e32 v37, v57, v53
	v_add_f32_e32 v47, v61, v62
	v_add_f32_e32 v37, v37, v47
	ds_bpermute_b32 v56, v45, v35
	ds_bpermute_b32 v57, v45, v37
	v_cvt_pk_bf16_f32 v52, v48, v49
	v_cvt_pk_bf16_f32 v53, v58, v59
	s_waitcnt lgkmcnt(1)
	v_add_f32_e32 v35, v35, v56
	s_waitcnt lgkmcnt(0)
	v_add_f32_e32 v48, v37, v57
	ds_bpermute_b32 v47, v46, v35
	ds_bpermute_b32 v49, v46, v48
	v_mov_b32_e32 v37, v33
	v_lshl_add_u64 v[54:55], v[54:55], 0, v[36:37]
	global_store_dwordx4 v[54:55], v[50:53], off
	s_and_saveexec_b64 s[18:19], s[0:1]
	s_cbranch_execz .LBB0_1111
	v_lshlrev_b64 v[50:51], 2, v[32:33]
	v_lshl_add_u64 v[52:53], s[10:11], 0, v[50:51]
	v_lshl_add_u64 v[50:51], s[8:9], 0, v[50:51]
	s_waitcnt lgkmcnt(1)
	v_add_f32_e32 v32, v35, v47
	s_waitcnt lgkmcnt(0)
	v_add_f32_e32 v35, v48, v49
	global_atomic_add_f32 v[50:51], v32, off
	global_atomic_add_f32 v[52:53], v35, off
.LBB0_1111:
	s_or_b64 exec, exec, s[18:19]
	v_or_b32_e32 v32, 48, v34
	s_waitcnt lgkmcnt(0)
	v_lshl_add_u64 v[48:49], v[32:33], 2, s[92:93]
	v_lshl_add_u64 v[52:53], s[16:17], 0, v[32:33]
	v_lshlrev_b64 v[52:53], 9, v[52:53]
	v_lshl_add_u64 v[52:53], s[2:3], 0, v[52:53]
	v_lshl_add_u64 v[36:37], v[52:53], 0, v[36:37]
	v_mov_b32_e32 v35, v242
	v_fmamk_f32 v35, v35, 0x3a000000, v42
	v_mul_f32_e32 v47, 0x4b800000, v35
	v_cmp_gt_f32_e32 vcc, s36, v35
	s_nop 1
	v_cndmask_b32_e32 v35, v35, v47, vcc
	v_rsq_f32_e32 v35, v35
	s_nop 0
	v_mul_f32_e32 v47, 0x45800000, v35
	v_cndmask_b32_e32 v48, v35, v47, vcc
	v_pk_mul_f32 v[50:51], v[2:3], v[48:49] op_sel_hi:[1,0]
	v_pk_mul_f32 v[54:55], v[0:1], v[48:49] op_sel_hi:[1,0]
	v_pk_mul_f32 v[56:57], v[6:7], v[48:49] op_sel_hi:[1,0]
	v_pk_mul_f32 v[58:59], v[4:5], v[48:49] op_sel_hi:[1,0]
	v_cvt_pk_bf16_f32 v48, v54, v55
	v_cvt_pk_bf16_f32 v49, v50, v51
	v_add_f32_e32 v35, v54, v55
	v_add_f32_e32 v47, v50, v51
	v_add_f32_e32 v60, v58, v59
	v_add_f32_e32 v61, v56, v57
	v_mul_f32_e32 v55, v55, v55
	v_mul_f32_e32 v51, v51, v51
	v_mul_f32_e32 v62, v59, v59
	v_mul_f32_e32 v63, v57, v57
	v_add_f32_e32 v35, v35, v47
	v_add_f32_e32 v47, v60, v61
	v_fmac_f32_e32 v55, v54, v54
	v_fmac_f32_e32 v51, v50, v50
	v_fmac_f32_e32 v62, v58, v58
	v_fmac_f32_e32 v63, v56, v56
	v_add_f32_e32 v35, v35, v47
	v_add_f32_e32 v47, v55, v51
	v_add_f32_e32 v50, v62, v63
	v_add_f32_e32 v47, v47, v50
	ds_bpermute_b32 v54, v45, v35
	ds_bpermute_b32 v55, v45, v47
	v_cvt_pk_bf16_f32 v50, v58, v59
	v_cvt_pk_bf16_f32 v51, v56, v57
	global_store_dwordx4 v[36:37], v[48:51], off
	s_waitcnt lgkmcnt(1)
	v_add_f32_e32 v35, v35, v54
	s_waitcnt lgkmcnt(0)
	v_add_f32_e32 v47, v47, v55
	ds_bpermute_b32 v45, v46, v35
	ds_bpermute_b32 v46, v46, v47
	s_and_saveexec_b64 s[16:17], s[0:1]
	s_cbranch_execz .LBB0_1113
	v_lshlrev_b64 v[36:37], 2, v[32:33]
	v_lshl_add_u64 v[48:49], s[10:11], 0, v[36:37]
	v_lshl_add_u64 v[36:37], s[8:9], 0, v[36:37]
	s_waitcnt lgkmcnt(1)
	v_add_f32_e32 v32, v35, v45
	s_waitcnt lgkmcnt(0)
	v_add_f32_e32 v35, v47, v46
	global_atomic_add_f32 v[36:37], v32, off
	global_atomic_add_f32 v[48:49], v35, off

; __device__ __forceinline__ unsigned cvtpk(float lo, float hi) { unsigned r; asm volatile("v_cvt_pk_bf16_f32 %0, %1, %2" : "=v"(r) : "v"(lo), "v"(hi)); return r; }
; __device__ __forceinline__ float silu_fast(float g) { return g * __builtin_amdgcn_rcpf(1.f + __builtin_amdgcn_exp2f(-g * LOG2E)); }
;     __device__ __forceinline__ void quad(const f32x4 (&a)[4][2], int rowq, int colq, int wr, int wc, int fr, int fq) const {
;     ...
;         if (colq < 2 * CW) {
; #pragma unroll
;             for (int m = 0; m < 4; ++m) { const int row = row0 + m * 16; const float rs = rsqrtf(ssq1[row] * (1.f / DM) + RMS_EPS);
;                 const f32x4 uu = a[m][0] * rs, zz = a[m][1] * rs; u32x2 w;
;                 w.x = cvtpk(uu[0] * silu_fast(zz[0]), uu[1] * silu_fast(zz[1])); w.y = cvtpk(uu[2] * silu_fast(zz[2]), uu[3] * silu_fast(zz[3]));
;                 const int cu = col0 >> 1; *(u32x2*)(UZV + ((size_t)(cu >> 8) * MT + row) * 256 + (cu & 255)) = w; }
.LBB0_1114:
	s_and_b64 vcc, exec, s[16:17]
	s_cbranch_vccz .LBB0_1101
	v_mul_f32_e32 v32, 0xbfb8aa3b, v24
	v_exp_f32_e32 v32, v32
	v_mul_f32_e32 v35, 0xbfb8aa3b, v25
	v_exp_f32_e32 v35, v35
	s_lshr_b32 s16, s37, 2
	v_add_f32_e32 v32, 1.0, v32
	v_rcp_f32_e32 v32, v32
	v_add_f32_e32 v35, 1.0, v35
	v_rcp_f32_e32 v35, v35
	s_mulk_i32 s16, 0x2200
	v_mul_f32_e32 v24, v24, v32
	v_mul_f32_e32 v24, v28, v24
	v_mul_f32_e32 v28, 0xbfb8aa3b, v26
	v_mul_f32_e32 v32, 0xbfb8aa3b, v27
	v_exp_f32_e32 v28, v28
	v_exp_f32_e32 v32, v32
	v_mul_f32_e32 v25, v25, v35
	v_mul_f32_e32 v25, v29, v25
	v_add_f32_e32 v28, 1.0, v28
	v_add_f32_e32 v29, 1.0, v32
	v_rcp_f32_e32 v28, v28
	v_rcp_f32_e32 v29, v29
	v_cvt_pk_bf16_f32 v24, v24, v25
	v_add_u32_e32 v32, s16, v34
	v_mul_f32_e32 v25, v26, v28
	v_mul_f32_e32 v26, v27, v29
	v_mul_f32_e32 v25, v30, v25
	v_mul_f32_e32 v26, v31, v26
	v_cvt_pk_bf16_f32 v25, v25, v26
	v_lshlrev_b64 v[26:27], 9, v[32:33]
	v_lshl_add_u64 v[26:27], s[6:7], 0, v[26:27]
	v_and_b32_e32 v32, 0x1f8, v44
	v_lshl_add_u64 v[26:27], v[26:27], 0, v[32:33]
	global_store_dwordx2 v[26:27], v[24:25], off
	v_or_b32_e32 v24, 16, v34
	v_mov_b32_e32 v25, v33
	v_lshl_add_u64 v[26:27], v[24:25], 2, s[92:93]
	v_or_b32_e32 v26, 32, v34
	v_mov_b32_e32 v27, v33
	v_lshl_add_u64 v[28:29], v[26:27], 2, s[92:93]
	v_add_u32_e32 v24, s16, v24
	v_lshlrev_b64 v[24:25], 9, v[24:25]
	v_lshl_add_u64 v[24:25], s[6:7], 0, v[24:25]
	v_lshl_add_u64 v[24:25], v[24:25], 0, v[32:33]
	v_mov_b32_e32 v30, v240
	v_fmamk_f32 v27, v30, 0x3a000000, v42
	v_mul_f32_e32 v30, 0x4b800000, v27
	v_cmp_gt_f32_e32 vcc, s36, v27
	s_nop 1
	v_cndmask_b32_e32 v27, v27, v30, vcc
	v_rsq_f32_e32 v27, v27
	s_nop 0
	v_mul_f32_e32 v30, 0x45800000, v27
	v_cndmask_b32_e32 v30, v27, v30, vcc
	v_pk_mul_f32 v[16:17], v[16:17], v[30:31] op_sel_hi:[1,0]
	v_pk_mul_f32 v[22:23], v[22:23], v[30:31] op_sel_hi:[1,0]
	v_pk_mul_f32 v[20:21], v[20:21], v[30:31] op_sel_hi:[1,0]
	v_pk_mul_f32 v[18:19], v[18:19], v[30:31] op_sel_hi:[1,0]
	v_mul_f32_e32 v27, 0xbfb8aa3b, v16
	v_mul_f32_e32 v30, 0xbfb8aa3b, v17
	v_mul_f32_e32 v31, 0xbfb8aa3b, v18
	v_mul_f32_e32 v35, 0xbfb8aa3b, v19
	v_exp_f32_e32 v27, v27
	v_exp_f32_e32 v30, v30
	v_exp_f32_e32 v31, v31
	v_exp_f32_e32 v35, v35
	v_add_f32_e32 v27, 1.0, v27
	v_add_f32_e32 v30, 1.0, v30
	v_add_f32_e32 v31, 1.0, v31
	v_add_f32_e32 v35, 1.0, v35
	v_rcp_f32_e32 v27, v27
	v_rcp_f32_e32 v30, v30
	v_rcp_f32_e32 v31, v31
	v_rcp_f32_e32 v35, v35
	v_mul_f32_e32 v16, v16, v27
	v_mul_f32_e32 v17, v17, v30
	v_mul_f32_e32 v18, v18, v31
	v_mul_f32_e32 v19, v19, v35
	v_mul_f32_e32 v16, v20, v16
	v_mul_f32_e32 v17, v21, v17
	v_mul_f32_e32 v18, v22, v18
	v_mul_f32_e32 v19, v23, v19
	v_cvt_pk_bf16_f32 v16, v16, v17
	v_cvt_pk_bf16_f32 v17, v18, v19
	global_store_dwordx2 v[24:25], v[16:17], off
	v_or_b32_e32 v18, 48, v34
	v_mov_b32_e32 v19, v33
	v_lshl_add_u64 v[20:21], v[18:19], 2, s[92:93]
	v_mov_b32_e32 v17, v33
	v_add_u32_e32 v16, s16, v26
	v_lshlrev_b64 v[16:17], 9, v[16:17]
	v_lshl_add_u64 v[16:17], s[6:7], 0, v[16:17]
	v_lshl_add_u64 v[16:17], v[16:17], 0, v[32:33]
	v_mov_b32_e32 v22, v241
	v_fmamk_f32 v19, v22, 0x3a000000, v42
	v_mul_f32_e32 v22, 0x4b800000, v19
	v_cmp_gt_f32_e32 vcc, s36, v19
	s_nop 1
	v_cndmask_b32_e32 v19, v19, v22, vcc
	v_rsq_f32_e32 v19, v19
	s_nop 0
	v_mul_f32_e32 v22, 0x45800000, v19
	v_cndmask_b32_e32 v22, v19, v22, vcc
	v_pk_mul_f32 v[8:9], v[8:9], v[22:23] op_sel_hi:[1,0]
	v_pk_mul_f32 v[14:15], v[14:15], v[22:23] op_sel_hi:[1,0]
	v_pk_mul_f32 v[12:13], v[12:13], v[22:23] op_sel_hi:[1,0]
	v_pk_mul_f32 v[10:11], v[10:11], v[22:23] op_sel_hi:[1,0]
	v_mul_f32_e32 v19, 0xbfb8aa3b, v8
	v_mul_f32_e32 v22, 0xbfb8aa3b, v9
	v_mul_f32_e32 v23, 0xbfb8aa3b, v10
	v_mul_f32_e32 v24, 0xbfb8aa3b, v11
	v_exp_f32_e32 v19, v19
	v_exp_f32_e32 v22, v22
	v_exp_f32_e32 v23, v23
	v_exp_f32_e32 v24, v24
	v_add_f32_e32 v19, 1.0, v19
	v_add_f32_e32 v22, 1.0, v22
	v_add_f32_e32 v23, 1.0, v23
	v_add_f32_e32 v24, 1.0, v24
	v_rcp_f32_e32 v19, v19
	v_rcp_f32_e32 v22, v22
	v_rcp_f32_e32 v23, v23
	v_rcp_f32_e32 v24, v24
	v_mul_f32_e32 v8, v8, v19
	v_mul_f32_e32 v9, v9, v22
	v_mul_f32_e32 v10, v10, v23
	v_mul_f32_e32 v11, v11, v24
	v_mul_f32_e32 v8, v12, v8
	v_mul_f32_e32 v9, v13, v9
	v_mul_f32_e32 v10, v14, v10
	v_mul_f32_e32 v11, v15, v11
	v_cvt_pk_bf16_f32 v8, v8, v9
	v_cvt_pk_bf16_f32 v9, v10, v11
	global_store_dwordx2 v[16:17], v[8:9], off
	v_mov_b32_e32 v9, v33
	v_mov_b32_e32 v8, v242
	v_fmamk_f32 v8, v8, 0x3a000000, v42
	v_mul_f32_e32 v10, 0x4b800000, v8
	v_cmp_gt_f32_e32 vcc, s36, v8
	s_nop 1
	v_cndmask_b32_e32 v8, v8, v10, vcc
	v_rsq_f32_e32 v10, v8
	v_add_u32_e32 v8, s16, v18
	v_lshlrev_b64 v[8:9], 9, v[8:9]
	v_lshl_add_u64 v[8:9], s[6:7], 0, v[8:9]
	v_mul_f32_e32 v11, 0x45800000, v10
	v_cndmask_b32_e32 v10, v10, v11, vcc
	v_pk_mul_f32 v[6:7], v[6:7], v[10:11] op_sel_hi:[1,0]
	v_pk_mul_f32 v[4:5], v[4:5], v[10:11] op_sel_hi:[1,0]
	v_pk_mul_f32 v[2:3], v[2:3], v[10:11] op_sel_hi:[1,0]
	v_pk_mul_f32 v[0:1], v[0:1], v[10:11] op_sel_hi:[1,0]
	v_mul_f32_e32 v10, 0xbfb8aa3b, v4
	v_mul_f32_e32 v11, 0xbfb8aa3b, v5
	v_mul_f32_e32 v12, 0xbfb8aa3b, v6
	v_mul_f32_e32 v13, 0xbfb8aa3b, v7
	v_exp_f32_e32 v10, v10
	v_exp_f32_e32 v11, v11
	v_exp_f32_e32 v12, v12
	v_exp_f32_e32 v13, v13
	v_add_f32_e32 v10, 1.0, v10
	v_add_f32_e32 v11, 1.0, v11
	v_add_f32_e32 v12, 1.0, v12
	v_add_f32_e32 v13, 1.0, v13
	v_rcp_f32_e32 v10, v10
	v_rcp_f32_e32 v11, v11
	v_rcp_f32_e32 v12, v12
	v_rcp_f32_e32 v13, v13
	v_mul_f32_e32 v4, v4, v10
	v_mul_f32_e32 v5, v5, v11
	v_mul_f32_e32 v6, v6, v12
	v_mul_f32_e32 v7, v7, v13
	v_mul_f32_e32 v0, v0, v4
	v_mul_f32_e32 v1, v1, v5
	v_mul_f32_e32 v2, v2, v6
	v_mul_f32_e32 v3, v3, v7
	v_cvt_pk_bf16_f32 v0, v0, v1
	v_cvt_pk_bf16_f32 v1, v2, v3
	v_lshl_add_u64 v[2:3], v[8:9], 0, v[32:33]
	global_store_dwordx2 v[2:3], v[0:1], off
	s_branch .LBB0_1101

; __device__ __forceinline__ bf16x8 tobf8(f32x8 x) { u32x4 w = {cvtpk(x[0], x[1]), cvtpk(x[2], x[3]), cvtpk(x[4], x[5]), cvtpk(x[6], x[7])}; return *reinterpret_cast<bf16x8*>(&w); }
; __device__ __forceinline__ void spatial_phase(const Params& p, char* lds) {
;     ...
;         if (g != g_loaded) { g_loaded = g;
; #pragma unroll
;             for (int st_ = 0; st_ < 2; ++st_)
; #pragma unroll
;                 for (int ks = 0; ks < 4; ++ks) { const int s0 = 64 * st_ + 16 * ks + 8 * hi; const float* wp = p.w_sp + ((size_t)g * CCH + t) * CCH + s0;
;                     const f32x4 a = *(const f32x4*)wp, c = *(const f32x4*)(wp + 4); f32x8 y;
; #pragma unroll
;                     for (int i = 0; i < 4; ++i) { y[i] = (s0 + i <= t) ? a[i] : 0.f; y[4 + i] = (s0 + 4 + i <= t) ? c[i] : 0.f; }
;                     pa[st_][ks] = tobf8(y); }
.LBB0_1200:
	s_and_b32 s42, s79, 15
	s_cmp_eq_u32 s42, s33
	s_cbranch_scc1 .LBB0_1202
	v_lshl_or_b32 v0, s42, 16, v209
	v_mov_b32_e32 v1, v96
	v_lshl_add_u64 v[0:1], v[224:225], 0, v[0:1]
	global_load_dwordx4 v[24:27], v[0:1], off
	global_load_dwordx4 v[28:31], v[0:1], off offset:16
	global_load_dwordx4 v[32:35], v[0:1], off offset:64
	global_load_dwordx4 v[36:39], v[0:1], off offset:80
	global_load_dwordx4 v[40:43], v[0:1], off offset:128
	global_load_dwordx4 v[44:47], v[0:1], off offset:144
	global_load_dwordx4 v[48:51], v[0:1], off offset:192
	global_load_dwordx4 v[52:55], v[0:1], off offset:208
	global_load_dwordx4 v[56:59], v[0:1], off offset:256
	global_load_dwordx4 v[60:63], v[0:1], off offset:272
	global_load_dwordx4 v[100:103], v[0:1], off offset:320
	global_load_dwordx4 v[104:107], v[0:1], off offset:336
	global_load_dwordx4 v[108:111], v[0:1], off offset:384
	global_load_dwordx4 v[112:115], v[0:1], off offset:400
	global_load_dwordx4 v[116:119], v[0:1], off offset:448
	global_load_dwordx4 v[120:123], v[0:1], off offset:464
	s_waitcnt vmcnt(0)
	v_readlane_b32 s38, v253, 16
	v_readlane_b32 s39, v253, 17
	v_readlane_b32 s52, v253, 0
	v_readlane_b32 s53, v253, 1
	s_mov_b32 s33, s42
	v_readlane_b32 s54, v253, 2
	v_readlane_b32 s55, v253, 3
	v_readlane_b32 s56, v253, 4
	v_readlane_b32 s57, v253, 5
	v_readlane_b32 s58, v253, 6
	v_readlane_b32 s59, v253, 7
	v_mov_b32_e32 v2, v24
	v_mov_b32_e32 v3, v25
	v_mov_b32_e32 v4, v26
	v_mov_b32_e32 v5, v27
	v_cndmask_b32_e64 v2, v2, 0, s[38:39]
	v_readlane_b32 s38, v253, 53
	v_readlane_b32 s39, v253, 54
	v_mov_b32_e32 v6, v28
	v_mov_b32_e32 v7, v29
	v_mov_b32_e32 v8, v30
	v_mov_b32_e32 v9, v31
	s_nop 0
	v_cndmask_b32_e64 v6, v6, 0, s[38:39]
	v_readlane_b32 s38, v253, 57
	v_readlane_b32 s39, v253, 58
	s_nop 1
	v_cndmask_b32_e64 v3, 0, v3, s[38:39]
	v_readlane_b32 s38, v253, 59
	v_readlane_b32 s39, v253, 60
	v_cvt_pk_bf16_f32 v132, v2, v3
	s_nop 1
	v_cndmask_b32_e64 v7, v7, 0, s[38:39]
	v_readlane_b32 s38, v253, 61
	v_readlane_b32 s39, v253, 62
	s_nop 1
	v_cndmask_b32_e64 v4, v4, 0, s[38:39]
	v_readlane_b32 s38, v253, 63
	v_readlane_b32 s39, v254, 0
	s_nop 1
	v_cndmask_b32_e64 v8, v8, 0, s[38:39]
	v_readlane_b32 s38, v254, 1
	v_readlane_b32 s39, v254, 2
	s_nop 1
	v_cndmask_b32_e64 v5, v5, 0, s[38:39]
	v_readlane_b32 s38, v254, 3
	v_readlane_b32 s39, v254, 4
	v_cvt_pk_bf16_f32 v133, v4, v5
	v_cvt_pk_bf16_f32 v134, v6, v7
	s_nop 1
	v_cndmask_b32_e64 v9, v9, 0, s[38:39]
	v_cvt_pk_bf16_f32 v135, v8, v9
	v_readlane_b32 s38, v254, 5
	v_readlane_b32 s39, v254, 6
	v_mov_b32_e32 v2, v32
	v_mov_b32_e32 v3, v33
	v_mov_b32_e32 v4, v34
	v_mov_b32_e32 v5, v35
	s_nop 0
	v_cndmask_b32_e64 v2, v2, 0, s[38:39]
	v_readlane_b32 s38, v253, 55
	v_readlane_b32 s39, v253, 56
	v_mov_b32_e32 v6, v36
	v_mov_b32_e32 v7, v37
	v_mov_b32_e32 v8, v38
	v_mov_b32_e32 v9, v39
	s_nop 0
	v_cndmask_b32_e64 v6, v6, 0, s[38:39]
	v_readlane_b32 s38, v254, 7
	v_readlane_b32 s39, v254, 8
	s_nop 1
	v_cndmask_b32_e64 v3, v3, 0, s[38:39]
	v_readlane_b32 s38, v254, 9
	v_readlane_b32 s39, v254, 10
	v_cvt_pk_bf16_f32 v136, v2, v3
	s_nop 1
	v_cndmask_b32_e64 v7, v7, 0, s[38:39]
	v_readlane_b32 s38, v254, 11
	v_readlane_b32 s39, v254, 12
	s_nop 1
	v_cndmask_b32_e64 v4, v4, 0, s[38:39]
	v_readlane_b32 s38, v254, 13
	v_readlane_b32 s39, v254, 14
	s_nop 1
	v_cndmask_b32_e64 v8, v8, 0, s[38:39]
	v_readlane_b32 s38, v254, 15
	v_readlane_b32 s39, v254, 16
	s_nop 1
	v_cndmask_b32_e64 v5, v5, 0, s[38:39]
	v_readlane_b32 s38, v253, 49
	v_readlane_b32 s39, v253, 50
	v_cvt_pk_bf16_f32 v137, v4, v5
	v_cvt_pk_bf16_f32 v138, v6, v7
	s_nop 1
	v_cndmask_b32_e64 v9, v9, 0, s[38:39]
	v_cvt_pk_bf16_f32 v139, v8, v9
	v_readlane_b32 s38, v254, 17
	v_readlane_b32 s39, v254, 18
	v_mov_b32_e32 v2, v40
	v_mov_b32_e32 v3, v41
	v_mov_b32_e32 v4, v42
	v_mov_b32_e32 v5, v43
	s_nop 0
	v_cndmask_b32_e64 v2, v2, 0, s[38:39]
	v_readlane_b32 s38, v253, 51
	v_readlane_b32 s39, v253, 52
	v_mov_b32_e32 v6, v44
	v_mov_b32_e32 v7, v45
	v_mov_b32_e32 v8, v46
	v_mov_b32_e32 v9, v47
	s_nop 0
	v_cndmask_b32_e64 v6, v6, 0, s[38:39]
	v_readlane_b32 s38, v254, 19
	v_readlane_b32 s39, v254, 20
	s_nop 1
	v_cndmask_b32_e64 v3, v3, 0, s[38:39]
	v_readlane_b32 s38, v254, 21
	v_readlane_b32 s39, v254, 22
	v_cvt_pk_bf16_f32 v140, v2, v3
	s_nop 1
	v_cndmask_b32_e64 v7, v7, 0, s[38:39]
	v_readlane_b32 s38, v254, 23
	v_readlane_b32 s39, v254, 24
	s_nop 1
	v_cndmask_b32_e64 v4, v4, 0, s[38:39]
	v_readlane_b32 s38, v254, 25
	v_readlane_b32 s39, v254, 26
	s_nop 1
	v_cndmask_b32_e64 v8, v8, 0, s[38:39]
	v_readlane_b32 s38, v254, 27
	v_readlane_b32 s39, v254, 28
	s_nop 1
	v_cndmask_b32_e64 v5, v5, 0, s[38:39]
	v_readlane_b32 s38, v254, 29
	v_readlane_b32 s39, v254, 30
	v_cvt_pk_bf16_f32 v141, v4, v5
	v_cvt_pk_bf16_f32 v142, v6, v7
; __device__ __forceinline__ int crow(int r, int hi) { return (r & 3) + 8 * (r >> 2) + 4 * hi; }
; __device__ __forceinline__ bf16x8 tobf8(f32x8 x) { u32x4 w = {cvtpk(x[0], x[1]), cvtpk(x[2], x[3]), cvtpk(x[4], x[5]), cvtpk(x[6], x[7])}; return *reinterpret_cast<bf16x8*>(&w); }
; __device__ __forceinline__ void spatial_phase(const Params& p, char* lds) {
;     ...
;                 for (int ks = 0; ks < 4; ++ks) { const int s0 = 64 * st_ + 16 * ks + 8 * hi; const float* wp = p.w_sp + ((size_t)g * CCH + t) * CCH + s0;
;                     const f32x4 a = *(const f32x4*)wp, c = *(const f32x4*)(wp + 4); f32x8 y;
; #pragma unroll
;                     for (int i = 0; i < 4; ++i) { y[i] = (s0 + i <= t) ? a[i] : 0.f; y[4 + i] = (s0 + 4 + i <= t) ? c[i] : 0.f; }
;                     pa[st_][ks] = tobf8(y); }
; #pragma unroll
;             for (int r = 0; r < 16; ++r) bsp_[r] = p.b_sp[g * CCH + 32 * tb + crow(r, hi)]; }
	s_nop 1
	v_cndmask_b32_e64 v9, v9, 0, s[38:39]
	v_cvt_pk_bf16_f32 v143, v8, v9
	v_readlane_b32 s38, v254, 31
	v_readlane_b32 s39, v254, 32
	v_mov_b32_e32 v2, v48
	v_mov_b32_e32 v3, v49
	v_mov_b32_e32 v4, v50
	v_mov_b32_e32 v5, v51
	s_nop 0
	v_cndmask_b32_e64 v2, v2, 0, s[38:39]
	v_readlane_b32 s38, v254, 33
	v_readlane_b32 s39, v254, 34
	v_mov_b32_e32 v6, v52
	v_mov_b32_e32 v7, v53
	v_mov_b32_e32 v8, v54
	v_mov_b32_e32 v9, v55
	s_nop 0
	v_cndmask_b32_e64 v6, v6, 0, s[38:39]
	v_readlane_b32 s38, v254, 35
	v_readlane_b32 s39, v254, 36
	s_nop 1
	v_cndmask_b32_e64 v3, v3, 0, s[38:39]
	v_readlane_b32 s38, v254, 37
	v_readlane_b32 s39, v254, 38
	v_cvt_pk_bf16_f32 v144, v2, v3
	s_nop 1
	v_cndmask_b32_e64 v7, v7, 0, s[38:39]
	v_readlane_b32 s38, v254, 39
	v_readlane_b32 s39, v254, 40
	s_nop 1
	v_cndmask_b32_e64 v4, v4, 0, s[38:39]
	v_readlane_b32 s38, v254, 41
	v_readlane_b32 s39, v254, 42
	s_nop 1
	v_cndmask_b32_e64 v8, v8, 0, s[38:39]
	v_readlane_b32 s38, v254, 43
	v_readlane_b32 s39, v254, 44
	s_nop 1
	v_cndmask_b32_e64 v5, v5, 0, s[38:39]
	v_readlane_b32 s38, v254, 45
	v_readlane_b32 s39, v254, 46
	v_cvt_pk_bf16_f32 v145, v4, v5
	v_cvt_pk_bf16_f32 v146, v6, v7
	s_nop 1
	v_cndmask_b32_e64 v9, v9, 0, s[38:39]
	v_cvt_pk_bf16_f32 v147, v8, v9
	v_readlane_b32 s38, v254, 47
	v_readlane_b32 s39, v254, 48
	v_mov_b32_e32 v2, v56
	v_mov_b32_e32 v3, v57
	v_mov_b32_e32 v4, v58
	v_mov_b32_e32 v5, v59
	s_nop 0
	v_cndmask_b32_e64 v2, v2, 0, s[38:39]
	v_readlane_b32 s38, v254, 49
	v_readlane_b32 s39, v254, 50
	v_mov_b32_e32 v6, v60
	v_mov_b32_e32 v7, v61
	v_mov_b32_e32 v8, v62
	v_mov_b32_e32 v9, v63
	s_nop 0
	v_cndmask_b32_e64 v6, v6, 0, s[38:39]
	v_readlane_b32 s38, v254, 51
	v_readlane_b32 s39, v254, 52
	s_nop 1
	v_cndmask_b32_e64 v3, v3, 0, s[38:39]
	v_readlane_b32 s38, v254, 53
	v_readlane_b32 s39, v254, 54
	v_cvt_pk_bf16_f32 v148, v2, v3
	s_nop 1
	v_cndmask_b32_e64 v7, v7, 0, s[38:39]
	v_readlane_b32 s38, v254, 55
	v_readlane_b32 s39, v254, 56
	s_nop 1
	v_cndmask_b32_e64 v4, v4, 0, s[38:39]
	v_readlane_b32 s38, v254, 57
	v_readlane_b32 s39, v254, 58
	s_nop 1
	v_cndmask_b32_e64 v8, v8, 0, s[38:39]
	v_readlane_b32 s38, v254, 59
	v_readlane_b32 s39, v254, 60
	s_nop 1
	v_cndmask_b32_e64 v5, v5, 0, s[38:39]
	v_readlane_b32 s38, v254, 61
	v_readlane_b32 s39, v254, 62
	v_cvt_pk_bf16_f32 v149, v4, v5
	v_cvt_pk_bf16_f32 v150, v6, v7
	s_nop 1
	v_cndmask_b32_e64 v9, v9, 0, s[38:39]
	v_cvt_pk_bf16_f32 v151, v8, v9
	v_readlane_b32 s38, v254, 63
	v_readlane_b32 s39, v255, 0
	v_mov_b32_e32 v2, v100
	v_mov_b32_e32 v3, v101
	v_mov_b32_e32 v4, v102
	v_mov_b32_e32 v5, v103
	v_cndmask_b32_e64 v4, v4, 0, s[84:85]
	v_cndmask_b32_e64 v2, v2, 0, s[38:39]
	v_readlane_b32 s38, v255, 1
	v_readlane_b32 s39, v255, 2
	v_mov_b32_e32 v6, v104
	v_mov_b32_e32 v7, v105
	v_mov_b32_e32 v8, v106
	v_mov_b32_e32 v9, v107
	v_cndmask_b32_e64 v7, v7, 0, s[50:51]
	v_cndmask_b32_e64 v8, v8, 0, s[88:89]
	v_cndmask_b32_e64 v6, v6, 0, s[38:39]
	v_readlane_b32 s38, v255, 3
	v_readlane_b32 s39, v255, 4
	v_cndmask_b32_e64 v5, v5, 0, s[96:97]
	v_cndmask_b32_e64 v9, v9, 0, s[0:1]
	v_cndmask_b32_e64 v3, v3, 0, s[38:39]
	v_cvt_pk_bf16_f32 v152, v2, v3
	v_cvt_pk_bf16_f32 v153, v4, v5
	v_cvt_pk_bf16_f32 v154, v6, v7
	v_cvt_pk_bf16_f32 v155, v8, v9
	v_mov_b32_e32 v2, v108
	v_mov_b32_e32 v3, v109
	v_mov_b32_e32 v4, v110
	v_mov_b32_e32 v5, v111
	v_cndmask_b32_e64 v2, v2, 0, s[2:3]
	v_mov_b32_e32 v6, v112
	v_mov_b32_e32 v7, v113
	v_mov_b32_e32 v8, v114
	v_mov_b32_e32 v9, v115
	v_cndmask_b32_e64 v6, v6, 0, s[4:5]
	v_cndmask_b32_e64 v3, v3, 0, s[6:7]
	v_cndmask_b32_e64 v7, v7, 0, s[8:9]
	v_cndmask_b32_e64 v4, v4, 0, s[10:11]
	v_cndmask_b32_e64 v8, v8, 0, s[12:13]
	v_cndmask_b32_e64 v5, v5, 0, s[14:15]
	v_cndmask_b32_e64 v9, v9, 0, s[16:17]
	v_cvt_pk_bf16_f32 v156, v2, v3
	v_cvt_pk_bf16_f32 v157, v4, v5
	v_cvt_pk_bf16_f32 v158, v6, v7
	v_cvt_pk_bf16_f32 v159, v8, v9
	v_lshl_or_b32 v0, s42, 9, v211
	v_mov_b32_e32 v2, v116
	v_mov_b32_e32 v3, v117
	v_mov_b32_e32 v4, v118
	v_mov_b32_e32 v5, v119
	v_cndmask_b32_e64 v1, v2, 0, s[18:19]
	v_mov_b32_e32 v6, v120
	v_mov_b32_e32 v7, v121
	v_mov_b32_e32 v8, v122
	v_mov_b32_e32 v9, v123
	v_cndmask_b32_e64 v2, v6, 0, s[20:21]
	v_cndmask_b32_e64 v3, v3, 0, s[22:23]
	v_cndmask_b32_e64 v6, v7, 0, s[24:25]
	v_cndmask_b32_e64 v4, v4, 0, s[26:27]
	v_cndmask_b32_e64 v7, v8, 0, s[28:29]
	v_cndmask_b32_e64 v5, v5, 0, s[30:31]
	v_cndmask_b32_e64 v8, v9, 0, s[34:35]
	v_cvt_pk_bf16_f32 v160, v1, v3
	v_cvt_pk_bf16_f32 v161, v4, v5
	v_cvt_pk_bf16_f32 v162, v2, v6
	v_cvt_pk_bf16_f32 v163, v7, v8
	global_load_dwordx4 v[164:167], v0, s[52:53]
	global_load_dwordx4 v[168:171], v0, s[52:53] offset:32
	global_load_dwordx4 v[172:175], v0, s[52:53] offset:64
	global_load_dwordx4 v[176:179], v0, s[52:53] offset:96

;     __device__ __forceinline__ void quad(const f32x4 (&a)[4][2], int rowq, int colq, int wr, int wc, int fr, int fq) const {
;         const int col0 = colq + wc * 32 + 4 * fq;
; #pragma unroll
;         for (int m = 0; m < 4; ++m) { const int row = rowq + wr * 64 + m * 16 + fr; float s = 0.f;
; #pragma unroll
;             for (int n = 0; n < 2; ++n) { const int c = col0 + n * 16; f32x4 hv = a[m][n]; if (!pre) hv += *(const f32x4*)(H1 + (size_t)row * DM + c);
;                 *(f32x4*)(out + (size_t)row * DM + c) = hv; s += (hv[0] * hv[0] + hv[1] * hv[1]) + (hv[2] * hv[2] + hv[3] * hv[3]); }
;             s += __shfl_xor(s, 16); s += __shfl_xor(s, 32);
;             if (fq == 0) unsafeAtomicAdd(ssq + row, s); }
.LBB0_1393:
	v_add_u32_e32 v38, s81, v42
	v_mov_b32_e32 v39, v33
	v_lshl_or_b32 v32, s80, 7, v60
	v_lshlrev_b64 v[40:41], 13, v[38:39]
	v_lshl_add_u64 v[66:67], s[6:7], 0, v[40:41]
	v_lshlrev_b32_e32 v36, 2, v32
	v_mov_b32_e32 v37, v33
	v_lshl_add_u64 v[70:71], v[66:67], 0, v[36:37]
	global_load_dwordx4 v[66:69], v[70:71], off
	s_mov_b32 s98, 0x20000
	s_mov_b32 s99, 0
	global_load_dwordx4 v[152:155], v[70:71], off offset:64
	v_lshl_add_u64 v[148:149], v[70:71], 0, s[98:99]
	global_load_dwordx4 v[156:159], v[148:149], off
	global_load_dwordx4 v[160:163], v[148:149], off offset:64
	v_lshl_add_u64 v[148:149], v[148:149], 0, s[98:99]
	global_load_dwordx4 v[164:167], v[148:149], off
	global_load_dwordx4 v[168:171], v[148:149], off offset:64
	v_lshl_add_u64 v[148:149], v[148:149], 0, s[98:99]
	global_load_dwordx4 v[172:175], v[148:149], off
	global_load_dwordx4 v[176:179], v[148:149], off offset:64
	v_readlane_b32 s80, v253, 0
	v_readlane_b32 s86, v253, 6
	v_readlane_b32 s87, v253, 7
	v_readlane_b32 s81, v253, 1
	v_readlane_b32 s82, v253, 2
	v_lshl_add_u64 v[40:41], s[86:87], 0, v[40:41]
	v_lshl_add_u64 v[40:41], v[40:41], 0, v[36:37]
	v_readlane_b32 s83, v253, 3
	v_readlane_b32 s84, v253, 4
	v_readlane_b32 s85, v253, 5
	s_waitcnt vmcnt(0)
	v_pk_add_f32 v[68:69], v[2:3], v[68:69]
	v_pk_add_f32 v[66:67], v[0:1], v[66:67]
	global_store_dwordx4 v[40:41], v[66:69], off
	v_mul_f32_e32 v2, v67, v67
	v_mul_f32_e32 v3, v69, v69
	v_and_b32_e32 v1, 64, v64
	v_fmac_f32_e32 v2, v66, v66
	v_fmac_f32_e32 v3, v68, v68
	v_xor_b32_e32 v0, 16, v64
	v_add_u32_e32 v1, 64, v1
	v_add_f32_e32 v2, v2, v3
	v_cmp_lt_i32_e32 vcc, v0, v1
	v_mov_b32_e32 v70, v152
	v_mov_b32_e32 v71, v153
	v_mov_b32_e32 v72, v154
	v_mov_b32_e32 v73, v155
	v_pk_add_f32 v[6:7], v[6:7], v[72:73]
	v_pk_add_f32 v[4:5], v[4:5], v[70:71]
	v_mul_f32_e32 v32, v7, v7
	v_mul_f32_e32 v3, v5, v5
	v_fmac_f32_e32 v3, v4, v4
	v_fmac_f32_e32 v32, v6, v6
	v_cndmask_b32_e32 v0, v64, v0, vcc
	v_add_f32_e32 v3, v3, v32
	v_lshlrev_b32_e32 v0, 2, v0
	v_add_f32_e32 v2, v2, v3
	ds_bpermute_b32 v3, v0, v2
	v_xor_b32_e32 v32, 32, v64
	v_cmp_lt_i32_e32 vcc, v32, v1
	global_store_dwordx4 v[40:41], v[4:7], off offset:64
	s_waitcnt lgkmcnt(0)
	v_add_f32_e32 v2, v2, v3
	v_cndmask_b32_e32 v1, v64, v32, vcc
	v_lshlrev_b32_e32 v1, 2, v1
	ds_bpermute_b32 v3, v1, v2
	s_and_saveexec_b64 s[2:3], s[0:1]
	s_cbranch_execz .LBB0_1395
	v_lshl_add_u64 v[4:5], v[38:39], 2, s[8:9]
	s_waitcnt lgkmcnt(0)
	v_add_f32_e32 v2, v2, v3
	global_atomic_add_f32 v[4:5], v2, off
.LBB0_1395:
	s_or_b64 exec, exec, s[2:3]
	v_or_b32_e32 v32, 16, v38
	v_lshlrev_b64 v[6:7], 13, v[32:33]
	s_waitcnt lgkmcnt(0)
	v_lshl_add_u64 v[2:3], s[6:7], 0, v[6:7]
	v_lshl_add_u64 v[40:41], v[2:3], 0, v[36:37]
	v_readlane_b32 s80, v253, 0
	v_readlane_b32 s86, v253, 6
	v_readlane_b32 s87, v253, 7
	v_readlane_b32 s81, v253, 1
	v_readlane_b32 s82, v253, 2
	v_lshl_add_u64 v[6:7], s[86:87], 0, v[6:7]
	v_lshl_add_u64 v[66:67], v[6:7], 0, v[36:37]
	v_readlane_b32 s83, v253, 3
	v_readlane_b32 s84, v253, 4
	v_readlane_b32 s85, v253, 5
	v_mov_b32_e32 v2, v156
	v_mov_b32_e32 v3, v157
	v_mov_b32_e32 v4, v158
	v_mov_b32_e32 v5, v159
	v_pk_add_f32 v[4:5], v[10:11], v[4:5]
	v_pk_add_f32 v[2:3], v[8:9], v[2:3]
	global_store_dwordx4 v[66:67], v[2:5], off
	v_mov_b32_e32 v6, v160
	v_mov_b32_e32 v7, v161
	v_mov_b32_e32 v8, v162
	v_mov_b32_e32 v9, v163
	v_pk_add_f32 v[8:9], v[14:15], v[8:9]
	v_mul_f32_e32 v3, v3, v3
	v_mul_f32_e32 v5, v5, v5
	v_fmac_f32_e32 v3, v2, v2
	v_fmac_f32_e32 v5, v4, v4
	v_pk_add_f32 v[6:7], v[12:13], v[6:7]
	v_add_f32_e32 v2, v3, v5
	v_mul_f32_e32 v3, v7, v7
	v_mul_f32_e32 v4, v9, v9
	v_fmac_f32_e32 v3, v6, v6
	v_fmac_f32_e32 v4, v8, v8
	v_add_f32_e32 v3, v3, v4
	v_add_f32_e32 v2, v2, v3
	ds_bpermute_b32 v3, v0, v2
	global_store_dwordx4 v[66:67], v[6:9], off offset:64
	s_waitcnt lgkmcnt(0)
	v_add_f32_e32 v2, v2, v3
	ds_bpermute_b32 v3, v1, v2
	s_and_saveexec_b64 s[2:3], s[0:1]
	s_cbranch_execz .LBB0_1397
	v_lshl_add_u64 v[4:5], v[32:33], 2, s[8:9]
	s_waitcnt lgkmcnt(0)
	v_add_f32_e32 v2, v2, v3
	global_atomic_add_f32 v[4:5], v2, off
;     __device__ __forceinline__ void quad(const f32x4 (&a)[4][2], int rowq, int colq, int wr, int wc, int fr, int fq) const {
;     ...
;         for (int m = 0; m < 4; ++m) { const int row = rowq + wr * 64 + m * 16 + fr; float s = 0.f;
; #pragma unroll
;             for (int n = 0; n < 2; ++n) { const int c = col0 + n * 16; f32x4 hv = a[m][n]; if (!pre) hv += *(const f32x4*)(H1 + (size_t)row * DM + c);
;                 *(f32x4*)(out + (size_t)row * DM + c) = hv; s += (hv[0] * hv[0] + hv[1] * hv[1]) + (hv[2] * hv[2] + hv[3] * hv[3]); }
;             s += __shfl_xor(s, 16); s += __shfl_xor(s, 32);
;             if (fq == 0) unsafeAtomicAdd(ssq + row, s); }
.LBB0_1397:
	s_or_b64 exec, exec, s[2:3]
	v_or_b32_e32 v32, 32, v38
	v_lshlrev_b64 v[6:7], 13, v[32:33]
	s_waitcnt lgkmcnt(0)
	v_lshl_add_u64 v[2:3], s[6:7], 0, v[6:7]
	v_mov_b32_e32 v37, v33
	v_lshl_add_u64 v[8:9], v[2:3], 0, v[36:37]
	v_readlane_b32 s80, v253, 0
	v_readlane_b32 s86, v253, 6
	v_readlane_b32 s87, v253, 7
	v_readlane_b32 s81, v253, 1
	v_readlane_b32 s82, v253, 2
	v_lshl_add_u64 v[6:7], s[86:87], 0, v[6:7]
	v_lshl_add_u64 v[10:11], v[6:7], 0, v[36:37]
	v_readlane_b32 s83, v253, 3
	v_readlane_b32 s84, v253, 4
	v_readlane_b32 s85, v253, 5
	v_mov_b32_e32 v2, v164
	v_mov_b32_e32 v3, v165
	v_mov_b32_e32 v4, v166
	v_mov_b32_e32 v5, v167
	v_pk_add_f32 v[4:5], v[18:19], v[4:5]
	v_pk_add_f32 v[2:3], v[16:17], v[2:3]
	global_store_dwordx4 v[10:11], v[2:5], off
	v_mov_b32_e32 v6, v168
	v_mov_b32_e32 v7, v169
	v_mov_b32_e32 v8, v170
	v_mov_b32_e32 v9, v171
	v_pk_add_f32 v[8:9], v[22:23], v[8:9]
	v_mul_f32_e32 v3, v3, v3
	v_mul_f32_e32 v5, v5, v5
	v_fmac_f32_e32 v3, v2, v2
	v_fmac_f32_e32 v5, v4, v4
	v_pk_add_f32 v[6:7], v[20:21], v[6:7]
	v_add_f32_e32 v2, v3, v5
	v_mul_f32_e32 v3, v7, v7
	v_mul_f32_e32 v4, v9, v9
	v_fmac_f32_e32 v3, v6, v6
	v_fmac_f32_e32 v4, v8, v8
	v_add_f32_e32 v3, v3, v4
	v_add_f32_e32 v2, v2, v3
	ds_bpermute_b32 v3, v0, v2
	global_store_dwordx4 v[10:11], v[6:9], off offset:64
	s_waitcnt lgkmcnt(0)
	v_add_f32_e32 v2, v2, v3
	ds_bpermute_b32 v3, v1, v2
	s_and_saveexec_b64 s[2:3], s[0:1]
	s_cbranch_execz .LBB0_1399
	v_lshl_add_u64 v[4:5], v[32:33], 2, s[8:9]
	s_waitcnt lgkmcnt(0)
	v_add_f32_e32 v2, v2, v3
	global_atomic_add_f32 v[4:5], v2, off
.LBB0_1399:
	s_or_b64 exec, exec, s[2:3]
	v_or_b32_e32 v32, 48, v38
	v_lshlrev_b64 v[6:7], 13, v[32:33]
	s_waitcnt lgkmcnt(0)
	v_lshl_add_u64 v[2:3], s[6:7], 0, v[6:7]
	v_lshl_add_u64 v[8:9], v[2:3], 0, v[36:37]
	v_readlane_b32 s80, v253, 0
	v_readlane_b32 s86, v253, 6
	v_readlane_b32 s87, v253, 7
	v_readlane_b32 s81, v253, 1
	v_readlane_b32 s82, v253, 2
	v_lshl_add_u64 v[6:7], s[86:87], 0, v[6:7]
	v_lshl_add_u64 v[10:11], v[6:7], 0, v[36:37]
	v_readlane_b32 s83, v253, 3
	v_readlane_b32 s84, v253, 4
	v_readlane_b32 s85, v253, 5
	v_mov_b32_e32 v2, v172
	v_mov_b32_e32 v3, v173
	v_mov_b32_e32 v4, v174
	v_mov_b32_e32 v5, v175
	v_pk_add_f32 v[4:5], v[26:27], v[4:5]
	v_pk_add_f32 v[2:3], v[24:25], v[2:3]
	global_store_dwordx4 v[10:11], v[2:5], off
	s_nop 1
	s_nop 0
	v_mul_f32_e32 v3, v3, v3
	v_mul_f32_e32 v5, v5, v5
	v_fmac_f32_e32 v3, v2, v2
	v_fmac_f32_e32 v5, v4, v4
	v_add_f32_e32 v12, v3, v5
	v_mov_b32_e32 v6, v176
	v_mov_b32_e32 v7, v177
	v_mov_b32_e32 v8, v178
	v_mov_b32_e32 v9, v179
	v_pk_add_f32 v[4:5], v[30:31], v[8:9]
	v_pk_add_f32 v[2:3], v[28:29], v[6:7]
	v_mul_f32_e32 v7, v5, v5
	v_mul_f32_e32 v6, v3, v3
	v_fmac_f32_e32 v6, v2, v2
	v_fmac_f32_e32 v7, v4, v4
	v_add_f32_e32 v6, v6, v7
	v_add_f32_e32 v6, v12, v6
	ds_bpermute_b32 v0, v0, v6
	global_store_dwordx4 v[10:11], v[2:5], off offset:64
	s_waitcnt lgkmcnt(0)
	v_add_f32_e32 v0, v6, v0
	ds_bpermute_b32 v1, v1, v0
	s_and_saveexec_b64 s[2:3], s[0:1]
	s_cbranch_execz .LBB0_1401
	v_lshl_add_u64 v[2:3], v[32:33], 2, s[8:9]
	s_waitcnt lgkmcnt(0)
	v_add_f32_e32 v0, v0, v1
	global_atomic_add_f32 v[2:3], v0, off
